# K-rotation (k0=((rank&7)+(rank>>3))&3 tile pairs) applied to all six K=1024 256x256 GEMM loops: in-proj RG and GLA, out-proj, Q, Wo, MLP-up
# baseline (speedup 1.0000x reference)
; template <class Epi, class Sched, bool ALIGN_EPI = false, bool SP2 = false>
; __device__ __forceinline__ void gemm_phase(PG8_LAS unsigned char* lds, const Gemm g, const Sched& S, const Epi& E, const int tid) {
;     const int wid = __builtin_amdgcn_readfirstlane(tid >> 6), lane = tid & 63, wr = wid >> 2, wc = wid & 3, fr = lane & 15, fq = lane >> 4;
;     const int K = g.K, nt = K / BK;
;     unsigned voffA[2], voffB[2];
; #pragma unroll
;     for (int i = 0; i < 2; ++i) { int R, C; stage_rc(tid * 16 + i * 8192, R, C); const int Rb = Epi::PERM ? (2 * (R & ~31) + perm32(R & 31)) : R;
;         voffA[i] = (unsigned)(R * K + C) * 2u; voffB[i] = (unsigned)(Rb * K + C) * 2u; }
;     const size_t kstep = (size_t)(BK * 2);
;     const size_t hstep = (size_t)HALF * K * 2;
;     const size_t tstep = 2 * hstep;
;     const size_t hstepB = Epi::PERM ? (size_t)32 * K * 2 : hstep;
;     const unsigned ldsw = (unsigned)wid * 1024u;
;     const int aoff = lds_byte(wr * 64 + fr, fq * 8), boff = lds_byte(wc * 32 + fr, fq * 8);
;     ...
;     Unit cur, nxt; int ui = 0;
;     if (!S.next(0, cur)) return;
;     f32x4 acc[2][2][4][2];
;     u32x4 iw_[Epi::HAS_INIT ? 16 : 1];
;     if constexpr (Epi::HAS_INIT) E.init_issue(iw_, cur, wr, wc, fr, fq);
;     else {
; #pragma unroll
;     for (int a = 0; a < 2; ++a)
; #pragma unroll
;         for (int b = 0; b < 2; ++b)
; #pragma unroll
;             for (int m = 0; m < 4; ++m)
; #pragma unroll
;                 for (int n = 0; n < 2; ++n) acc[a][b][m][n] = (f32x4){0.f, 0.f, 0.f, 0.f};
;     }
;     bf16x8 At[4][2], B0[2][2], B1[2][2];
;     const char* cA = (const char*)g.A + (size_t)cur.pm * tstep; const char* cB = (const char*)g.Bt + (size_t)cur.pn * tstep;
;     S.a_ready(cur);
;     if constexpr (SP2) {
;         PG8_STAGE(PG8_SB(0, 0), cB, voffB); PG8_STAGE(PG8_SB(0, 1), cB + hstepB, voffB); PG8_STAGE(PG8_SA(0, 0), cA, voffA); PG8_STAGE(PG8_SA(0, 1), cA + hstep, voffA);
;         if (wr == 1) PG8_BAR;
;         PG8_WAIT_V(2); PG8_BAR;
;         PG8_STAGE(PG8_SB(1, 0), cB + kstep, voffB); PG8_STAGE(PG8_SA(1, 0), cA + kstep, voffA); PG8_STAGE(PG8_SB(1, 1), cB + hstepB + kstep, voffB);
;         PG8_WAIT_V(6); PG8_BAR;
;     } else {
;         PG8_STAGE(PG8_SB(0, 0), cB, voffB); PG8_STAGE(PG8_SA(0, 0), cA, voffA); PG8_STAGE(PG8_SB(0, 1), cB + hstepB, voffB); PG8_STAGE(PG8_SA(0, 1), cA + hstep, voffA);
;         if (wr == 1) PG8_BAR;
.LBB0_176:
	v_ashrrev_i32_e32 v3, 31, v133
	v_lshrrev_b32_e32 v3, 26, v3
	v_add_u32_e32 v3, v133, v3
	v_ashrrev_i32_e32 v4, 6, v3
	v_bfe_i32 v3, v133, 27, 1
	v_lshlrev_b32_e32 v7, 4, v133
	v_lshrrev_b32_e32 v3, 22, v3
	v_add_u32_e32 v3, v7, v3
	v_and_b32_e32 v3, 0xfffffc00, v3
	v_sub_u32_e32 v3, v7, v3
	v_lshrrev_b32_e32 v5, 4, v3
	v_bitop3_b32 v3, v5, v3, 32 bitop3:0x6c
	v_lshlrev_b32_e32 v5, 3, v4
	v_and_b32_e32 v6, -16, v5
	v_ashrrev_i32_e32 v5, 31, v3
	v_lshrrev_b32_e32 v5, 26, v5
	v_add_u32_e32 v8, v3, v5
	s_mul_i32 s6, s94, 0x680000
	v_ashrrev_i32_e32 v5, 6, v8
	s_mul_hi_u32 s5, s94, 0x680000
	s_add_u32 s6, s0, s6
	v_add_u32_e32 v158, v5, v6
	v_lshlrev_b32_e32 v6, 5, v4
	s_addc_u32 s5, s1, s5
	v_and_b32_e32 v9, 32, v6
	v_and_b32_e32 v6, 0xc0, v8
	s_add_u32 s12, s6, 0x6d00000
	v_sub_u32_e32 v3, v3, v6
	s_addc_u32 s13, s5, 0
	v_ashrrev_i16_sdwa v3, v205, sext(v3) dst_sel:DWORD dst_unused:UNUSED_PAD src0_sel:DWORD src1_sel:BYTE_0
	s_add_u32 s14, s0, 0xc300000
	v_bfe_i32 v6, v3, 0, 16
	v_lshrrev_b32_e32 v3, 2, v158
	s_addc_u32 s15, s1, 0
	v_and_b32_e32 v159, 4, v3
	v_and_b32_e32 v156, 15, v133
	v_lshrrev_b32_e32 v3, 1, v133
	s_add_u32 s6, s0, 0x1f900000
	v_add_u32_e32 v132, v9, v6
	v_lshlrev_b32_e32 v161, 1, v158
	v_and_b32_e32 v160, 3, v5
	v_and_b32_e32 v157, 24, v3
	v_lshlrev_b32_e32 v3, 6, v156
	s_addc_u32 s7, s1, 0
	s_andn2_b64 vcc, exec, s[16:17]
	s_cbranch_vccnz .LBB0_224
	v_and_b32_e32 v8, 0x1fffd8, v161
	v_or3_b32 v8, v160, v8, v159
	v_lshlrev_b32_e32 v9, 1, v132
	v_lshl_add_u32 v136, v8, 11, v9
	v_add_u32_e32 v8, 0x2000, v7
	v_ashrrev_i32_e32 v7, 31, v8
	v_lshrrev_b32_e32 v7, 22, v7
	v_add_u32_e32 v7, v8, v7
	v_ashrrev_i32_e32 v7, 10, v7
	v_lshl_add_u32 v134, v158, 11, v9
	v_mul_i32_i24_e32 v9, 0x400, v7
	v_sub_u32_e32 v8, v8, v9
	v_lshrrev_b32_e32 v9, 4, v8
	v_bitop3_b32 v9, v9, v8, 32 bitop3:0x6c
	v_lshlrev_b32_e32 v8, 3, v7
	v_and_b32_e32 v10, -16, v8
	v_ashrrev_i32_e32 v8, 31, v9
	v_lshrrev_b32_e32 v8, 26, v8
	s_ashr_i32 s18, s3, 6
	v_add_u32_e32 v11, v9, v8
	s_ashr_i32 s5, s4, 31
	s_ashr_i32 s37, s36, 31
	v_ashrrev_i32_e32 v8, 6, v11
	v_and_b32_e32 v11, 0xc0, v11
	s_ashr_i32 s20, s3, 8
	s_lshl_b32 s62, s18, 10
	s_lshl_b64 s[16:17], s[4:5], 19
	s_lshl_b64 s[22:23], s[36:37], 19
	v_add_u32_e32 v10, v8, v10
	v_sub_u32_e32 v9, v9, v11
	s_lshr_b32 s32, s2, 3
	s_lshr_b32 s99, s2, 6
	s_add_i32 s32, s32, s99
	s_and_b32 s32, s32, 3
	s_lshl_b32 s32, s32, 8
	s_add_u32 s40, s12, s22
	v_lshlrev_b32_e32 v12, 5, v7
	v_ashrrev_i16_sdwa v9, v205, sext(v9) dst_sel:DWORD dst_unused:UNUSED_PAD src0_sel:DWORD src1_sel:BYTE_0
	v_lshlrev_b32_e32 v11, 1, v10
	v_lshrrev_b32_e32 v13, 2, v10
	s_addc_u32 s41, s13, s23
	s_add_u32 s40, s40, s32
	s_addc_u32 s41, s41, 0
	s_add_i32 s63, s62, 0
	v_and_b32_e32 v12, 32, v12
	v_bfe_i32 v9, v9, 0, 16
	v_and_b32_e32 v13, 4, v13
	v_and_b32_e32 v14, 3, v8
	v_and_b32_e32 v11, 0x1fffd8, v11
	s_add_i32 m0, s63, 0x10000
	v_or3_b32 v11, v14, v13, v11
	v_add_lshl_u32 v12, v12, v9, 1
	global_load_lds_dwordx4 v136, s[40:41]
	s_add_i32 m0, s63, 0x12000
	v_lshl_add_u32 v140, v11, 11, v12
	s_add_u32 s22, s40, 0x10000
	global_load_lds_dwordx4 v140, s[40:41]
	s_addc_u32 s23, s41, 0
	s_add_i32 m0, s63, 0x14000
	v_lshl_add_u32 v138, v10, 11, v12
	global_load_lds_dwordx4 v136, s[22:23]
	s_add_i32 m0, s63, 0x16000
	s_add_u32 s38, s14, s16
	s_addc_u32 s39, s15, s17
	s_add_u32 s38, s38, s32
	s_addc_u32 s39, s39, 0
	s_add_i32 s64, s63, 0x2000
	global_load_lds_dwordx4 v140, s[22:23]
	s_mov_b32 m0, s63
	s_add_u32 s16, s38, 0x40000
	global_load_lds_dwordx4 v134, s[38:39]
	s_mov_b32 m0, s64
	s_addc_u32 s17, s39, 0
	s_add_i32 s65, s63, 0x4000
	global_load_lds_dwordx4 v138, s[38:39]
	s_mov_b32 m0, s65
	s_add_i32 s76, s63, 0x6000
	global_load_lds_dwordx4 v134, s[16:17]
	s_mov_b32 m0, s76
	s_cmp_eq_u32 s20, 1
	global_load_lds_dwordx4 v138, s[16:17]
	s_cselect_b64 s[16:17], -1, 0
	s_cmp_lg_u32 s20, 1
	s_cbranch_scc1 .LBB0_179
	s_barrier
.LBB0_179:
	v_mov_b32_e32 v137, v2
	v_lshl_add_u64 v[10:11], s[40:41], 0, v[136:137]
	v_mov_b32_e32 v141, v2
	v_lshlrev_b32_e32 v18, 1, v157
	v_lshlrev_b32_e32 v20, 2, v156
	v_lshl_add_u64 v[12:13], s[40:41], 0, v[140:141]
	v_mov_b32_e32 v135, v2
	s_and_b32 s5, s18, 3
	v_lshl_or_b32 v19, v156, 6, v18
	s_lshl_b32 s18, s20, 13
	v_and_b32_e32 v21, 32, v20
	s_add_i32 m0, s63, 0x18000
	v_lshl_add_u64 v[10:11], v[10:11], 0, s[52:53]
	v_lshl_add_u64 v[14:15], s[38:39], 0, v[134:135]
	v_mov_b32_e32 v139, v2
	v_bitop3_b32 v19, v19, s18, v21 bitop3:0xde
	v_or_b32_e32 v18, v18, v3
	s_lshl_b32 s18, s5, 12
	s_waitcnt vmcnt(2)
	s_barrier
	global_load_lds_dwordx4 v[10:11], off
	v_lshl_add_u64 v[10:11], v[12:13], 0, s[52:53]
	s_add_i32 m0, s63, 0x1a000
	s_add_i32 s78, s63, 0x8000
	s_add_i32 s79, s63, 0xa000
	v_lshl_add_u64 v[16:17], s[38:39], 0, v[138:139]
	v_bitop3_b32 v163, s18, v18, v21 bitop3:0xf6
	global_load_lds_dwordx4 v[10:11], off
	v_lshl_add_u64 v[10:11], v[14:15], 0, s[52:53]
	s_mov_b32 m0, s78
	s_add_u32 s18, s40, 0x10080
	global_load_lds_dwordx4 v[10:11], off
	v_lshl_add_u64 v[10:11], v[16:17], 0, s[52:53]
	s_mov_b32 m0, s79
	s_addc_u32 s19, s41, 0
	global_load_lds_dwordx4 v[10:11], off
	s_add_i32 m0, s63, 0x1c000
	v_lshl_add_u64 v[10:11], s[18:19], 0, v[136:137]
	global_load_lds_dwordx4 v[10:11], off
	v_lshl_add_u64 v[10:11], s[18:19], 0, v[140:141]
	s_add_i32 m0, s63, 0x1e000
	s_cmpk_lt_u32 s3, 0x100
	global_load_lds_dwordx4 v[10:11], off
	v_lshlrev_b32_e32 v10, 14, v4
	v_and_b32_e32 v10, 0xffff8000, v10
	v_lshl_add_u32 v5, v5, 11, v10
	v_and_b32_e32 v4, 1, v4
	v_lshl_or_b32 v4, v4, 6, v5
	v_lshl_add_u32 v142, v6, 1, v4
	v_lshlrev_b32_e32 v4, 14, v7
	s_cselect_b64 s[18:19], -1, 0
	s_lshl_b32 s3, s20, 8
	v_and_b32_e32 v4, 0xffff8000, v4
	s_waitcnt vmcnt(6)
	s_add_i32 s3, s3, 0
	v_lshl_add_u32 v4, v8, 11, v4
	v_and_b32_e32 v5, 1, v7
	s_add_i32 s3, s3, 0x20000
	v_lshl_or_b32 v4, v5, 6, v4
	v_lshl_or_b32 v162, s20, 6, v156
	s_lshl_b32 s80, s54, 3
	v_add_u32_e32 v164, s3, v20
	v_lshl_or_b32 v165, s5, 6, v157
	v_mov_b32_e32 v143, v2
	v_lshl_add_u32 v144, v9, 1, v4
	v_mov_b32_e32 v145, v2
	s_mov_b32 s81, 0
	v_add_u32_e32 v166, 0, v19
	s_barrier
	s_sub_u32 s40, s40, s32
	s_subb_u32 s41, s41, 0
	s_sub_u32 s38, s38, s32
	s_subb_u32 s39, s39, 0
	s_branch .LBB0_182

;     DI bool next(int i, Unit& u) const { const int L = i * 32 + rank; if (L >= ppg * nN) return false; u.pm = ppg * grp + (L % ppg); const int p0 = L / ppg, p1 = p0 + rot; u.pn = rev ? nN - 1 - p0 : (p1 >= nN ? p1 - nN : p1); return true; }
; #define PG8_STAGE(bufoff, gbase, voff) do { _Pragma("unroll") for (int _i = 0; _i < 2; ++_i) \
;         __builtin_amdgcn_global_load_lds((const unsigned*)((const char*)(gbase) + (voff)[_i]), (PG8_LAS unsigned*)(lds + (bufoff) + ldsw + _i * 8192), 16, 0, 0); } while (0)
; #define PG8_LDA(dst, b, h) do { _Pragma("unroll") for (int m = 0; m < 4; ++m) _Pragma("unroll") for (int k = 0; k < 2; ++k) dst[m][k] = *(const PG8_LAS bf16x8*)(lds + PG8_SA(b, h) + aoff + m * 2048 + k * 1024); } while (0)
; #define PG8_LDB(dst, b, h) do { _Pragma("unroll") for (int n = 0; n < 2; ++n) _Pragma("unroll") for (int k = 0; k < 2; ++k) dst[n][k] = *(const PG8_LAS bf16x8*)(lds + PG8_SB(b, h) + boff + n * 2048 + k * 1024); } while (0)
; #define PG8_WAIT_V(n) asm volatile("s_waitcnt vmcnt(" #n ")" ::: "memory")
; #define PG8_WAIT_L(n) asm volatile("s_waitcnt lgkmcnt(" #n ")" ::: "memory")
; template <class Epi, class Sched, bool ALIGN_EPI = false, bool SP2 = false>
; __device__ __forceinline__ void gemm_phase(PG8_LAS unsigned char* lds, const Gemm g, const Sched& S, const Epi& E, const int tid) {
;     ...
;         const bool has_next = S.next(ui + 1, nxt);
;         const char* nA = has_next ? (const char*)g.A + (size_t)nxt.pm * tstep : cA; const char* nB = has_next ? (const char*)g.Bt + (size_t)nxt.pn * tstep : cB;
;         for (int t = 0; t < nt; t += 2) {
;             const bool last = (t == nt - 2);
;             const char* a1 = cA + (size_t)(t + 1) * kstep;
;             const char* a2 = last ? nA : cA + (size_t)(t + 2) * kstep; const char* b2 = last ? nB : cB + (size_t)(t + 2) * kstep;
;             const char* a3 = a2 + kstep; const char* b3 = b2 + kstep;
;             if (last && has_next) S.a_ready(nxt);
;             if constexpr (SP2) {
;             PG8_LDB(B0, 0, 0); PG8_LDB(B1, 0, 1); PG8_SCHED; PG8_LDA(At, 0, 0); PG8_STAGE(PG8_SA(1, 1), a1 + hstep, voffA);
;             PG8_WAIT_V(8); PG8_WAIT_L(0); PG8_BAR; PG8_MMA(0, 0, At, B0); PG8_MMA(0, 1, At, B1); PG8_BAR; PG8_SCHED;
;             PG8_LDA(At, 0, 1); PG8_STAGE(PG8_SB(0, 0), b2, voffB); PG8_STAGE(PG8_SB(0, 1), b2 + hstepB, voffB); PG8_STAGE(PG8_SA(0, 0), a2, voffA);
.LBB0_184:
	s_ashr_i32 s21, s20, 31
	s_lshl_b64 s[24:25], s[20:21], 19
	s_add_u32 s24, s14, s24
	s_addc_u32 s25, s15, s25
	s_and_b64 s[30:31], s[28:29], exec
	s_cselect_b32 s3, s25, s39
	s_cselect_b32 s5, s24, s38
	s_add_u32 s5, s5, s32
	s_addc_u32 s3, s3, 0
	s_ashr_i32 s23, s22, 31
	s_lshl_b64 s[30:31], s[22:23], 19
	s_add_u32 s30, s12, s30
	s_addc_u32 s31, s13, s31
	s_and_b64 s[42:43], s[28:29], exec
	s_cselect_b32 s21, s31, s41
	s_cselect_b32 s23, s30, s40
	s_add_u32 s23, s23, s32
	s_addc_u32 s21, s21, 0
	s_add_u32 s38, s38, 0x40080
	s_addc_u32 s39, s39, 0
	s_mov_b32 s37, s40
	v_mov_b32_e32 v4, 0
	s_mov_b32 s66, s41
	s_mov_b32 s67, -2
	v_mov_b32_e32 v5, v4
	v_mov_b32_e32 v6, v4
	v_mov_b32_e32 v7, v4
	v_mov_b32_e32 v8, v4
	v_mov_b32_e32 v9, v4
	v_mov_b32_e32 v10, v4
	v_mov_b32_e32 v11, v4
	v_mov_b32_e32 v20, v4
	v_mov_b32_e32 v21, v4
	v_mov_b32_e32 v22, v4
	v_mov_b32_e32 v23, v4
	v_mov_b32_e32 v24, v4
	v_mov_b32_e32 v25, v4
	v_mov_b32_e32 v26, v4
	v_mov_b32_e32 v27, v4
	v_mov_b32_e32 v36, v4
	v_mov_b32_e32 v37, v4
	v_mov_b32_e32 v38, v4
	v_mov_b32_e32 v39, v4
	v_mov_b32_e32 v40, v4
	v_mov_b32_e32 v41, v4
	v_mov_b32_e32 v42, v4
	v_mov_b32_e32 v43, v4
	v_mov_b32_e32 v52, v4
	v_mov_b32_e32 v53, v4
	v_mov_b32_e32 v54, v4
	v_mov_b32_e32 v55, v4
	v_mov_b32_e32 v56, v4
	v_mov_b32_e32 v57, v4
	v_mov_b32_e32 v58, v4
	v_mov_b32_e32 v59, v4
	v_mov_b32_e32 v12, v4
	v_mov_b32_e32 v13, v4
	v_mov_b32_e32 v14, v4
	v_mov_b32_e32 v15, v4
	v_mov_b32_e32 v16, v4
	v_mov_b32_e32 v17, v4
	v_mov_b32_e32 v18, v4
	v_mov_b32_e32 v19, v4
	v_mov_b32_e32 v28, v4
	v_mov_b32_e32 v29, v4
	v_mov_b32_e32 v30, v4
	v_mov_b32_e32 v31, v4
	v_mov_b32_e32 v32, v4
	v_mov_b32_e32 v33, v4
	v_mov_b32_e32 v34, v4
	v_mov_b32_e32 v35, v4
	v_mov_b32_e32 v44, v4
	v_mov_b32_e32 v45, v4
	v_mov_b32_e32 v46, v4
	v_mov_b32_e32 v47, v4
	v_mov_b32_e32 v48, v4
	v_mov_b32_e32 v49, v4
	v_mov_b32_e32 v50, v4
	v_mov_b32_e32 v51, v4
	v_mov_b32_e32 v60, v4
	v_mov_b32_e32 v61, v4
	v_mov_b32_e32 v62, v4
	v_mov_b32_e32 v63, v4
	v_mov_b32_e32 v64, v4
	v_mov_b32_e32 v65, v4
	v_mov_b32_e32 v66, v4
	v_mov_b32_e32 v67, v4
	v_mov_b32_e32 v68, v4
	v_mov_b32_e32 v69, v4
	v_mov_b32_e32 v70, v4
	v_mov_b32_e32 v71, v4
	v_mov_b32_e32 v72, v4
	v_mov_b32_e32 v73, v4
	v_mov_b32_e32 v74, v4
	v_mov_b32_e32 v75, v4
	v_mov_b32_e32 v84, v4
	v_mov_b32_e32 v85, v4
	v_mov_b32_e32 v86, v4
	v_mov_b32_e32 v87, v4
	v_mov_b32_e32 v88, v4
	v_mov_b32_e32 v89, v4
	v_mov_b32_e32 v90, v4
	v_mov_b32_e32 v91, v4
	v_mov_b32_e32 v100, v4
	v_mov_b32_e32 v101, v4
	v_mov_b32_e32 v102, v4
	v_mov_b32_e32 v103, v4
	v_mov_b32_e32 v104, v4
	v_mov_b32_e32 v105, v4
	v_mov_b32_e32 v106, v4
	v_mov_b32_e32 v107, v4
	v_mov_b32_e32 v116, v4
	v_mov_b32_e32 v117, v4
	v_mov_b32_e32 v118, v4
	v_mov_b32_e32 v119, v4
	v_mov_b32_e32 v120, v4
	v_mov_b32_e32 v121, v4
	v_mov_b32_e32 v122, v4
	v_mov_b32_e32 v123, v4
	v_mov_b32_e32 v76, v4
	v_mov_b32_e32 v77, v4
	v_mov_b32_e32 v78, v4
	v_mov_b32_e32 v79, v4
	v_mov_b32_e32 v80, v4
	v_mov_b32_e32 v81, v4
	v_mov_b32_e32 v82, v4
	v_mov_b32_e32 v83, v4
	v_mov_b32_e32 v92, v4
	v_mov_b32_e32 v93, v4
	v_mov_b32_e32 v94, v4
	v_mov_b32_e32 v95, v4
	v_mov_b32_e32 v96, v4
	v_mov_b32_e32 v97, v4
	v_mov_b32_e32 v98, v4
	v_mov_b32_e32 v99, v4
	v_mov_b32_e32 v108, v4
	v_mov_b32_e32 v109, v4
	v_mov_b32_e32 v110, v4
	v_mov_b32_e32 v111, v4
	v_mov_b32_e32 v112, v4
	v_mov_b32_e32 v113, v4
	v_mov_b32_e32 v114, v4
	v_mov_b32_e32 v115, v4
	v_mov_b32_e32 v124, v4
	v_mov_b32_e32 v125, v4
	v_mov_b32_e32 v126, v4
	v_mov_b32_e32 v127, v4
	v_mov_b32_e32 v128, v4
	v_mov_b32_e32 v129, v4
	v_mov_b32_e32 v130, v4
	v_mov_b32_e32 v131, v4
.LBB0_185:
	s_lshl_b32 s100, s67, 7
	s_add_i32 s100, s100, s32
	s_add_i32 s100, s100, 0x100
	s_add_i32 s99, s100, 0x100
	s_and_b32 s100, s100, 0x700
	s_and_b32 s99, s99, 0x700
	s_add_u32 s100, s38, s100
	s_addc_u32 s101, s39, 0
	s_add_u32 s40, s38, 0xfffbff80
	s_addc_u32 s41, s39, -1
	s_add_u32 s40, s40, s99
	s_addc_u32 s41, s41, 0
	s_add_i32 s82, 0, 0x10000
	s_cmp_eq_u32 s67, 12
	s_cselect_b32 s43, s3, s41
	s_cselect_b32 s42, s5, s40
	v_add_u32_e32 v154, s82, v163
	s_add_u32 s40, s37, s99
	s_addc_u32 s41, s66, 0
	s_cmp_eq_u32 s67, 12
	s_cselect_b32 s41, s21, s41
	s_cselect_b32 s40, s23, s40
	s_add_i32 s84, 0, 0x14000
	ds_read_b128 v[146:149], v154
	ds_read_b128 v[150:153], v154 offset:1024
	ds_read_b128 v[170:173], v154 offset:2048
	ds_read_b128 v[174:177], v154 offset:3072
	v_add_u32_e32 v154, s84, v163
	ds_read_b128 v[178:181], v154
	ds_read_b128 v[182:185], v154 offset:1024
	ds_read_b128 v[186:189], v154 offset:2048
	ds_read_b128 v[190:193], v154 offset:3072
	v_lshl_add_u64 v[154:155], s[100:101], 0, v[142:143]
	s_add_i32 m0, s63, 0xc000
	ds_read_b128 v[194:197], v166
	ds_read_b128 v[198:201], v166 offset:1024
	ds_read_b128 v[212:215], v166 offset:2048
	ds_read_b128 v[216:219], v166 offset:3072
	ds_read_b128 v[220:223], v166 offset:4096
	ds_read_b128 v[224:227], v166 offset:5120
	ds_read_b128 v[228:231], v166 offset:6144
	ds_read_b128 v[232:235], v166 offset:7168
	global_load_lds_dwordx4 v[154:155], off
	v_lshl_add_u64 v[154:155], s[100:101], 0, v[144:145]
	s_add_i32 m0, s63, 0xe000
	s_nop 0
	global_load_lds_dwordx4 v[154:155], off
	s_waitcnt vmcnt(8)
	s_waitcnt lgkmcnt(0)
	s_barrier
; #define PG8_STAGE(bufoff, gbase, voff) do { _Pragma("unroll") for (int _i = 0; _i < 2; ++_i) \
;         __builtin_amdgcn_global_load_lds((const unsigned*)((const char*)(gbase) + (voff)[_i]), (PG8_LAS unsigned*)(lds + (bufoff) + ldsw + _i * 8192), 16, 0, 0); } while (0)
; #define PG8_LDA(dst, b, h) do { _Pragma("unroll") for (int m = 0; m < 4; ++m) _Pragma("unroll") for (int k = 0; k < 2; ++k) dst[m][k] = *(const PG8_LAS bf16x8*)(lds + PG8_SA(b, h) + aoff + m * 2048 + k * 1024); } while (0)
; #define PG8_LDB(dst, b, h) do { _Pragma("unroll") for (int n = 0; n < 2; ++n) _Pragma("unroll") for (int k = 0; k < 2; ++k) dst[n][k] = *(const PG8_LAS bf16x8*)(lds + PG8_SB(b, h) + boff + n * 2048 + k * 1024); } while (0)
; #define PG8_MMA(ai, bj, At, Bt) do { __builtin_amdgcn_s_setprio(1); _Pragma("unroll") for (int m = 0; m < 4; ++m) _Pragma("unroll") for (int n = 0; n < 2; ++n) _Pragma("unroll") for (int k = 0; k < 2; ++k) \
;         acc[ai][bj][m][n] = __builtin_amdgcn_mfma_f32_16x16x32_bf16(Bt[n][k], At[m][k], acc[ai][bj][m][n], 0, 0, 0); __builtin_amdgcn_s_setprio(0); } while (0)
; #define PG8_WAIT_V(n) asm volatile("s_waitcnt vmcnt(" #n ")" ::: "memory")
; #define PG8_WAIT_L(n) asm volatile("s_waitcnt lgkmcnt(" #n ")" ::: "memory")
; #define PG8_BAR __builtin_amdgcn_s_barrier()
; #define PG8_SCHED __builtin_amdgcn_sched_barrier(0)
; template <class Epi, class Sched, bool ALIGN_EPI = false, bool SP2 = false>
; __device__ __forceinline__ void gemm_phase(PG8_LAS unsigned char* lds, const Gemm g, const Sched& S, const Epi& E, const int tid) {
;     ...
;             PG8_LDB(B0, 0, 0); PG8_LDB(B1, 0, 1); PG8_SCHED; PG8_LDA(At, 0, 0); PG8_STAGE(PG8_SA(1, 1), a1 + hstep, voffA);
;             PG8_WAIT_V(8); PG8_WAIT_L(0); PG8_BAR; PG8_MMA(0, 0, At, B0); PG8_MMA(0, 1, At, B1); PG8_BAR; PG8_SCHED;
;             PG8_LDA(At, 0, 1); PG8_STAGE(PG8_SB(0, 0), b2, voffB); PG8_STAGE(PG8_SB(0, 1), b2 + hstepB, voffB); PG8_STAGE(PG8_SA(0, 0), a2, voffA);
;             PG8_WAIT_V(8); PG8_WAIT_L(0); PG8_BAR; PG8_MMA(1, 0, At, B0); PG8_MMA(1, 1, At, B1); PG8_BAR; PG8_SCHED;
	s_setprio 1
	s_waitcnt lgkmcnt(0)
	v_mfma_f32_16x16x32_bf16 v[128:131], v[146:149], v[194:197], v[128:131]
	v_mfma_f32_16x16x32_bf16 v[124:127], v[170:173], v[194:197], v[124:127]
	v_mfma_f32_16x16x32_bf16 v[112:115], v[146:149], v[212:215], v[112:115]
	v_mfma_f32_16x16x32_bf16 v[108:111], v[170:173], v[212:215], v[108:111]
	v_mfma_f32_16x16x32_bf16 v[96:99], v[146:149], v[220:223], v[96:99]
	v_mfma_f32_16x16x32_bf16 v[92:95], v[170:173], v[220:223], v[92:95]
	v_mfma_f32_16x16x32_bf16 v[80:83], v[146:149], v[228:231], v[80:83]
	v_mfma_f32_16x16x32_bf16 v[76:79], v[170:173], v[228:231], v[76:79]
	v_mfma_f32_16x16x32_bf16 v[128:131], v[150:153], v[198:201], v[128:131]
	v_mfma_f32_16x16x32_bf16 v[124:127], v[174:177], v[198:201], v[124:127]
	v_mfma_f32_16x16x32_bf16 v[112:115], v[150:153], v[216:219], v[112:115]
	v_mfma_f32_16x16x32_bf16 v[108:111], v[174:177], v[216:219], v[108:111]
	v_mfma_f32_16x16x32_bf16 v[96:99], v[150:153], v[224:227], v[96:99]
	v_mfma_f32_16x16x32_bf16 v[92:95], v[174:177], v[224:227], v[92:95]
	v_mfma_f32_16x16x32_bf16 v[80:83], v[150:153], v[232:235], v[80:83]
	v_mfma_f32_16x16x32_bf16 v[76:79], v[174:177], v[232:235], v[76:79]
	s_setprio 0
	s_setprio 1
	v_mfma_f32_16x16x32_bf16 v[120:123], v[178:181], v[194:197], v[120:123]
	v_mfma_f32_16x16x32_bf16 v[116:119], v[186:189], v[194:197], v[116:119]
	v_mfma_f32_16x16x32_bf16 v[104:107], v[178:181], v[212:215], v[104:107]
	v_mfma_f32_16x16x32_bf16 v[100:103], v[186:189], v[212:215], v[100:103]
	v_mfma_f32_16x16x32_bf16 v[88:91], v[178:181], v[220:223], v[88:91]
	v_mfma_f32_16x16x32_bf16 v[84:87], v[186:189], v[220:223], v[84:87]
	v_mfma_f32_16x16x32_bf16 v[72:75], v[178:181], v[228:231], v[72:75]
	v_mfma_f32_16x16x32_bf16 v[68:71], v[186:189], v[228:231], v[68:71]
	v_mfma_f32_16x16x32_bf16 v[120:123], v[182:185], v[198:201], v[120:123]
	v_mfma_f32_16x16x32_bf16 v[116:119], v[190:193], v[198:201], v[116:119]
	v_mfma_f32_16x16x32_bf16 v[104:107], v[182:185], v[216:219], v[104:107]
	v_mfma_f32_16x16x32_bf16 v[100:103], v[190:193], v[216:219], v[100:103]
	v_mfma_f32_16x16x32_bf16 v[88:91], v[182:185], v[224:227], v[88:91]
	v_mfma_f32_16x16x32_bf16 v[84:87], v[190:193], v[224:227], v[84:87]
	v_mfma_f32_16x16x32_bf16 v[72:75], v[182:185], v[232:235], v[72:75]
	v_mfma_f32_16x16x32_bf16 v[68:71], v[190:193], v[232:235], v[68:71]
	s_setprio 0
	s_barrier
	s_add_i32 s82, s82, s62
	v_lshl_add_u64 v[154:155], s[40:41], 0, v[136:137]
	s_mov_b32 m0, s82
	ds_read_b128 v[194:197], v166 offset:16384
	ds_read_b128 v[198:201], v166 offset:17408
	ds_read_b128 v[212:215], v166 offset:18432
	ds_read_b128 v[216:219], v166 offset:19456
	ds_read_b128 v[220:223], v166 offset:20480
	ds_read_b128 v[224:227], v166 offset:21504
	ds_read_b128 v[228:231], v166 offset:22528
	ds_read_b128 v[232:235], v166 offset:23552
	global_load_lds_dwordx4 v[154:155], off
	s_add_i32 m0, s82, 0x2000
	s_add_u32 s82, s40, 0x10000
	v_lshl_add_u64 v[236:237], s[40:41], 0, v[140:141]
	s_addc_u32 s83, s41, 0
	s_add_i32 s84, s84, s62
	global_load_lds_dwordx4 v[236:237], off
	v_lshl_add_u64 v[238:239], s[82:83], 0, v[136:137]
	s_mov_b32 m0, s84
	v_lshl_add_u64 v[240:241], s[42:43], 0, v[138:139]
	global_load_lds_dwordx4 v[238:239], off
	v_lshl_add_u64 v[238:239], s[82:83], 0, v[140:141]
	s_add_i32 m0, s84, 0x2000
	s_nop 0
	global_load_lds_dwordx4 v[238:239], off
	v_lshl_add_u64 v[238:239], s[42:43], 0, v[134:135]
	s_mov_b32 m0, s63
	s_nop 0
	global_load_lds_dwordx4 v[238:239], off
	s_mov_b32 m0, s64
	s_nop 0
	global_load_lds_dwordx4 v[240:241], off
	s_waitcnt vmcnt(8)
	s_waitcnt lgkmcnt(0)
	s_barrier
	s_setprio 1
	s_waitcnt lgkmcnt(0)
	v_mfma_f32_16x16x32_bf16 v[64:67], v[146:149], v[194:197], v[64:67]
	v_mfma_f32_16x16x32_bf16 v[60:63], v[170:173], v[194:197], v[60:63]
	v_mfma_f32_16x16x32_bf16 v[48:51], v[146:149], v[212:215], v[48:51]
	v_mfma_f32_16x16x32_bf16 v[44:47], v[170:173], v[212:215], v[44:47]
	v_mfma_f32_16x16x32_bf16 v[32:35], v[146:149], v[220:223], v[32:35]
	v_mfma_f32_16x16x32_bf16 v[28:31], v[170:173], v[220:223], v[28:31]
	v_mfma_f32_16x16x32_bf16 v[16:19], v[146:149], v[228:231], v[16:19]
	v_mfma_f32_16x16x32_bf16 v[12:15], v[170:173], v[228:231], v[12:15]
	v_mfma_f32_16x16x32_bf16 v[64:67], v[150:153], v[198:201], v[64:67]
	v_mfma_f32_16x16x32_bf16 v[60:63], v[174:177], v[198:201], v[60:63]
	v_mfma_f32_16x16x32_bf16 v[48:51], v[150:153], v[216:219], v[48:51]
	v_mfma_f32_16x16x32_bf16 v[44:47], v[174:177], v[216:219], v[44:47]
	v_mfma_f32_16x16x32_bf16 v[32:35], v[150:153], v[224:227], v[32:35]
	v_mfma_f32_16x16x32_bf16 v[28:31], v[174:177], v[224:227], v[28:31]
	v_mfma_f32_16x16x32_bf16 v[16:19], v[150:153], v[232:235], v[16:19]
	v_mfma_f32_16x16x32_bf16 v[12:15], v[174:177], v[232:235], v[12:15]
	s_setprio 0
	s_setprio 1
	v_mfma_f32_16x16x32_bf16 v[56:59], v[178:181], v[194:197], v[56:59]
	v_mfma_f32_16x16x32_bf16 v[52:55], v[186:189], v[194:197], v[52:55]
	v_mfma_f32_16x16x32_bf16 v[40:43], v[178:181], v[212:215], v[40:43]
	v_mfma_f32_16x16x32_bf16 v[36:39], v[186:189], v[212:215], v[36:39]
	v_mfma_f32_16x16x32_bf16 v[24:27], v[178:181], v[220:223], v[24:27]
	v_mfma_f32_16x16x32_bf16 v[20:23], v[186:189], v[220:223], v[20:23]
	v_mfma_f32_16x16x32_bf16 v[8:11], v[178:181], v[228:231], v[8:11]
	v_mfma_f32_16x16x32_bf16 v[4:7], v[186:189], v[228:231], v[4:7]
	v_mfma_f32_16x16x32_bf16 v[56:59], v[182:185], v[198:201], v[56:59]
	v_mfma_f32_16x16x32_bf16 v[52:55], v[190:193], v[198:201], v[52:55]
	v_mfma_f32_16x16x32_bf16 v[40:43], v[182:185], v[216:219], v[40:43]
	v_mfma_f32_16x16x32_bf16 v[36:39], v[190:193], v[216:219], v[36:39]
	v_mfma_f32_16x16x32_bf16 v[24:27], v[182:185], v[224:227], v[24:27]
	v_mfma_f32_16x16x32_bf16 v[20:23], v[190:193], v[224:227], v[20:23]
	v_mfma_f32_16x16x32_bf16 v[8:11], v[182:185], v[232:235], v[8:11]
	v_mfma_f32_16x16x32_bf16 v[4:7], v[190:193], v[232:235], v[4:7]
	s_setprio 0
	s_barrier
; #define PG8_STAGE(bufoff, gbase, voff) do { _Pragma("unroll") for (int _i = 0; _i < 2; ++_i) \
;         __builtin_amdgcn_global_load_lds((const unsigned*)((const char*)(gbase) + (voff)[_i]), (PG8_LAS unsigned*)(lds + (bufoff) + ldsw + _i * 8192), 16, 0, 0); } while (0)
; #define PG8_LDA(dst, b, h) do { _Pragma("unroll") for (int m = 0; m < 4; ++m) _Pragma("unroll") for (int k = 0; k < 2; ++k) dst[m][k] = *(const PG8_LAS bf16x8*)(lds + PG8_SA(b, h) + aoff + m * 2048 + k * 1024); } while (0)
; #define PG8_LDB(dst, b, h) do { _Pragma("unroll") for (int n = 0; n < 2; ++n) _Pragma("unroll") for (int k = 0; k < 2; ++k) dst[n][k] = *(const PG8_LAS bf16x8*)(lds + PG8_SB(b, h) + boff + n * 2048 + k * 1024); } while (0)
; #define PG8_MMA(ai, bj, At, Bt) do { __builtin_amdgcn_s_setprio(1); _Pragma("unroll") for (int m = 0; m < 4; ++m) _Pragma("unroll") for (int n = 0; n < 2; ++n) _Pragma("unroll") for (int k = 0; k < 2; ++k) \
;         acc[ai][bj][m][n] = __builtin_amdgcn_mfma_f32_16x16x32_bf16(Bt[n][k], At[m][k], acc[ai][bj][m][n], 0, 0, 0); __builtin_amdgcn_s_setprio(0); } while (0)
; #define PG8_WAIT_V(n) asm volatile("s_waitcnt vmcnt(" #n ")" ::: "memory")
; #define PG8_WAIT_L(n) asm volatile("s_waitcnt lgkmcnt(" #n ")" ::: "memory")
; #define PG8_BAR __builtin_amdgcn_s_barrier()
; #define PG8_SCHED __builtin_amdgcn_sched_barrier(0)
; template <class Epi, class Sched, bool ALIGN_EPI = false, bool SP2 = false>
; __device__ __forceinline__ void gemm_phase(PG8_LAS unsigned char* lds, const Gemm g, const Sched& S, const Epi& E, const int tid) {
;     ...
;             PG8_LDB(B0, 1, 0); PG8_LDB(B1, 1, 1); PG8_SCHED; PG8_LDA(At, 1, 0); PG8_STAGE(PG8_SA(0, 1), a2 + hstep, voffA);
;             PG8_WAIT_V(8); PG8_WAIT_L(0); PG8_BAR; PG8_MMA(0, 0, At, B0); PG8_MMA(0, 1, At, B1); PG8_BAR; PG8_SCHED;
	s_add_i32 s82, 0, 0x18000
	v_add_u32_e32 v167, s82, v163
	s_add_i32 s83, 0, 0x1c000
	ds_read_b128 v[146:149], v167
	ds_read_b128 v[150:153], v167 offset:1024
	ds_read_b128 v[170:173], v167 offset:2048
	ds_read_b128 v[174:177], v167 offset:3072
	v_add_u32_e32 v167, s83, v163
	ds_read_b128 v[178:181], v167
	ds_read_b128 v[182:185], v167 offset:1024
	ds_read_b128 v[186:189], v167 offset:2048
	ds_read_b128 v[190:193], v167 offset:3072
	s_add_u32 s42, s42, 0x40000
	s_addc_u32 s43, s43, 0
	s_mov_b32 m0, s65
	v_lshl_add_u64 v[242:243], s[42:43], 0, v[134:135]
	ds_read_b128 v[194:197], v166 offset:32768
	ds_read_b128 v[198:201], v166 offset:33792
	ds_read_b128 v[212:215], v166 offset:34816
	ds_read_b128 v[216:219], v166 offset:35840
	ds_read_b128 v[220:223], v166 offset:36864
	ds_read_b128 v[224:227], v166 offset:37888
	ds_read_b128 v[228:231], v166 offset:38912
	ds_read_b128 v[232:235], v166 offset:39936
	global_load_lds_dwordx4 v[242:243], off
	v_lshl_add_u64 v[242:243], s[42:43], 0, v[138:139]
	s_mov_b32 m0, s76
	s_nop 0
	global_load_lds_dwordx4 v[242:243], off
	s_waitcnt vmcnt(8)
	s_waitcnt lgkmcnt(0)
	s_barrier
	s_setprio 1
	s_waitcnt lgkmcnt(0)
	v_mfma_f32_16x16x32_bf16 v[128:131], v[146:149], v[194:197], v[128:131]
	v_mfma_f32_16x16x32_bf16 v[124:127], v[170:173], v[194:197], v[124:127]
	v_mfma_f32_16x16x32_bf16 v[112:115], v[146:149], v[212:215], v[112:115]
	v_mfma_f32_16x16x32_bf16 v[108:111], v[170:173], v[212:215], v[108:111]
	v_mfma_f32_16x16x32_bf16 v[96:99], v[146:149], v[220:223], v[96:99]
	v_mfma_f32_16x16x32_bf16 v[92:95], v[170:173], v[220:223], v[92:95]
	v_mfma_f32_16x16x32_bf16 v[80:83], v[146:149], v[228:231], v[80:83]
	v_mfma_f32_16x16x32_bf16 v[76:79], v[170:173], v[228:231], v[76:79]
	v_mfma_f32_16x16x32_bf16 v[128:131], v[150:153], v[198:201], v[128:131]
	v_mfma_f32_16x16x32_bf16 v[124:127], v[174:177], v[198:201], v[124:127]
	v_mfma_f32_16x16x32_bf16 v[112:115], v[150:153], v[216:219], v[112:115]
	v_mfma_f32_16x16x32_bf16 v[108:111], v[174:177], v[216:219], v[108:111]
	v_mfma_f32_16x16x32_bf16 v[96:99], v[150:153], v[224:227], v[96:99]
	v_mfma_f32_16x16x32_bf16 v[92:95], v[174:177], v[224:227], v[92:95]
	v_mfma_f32_16x16x32_bf16 v[80:83], v[150:153], v[232:235], v[80:83]
	v_mfma_f32_16x16x32_bf16 v[76:79], v[174:177], v[232:235], v[76:79]
	s_setprio 0
	s_setprio 1
	v_mfma_f32_16x16x32_bf16 v[120:123], v[178:181], v[194:197], v[120:123]
	v_mfma_f32_16x16x32_bf16 v[116:119], v[186:189], v[194:197], v[116:119]
	v_mfma_f32_16x16x32_bf16 v[104:107], v[178:181], v[212:215], v[104:107]
	v_mfma_f32_16x16x32_bf16 v[100:103], v[186:189], v[212:215], v[100:103]
	v_mfma_f32_16x16x32_bf16 v[88:91], v[178:181], v[220:223], v[88:91]
	v_mfma_f32_16x16x32_bf16 v[84:87], v[186:189], v[220:223], v[84:87]
	v_mfma_f32_16x16x32_bf16 v[72:75], v[178:181], v[228:231], v[72:75]
	v_mfma_f32_16x16x32_bf16 v[68:71], v[186:189], v[228:231], v[68:71]
	v_mfma_f32_16x16x32_bf16 v[120:123], v[182:185], v[198:201], v[120:123]
	v_mfma_f32_16x16x32_bf16 v[116:119], v[190:193], v[198:201], v[116:119]
	v_mfma_f32_16x16x32_bf16 v[104:107], v[182:185], v[216:219], v[104:107]
	v_mfma_f32_16x16x32_bf16 v[100:103], v[190:193], v[216:219], v[100:103]
	v_mfma_f32_16x16x32_bf16 v[88:91], v[182:185], v[224:227], v[88:91]
	v_mfma_f32_16x16x32_bf16 v[84:87], v[190:193], v[224:227], v[84:87]
	v_mfma_f32_16x16x32_bf16 v[72:75], v[182:185], v[232:235], v[72:75]
	v_mfma_f32_16x16x32_bf16 v[68:71], v[190:193], v[232:235], v[68:71]
	s_setprio 0
	s_barrier
; #define PG8_STAGE(bufoff, gbase, voff) do { _Pragma("unroll") for (int _i = 0; _i < 2; ++_i) \
;         __builtin_amdgcn_global_load_lds((const unsigned*)((const char*)(gbase) + (voff)[_i]), (PG8_LAS unsigned*)(lds + (bufoff) + ldsw + _i * 8192), 16, 0, 0); } while (0)
; #define PG8_LDA(dst, b, h) do { _Pragma("unroll") for (int m = 0; m < 4; ++m) _Pragma("unroll") for (int k = 0; k < 2; ++k) dst[m][k] = *(const PG8_LAS bf16x8*)(lds + PG8_SA(b, h) + aoff + m * 2048 + k * 1024); } while (0)
; #define PG8_MMA(ai, bj, At, Bt) do { __builtin_amdgcn_s_setprio(1); _Pragma("unroll") for (int m = 0; m < 4; ++m) _Pragma("unroll") for (int n = 0; n < 2; ++n) _Pragma("unroll") for (int k = 0; k < 2; ++k) \
;         acc[ai][bj][m][n] = __builtin_amdgcn_mfma_f32_16x16x32_bf16(Bt[n][k], At[m][k], acc[ai][bj][m][n], 0, 0, 0); __builtin_amdgcn_s_setprio(0); } while (0)
; #define PG8_WAIT_V(n) asm volatile("s_waitcnt vmcnt(" #n ")" ::: "memory")
; #define PG8_WAIT_L(n) asm volatile("s_waitcnt lgkmcnt(" #n ")" ::: "memory")
; #define PG8_BAR __builtin_amdgcn_s_barrier()
; #define PG8_SCHED __builtin_amdgcn_sched_barrier(0)
; template <class Epi, class Sched, bool ALIGN_EPI = false, bool SP2 = false>
; __device__ __forceinline__ void gemm_phase(PG8_LAS unsigned char* lds, const Gemm g, const Sched& S, const Epi& E, const int tid) {
;     ...
;         for (int t = 0; t < nt; t += 2) {
;     ...
;             PG8_LDA(At, 1, 1); PG8_STAGE(PG8_SB(1, 0), b3, voffB); PG8_STAGE(PG8_SB(1, 1), b3 + hstepB, voffB); PG8_STAGE(PG8_SA(1, 0), a3, voffA);
;             PG8_WAIT_V(8); PG8_WAIT_L(0); PG8_BAR; PG8_MMA(1, 0, At, B0); PG8_MMA(1, 1, At, B1); PG8_BAR; PG8_SCHED;
	s_add_i32 s42, s82, s62
	v_lshl_add_u64 v[154:155], v[154:155], 0, s[52:53]
	s_mov_b32 m0, s42
	ds_read_b128 v[194:197], v166 offset:49152
	ds_read_b128 v[198:201], v166 offset:50176
	ds_read_b128 v[212:215], v166 offset:51200
	ds_read_b128 v[216:219], v166 offset:52224
	ds_read_b128 v[220:223], v166 offset:53248
	ds_read_b128 v[224:227], v166 offset:54272
	ds_read_b128 v[228:231], v166 offset:55296
	ds_read_b128 v[232:235], v166 offset:56320
	global_load_lds_dwordx4 v[154:155], off
	s_add_i32 m0, s42, 0x2000
	s_add_u32 s40, s40, 0x10080
	v_lshl_add_u64 v[154:155], v[236:237], 0, s[52:53]
	s_addc_u32 s41, s41, 0
	s_add_i32 s42, s83, s62
	global_load_lds_dwordx4 v[154:155], off
	v_lshl_add_u64 v[154:155], s[40:41], 0, v[136:137]
	s_mov_b32 m0, s42
	s_nop 0
	global_load_lds_dwordx4 v[154:155], off
	v_lshl_add_u64 v[154:155], s[40:41], 0, v[140:141]
	s_add_i32 m0, s42, 0x2000
	s_nop 0
	global_load_lds_dwordx4 v[154:155], off
	v_lshl_add_u64 v[154:155], v[238:239], 0, s[52:53]
	s_mov_b32 m0, s78
	s_nop 0
	global_load_lds_dwordx4 v[154:155], off
	v_lshl_add_u64 v[154:155], v[240:241], 0, s[52:53]
	s_mov_b32 m0, s79
	s_nop 0
	global_load_lds_dwordx4 v[154:155], off
	s_waitcnt vmcnt(8)
	s_waitcnt lgkmcnt(0)
	s_barrier
	s_setprio 1
	s_waitcnt lgkmcnt(0)
	v_mfma_f32_16x16x32_bf16 v[64:67], v[146:149], v[194:197], v[64:67]
	v_mfma_f32_16x16x32_bf16 v[60:63], v[170:173], v[194:197], v[60:63]
	v_mfma_f32_16x16x32_bf16 v[48:51], v[146:149], v[212:215], v[48:51]
	v_mfma_f32_16x16x32_bf16 v[44:47], v[170:173], v[212:215], v[44:47]
	v_mfma_f32_16x16x32_bf16 v[32:35], v[146:149], v[220:223], v[32:35]
	v_mfma_f32_16x16x32_bf16 v[28:31], v[170:173], v[220:223], v[28:31]
	v_mfma_f32_16x16x32_bf16 v[16:19], v[146:149], v[228:231], v[16:19]
	v_mfma_f32_16x16x32_bf16 v[12:15], v[170:173], v[228:231], v[12:15]
	v_mfma_f32_16x16x32_bf16 v[64:67], v[150:153], v[198:201], v[64:67]
	v_mfma_f32_16x16x32_bf16 v[60:63], v[174:177], v[198:201], v[60:63]
	v_mfma_f32_16x16x32_bf16 v[48:51], v[150:153], v[216:219], v[48:51]
	v_mfma_f32_16x16x32_bf16 v[44:47], v[174:177], v[216:219], v[44:47]
	v_mfma_f32_16x16x32_bf16 v[32:35], v[150:153], v[224:227], v[32:35]
	v_mfma_f32_16x16x32_bf16 v[28:31], v[174:177], v[224:227], v[28:31]
	v_mfma_f32_16x16x32_bf16 v[16:19], v[150:153], v[232:235], v[16:19]
	v_mfma_f32_16x16x32_bf16 v[12:15], v[174:177], v[232:235], v[12:15]
	s_setprio 0
	s_setprio 1
	v_mfma_f32_16x16x32_bf16 v[56:59], v[178:181], v[194:197], v[56:59]
	v_mfma_f32_16x16x32_bf16 v[52:55], v[186:189], v[194:197], v[52:55]
	v_mfma_f32_16x16x32_bf16 v[40:43], v[178:181], v[212:215], v[40:43]
	v_mfma_f32_16x16x32_bf16 v[36:39], v[186:189], v[212:215], v[36:39]
	v_mfma_f32_16x16x32_bf16 v[24:27], v[178:181], v[220:223], v[24:27]
	v_mfma_f32_16x16x32_bf16 v[20:23], v[186:189], v[220:223], v[20:23]
	v_mfma_f32_16x16x32_bf16 v[8:11], v[178:181], v[228:231], v[8:11]
	v_mfma_f32_16x16x32_bf16 v[4:7], v[186:189], v[228:231], v[4:7]
	v_mfma_f32_16x16x32_bf16 v[56:59], v[182:185], v[198:201], v[56:59]
	v_mfma_f32_16x16x32_bf16 v[52:55], v[190:193], v[198:201], v[52:55]
	v_mfma_f32_16x16x32_bf16 v[40:43], v[182:185], v[216:219], v[40:43]
	v_mfma_f32_16x16x32_bf16 v[36:39], v[190:193], v[216:219], v[36:39]
	v_mfma_f32_16x16x32_bf16 v[24:27], v[182:185], v[224:227], v[24:27]
	v_mfma_f32_16x16x32_bf16 v[20:23], v[190:193], v[224:227], v[20:23]
	v_mfma_f32_16x16x32_bf16 v[8:11], v[182:185], v[232:235], v[8:11]
	v_mfma_f32_16x16x32_bf16 v[4:7], v[190:193], v[232:235], v[4:7]
	s_setprio 0
	s_barrier
	s_add_i32 s67, s67, 2
	s_cmp_gt_u32 s67, 13
	s_cbranch_scc0 .LBB0_185
	s_and_b64 vcc, exec, s[18:19]
	s_cbranch_vccz .LBB0_188
	s_barrier

; template <class Epi, class Sched, bool ALIGN_EPI = false, bool SP2 = false>
; __device__ __forceinline__ void gemm_phase(PG8_LAS unsigned char* lds, const Gemm g, const Sched& S, const Epi& E, const int tid) {
;     const int wid = __builtin_amdgcn_readfirstlane(tid >> 6), lane = tid & 63, wr = wid >> 2, wc = wid & 3, fr = lane & 15, fq = lane >> 4;
;     const int K = g.K, nt = K / BK;
;     unsigned voffA[2], voffB[2];
; #pragma unroll
;     for (int i = 0; i < 2; ++i) { int R, C; stage_rc(tid * 16 + i * 8192, R, C); const int Rb = Epi::PERM ? (2 * (R & ~31) + perm32(R & 31)) : R;
;         voffA[i] = (unsigned)(R * K + C) * 2u; voffB[i] = (unsigned)(Rb * K + C) * 2u; }
;     const size_t kstep = (size_t)(BK * 2);
;     const size_t hstep = (size_t)HALF * K * 2;
;     const size_t tstep = 2 * hstep;
;     const size_t hstepB = Epi::PERM ? (size_t)32 * K * 2 : hstep;
;     const unsigned ldsw = (unsigned)wid * 1024u;
;     const int aoff = lds_byte(wr * 64 + fr, fq * 8), boff = lds_byte(wc * 32 + fr, fq * 8);
;     ...
;     Unit cur, nxt; int ui = 0;
;     if (!S.next(0, cur)) return;
;     f32x4 acc[2][2][4][2];
;     u32x4 iw_[Epi::HAS_INIT ? 16 : 1];
;     if constexpr (Epi::HAS_INIT) E.init_issue(iw_, cur, wr, wc, fr, fq);
;     else {
; #pragma unroll
;     for (int a = 0; a < 2; ++a)
; #pragma unroll
;         for (int b = 0; b < 2; ++b)
; #pragma unroll
;             for (int m = 0; m < 4; ++m)
; #pragma unroll
;                 for (int n = 0; n < 2; ++n) acc[a][b][m][n] = (f32x4){0.f, 0.f, 0.f, 0.f};
;     }
;     bf16x8 At[4][2], B0[2][2], B1[2][2];
;     const char* cA = (const char*)g.A + (size_t)cur.pm * tstep; const char* cB = (const char*)g.Bt + (size_t)cur.pn * tstep;
;     S.a_ready(cur);
;     if constexpr (SP2) {
;         PG8_STAGE(PG8_SB(0, 0), cB, voffB); PG8_STAGE(PG8_SB(0, 1), cB + hstepB, voffB); PG8_STAGE(PG8_SA(0, 0), cA, voffA); PG8_STAGE(PG8_SA(0, 1), cA + hstep, voffA);
;         if (wr == 1) PG8_BAR;
;         PG8_WAIT_V(2); PG8_BAR;
;         PG8_STAGE(PG8_SB(1, 0), cB + kstep, voffB); PG8_STAGE(PG8_SA(1, 0), cA + kstep, voffA); PG8_STAGE(PG8_SB(1, 1), cB + hstepB + kstep, voffB);
;         PG8_WAIT_V(6); PG8_BAR;
;     } else {
;         PG8_STAGE(PG8_SB(0, 0), cB, voffB); PG8_STAGE(PG8_SA(0, 0), cA, voffA); PG8_STAGE(PG8_SB(0, 1), cB + hstepB, voffB); PG8_STAGE(PG8_SA(0, 1), cA + hstep, voffA);
;         if (wr == 1) PG8_BAR;
.LBB0_607:
	v_ashrrev_i32_e32 v5, 31, v3
	s_lshl_b64 s[0:1], s[94:95], 22
	v_lshrrev_b32_e32 v5, 26, v5
	s_add_u32 s0, s18, s0
	v_add_u32_e32 v5, v3, v5
	s_addc_u32 s1, s19, s1
	v_ashrrev_i32_e32 v12, 6, v5
	v_bfe_i32 v5, v3, 27, 1
	s_add_u32 s28, s0, 0x6100000
	v_lshlrev_b32_e32 v4, 4, v3
	v_lshrrev_b32_e32 v5, 22, v5
	s_addc_u32 s29, s1, 0
	v_add_u32_e32 v5, v4, v5
	s_add_u32 s24, s18, 0xc300000
	v_and_b32_e32 v5, 0xfffffc00, v5
	s_addc_u32 s25, s19, 0
	v_sub_u32_e32 v5, v4, v5
	s_add_u32 s0, s18, 0x10b00000
	v_lshrrev_b32_e32 v6, 4, v5
	s_addc_u32 s1, s19, 0
	v_bitop3_b32 v5, v6, v5, 32 bitop3:0x6c
	s_add_u32 s14, s18, 0x12d00000
	v_ashrrev_i32_e32 v7, 31, v5
	s_addc_u32 s15, s19, 0
	s_mul_i32 s9, s94, 0x18000
	v_lshrrev_b32_e32 v7, 26, v7
	s_mul_hi_u32 s7, s94, 0x18000
	s_add_u32 s9, s16, s9
	v_add_u32_e32 v7, v5, v7
	s_addc_u32 s7, s17, s7
	v_lshlrev_b32_e32 v6, 3, v12
	v_ashrrev_i32_e32 v13, 6, v7
	v_and_b32_e32 v7, 0xc0, v7
	s_add_u32 s18, s9, 0x8410000
	v_and_b32_e32 v6, -16, v6
	v_sub_u32_e32 v5, v5, v7
	s_addc_u32 s19, s7, 0
	s_mul_i32 s9, s94, 0x180000
	v_add_u32_e32 v133, v13, v6
	v_ashrrev_i16_sdwa v5, v205, sext(v5) dst_sel:DWORD dst_unused:UNUSED_PAD src0_sel:DWORD src1_sel:BYTE_0
	s_mul_hi_u32 s7, s94, 0x180000
	s_add_u32 s9, s16, s9
	v_lshlrev_b32_e32 v6, 5, v12
	v_bfe_i32 v14, v5, 0, 16
	v_lshrrev_b32_e32 v5, 2, v133
	s_addc_u32 s7, s17, s7
	v_and_b32_e32 v6, 32, v6
	v_and_b32_e32 v171, 4, v5
	v_lshrrev_b32_e32 v5, 1, v3
	s_add_u32 s20, s9, 0x8d40000
	v_add_u32_e32 v132, v6, v14
	v_lshlrev_b32_e32 v173, 1, v133
	v_and_b32_e32 v172, 3, v13
	v_and_b32_e32 v170, 15, v3
	s_addc_u32 s21, s7, 0
	s_andn2_b64 vcc, exec, s[4:5]
	v_and_b32_e32 v143, 24, v5
	s_cbranch_vccnz .LBB0_735
	v_and_b32_e32 v5, 0x1fffd8, v173
	v_or3_b32 v5, v172, v5, v171
	v_lshlrev_b32_e32 v6, 1, v132
	v_add_u32_e32 v4, 0x2000, v4
	v_lshl_add_u32 v136, v5, 11, v6
	v_ashrrev_i32_e32 v5, 31, v4
	v_lshrrev_b32_e32 v5, 22, v5
	v_add_u32_e32 v5, v4, v5
	v_ashrrev_i32_e32 v15, 10, v5
	v_mul_i32_i24_e32 v5, 0x400, v15
	v_sub_u32_e32 v4, v4, v5
	v_lshrrev_b32_e32 v5, 4, v4
	v_bitop3_b32 v4, v5, v4, 32 bitop3:0x6c
	v_lshl_add_u32 v134, v133, 11, v6
	v_ashrrev_i32_e32 v6, 31, v4
	v_lshrrev_b32_e32 v6, 26, v6
	v_add_u32_e32 v6, v4, v6
	s_ashr_i32 s4, s3, 6
	v_lshlrev_b32_e32 v5, 3, v15
	v_ashrrev_i32_e32 v16, 6, v6
	v_and_b32_e32 v6, 0xc0, v6
	s_ashr_i32 s9, s8, 31
	s_ashr_i32 s7, s6, 31
	v_and_b32_e32 v5, -16, v5
	v_sub_u32_e32 v4, v4, v6
	s_ashr_i32 s38, s3, 8
	s_lshl_b32 s63, s4, 10
	s_lshl_b64 s[10:11], s[8:9], 19
	s_lshl_b64 s[12:13], s[6:7], 19
	v_add_u32_e32 v5, v16, v5
	v_ashrrev_i16_sdwa v4, v205, sext(v4) dst_sel:DWORD dst_unused:UNUSED_PAD src0_sel:DWORD src1_sel:BYTE_0
	s_lshr_b32 s32, s2, 3
	s_lshr_b32 s99, s2, 6
	s_add_i32 s32, s32, s99
	s_and_b32 s32, s32, 3
	s_lshl_b32 s32, s32, 8
	s_add_u32 s12, s28, s12
	v_lshlrev_b32_e32 v7, 5, v15
	v_bfe_i32 v17, v4, 0, 16
	v_lshlrev_b32_e32 v4, 1, v5
	v_lshrrev_b32_e32 v6, 2, v5
	s_addc_u32 s13, s29, s13
	s_add_u32 s12, s12, s32
	s_addc_u32 s13, s13, 0
	s_add_i32 s64, s63, 0
	v_and_b32_e32 v7, 32, v7
	v_and_b32_e32 v6, 4, v6
	v_and_b32_e32 v8, 3, v16
	v_and_b32_e32 v4, 0x1fffd8, v4
	s_add_i32 m0, s64, 0x10000
	v_or3_b32 v4, v8, v6, v4
	v_add_lshl_u32 v6, v7, v17, 1
	global_load_lds_dwordx4 v136, s[12:13]
	s_add_i32 m0, s64, 0x12000
	v_lshl_add_u32 v140, v4, 11, v6
	s_add_u32 s30, s12, 0x10000
	global_load_lds_dwordx4 v140, s[12:13]
	s_addc_u32 s31, s13, 0
	s_add_i32 m0, s64, 0x14000
	v_lshl_add_u32 v138, v5, 11, v6
	global_load_lds_dwordx4 v136, s[30:31]
	s_add_i32 m0, s64, 0x16000
	s_add_u32 s10, s24, s10
	s_addc_u32 s11, s25, s11
	s_add_u32 s10, s10, s32
	s_addc_u32 s11, s11, 0
	s_add_i32 s65, s64, 0x2000
	global_load_lds_dwordx4 v140, s[30:31]
	s_mov_b32 m0, s64
	s_add_u32 s30, s10, 0x40000
	global_load_lds_dwordx4 v134, s[10:11]
	s_mov_b32 m0, s65
	s_addc_u32 s31, s11, 0
	s_add_i32 s86, s64, 0x4000
	global_load_lds_dwordx4 v138, s[10:11]
	s_mov_b32 m0, s86
	s_add_i32 s87, s64, 0x6000
	global_load_lds_dwordx4 v134, s[30:31]
	s_mov_b32 m0, s87
	v_mov_b32_e32 v137, v2
	global_load_lds_dwordx4 v138, s[30:31]
	v_mov_b32_e32 v141, v2
	v_mov_b32_e32 v135, v2
	v_mov_b32_e32 v139, v2
	s_cmp_eq_u32 s38, 1
	v_lshl_add_u64 v[10:11], s[12:13], 0, v[136:137]
	v_lshl_add_u64 v[8:9], s[12:13], 0, v[140:141]
	v_lshl_add_u64 v[4:5], s[10:11], 0, v[134:135]
	s_cselect_b64 s[30:31], -1, 0
	s_cmp_lg_u32 s38, 1
	v_lshl_add_u64 v[6:7], s[10:11], 0, v[138:139]
	s_cbranch_scc1 .LBB0_610
	s_barrier
.LBB0_610:
	v_lshlrev_b32_e32 v18, 1, v143
	v_lshlrev_b32_e32 v19, 2, v170
	s_and_b32 s7, s4, 3
	v_lshl_or_b32 v18, v170, 6, v18
	s_lshl_b32 s4, s38, 13
	v_and_b32_e32 v20, 32, v19
	s_add_i32 m0, s64, 0x18000
	v_lshl_add_u64 v[10:11], v[10:11], 0, s[52:53]
	s_lshl_b32 s92, s38, 6
	v_bitop3_b32 v21, v18, s4, v20 bitop3:0xde
	s_lshl_b32 s4, s7, 12
	s_waitcnt vmcnt(2)
	s_barrier
	global_load_lds_dwordx4 v[10:11], off
	v_lshl_add_u64 v[8:9], v[8:9], 0, s[52:53]
	s_add_i32 m0, s64, 0x1a000
	s_add_i32 s93, s64, 0x8000
	s_add_i32 s95, s64, 0xa000
	v_bitop3_b32 v174, s4, v18, v20 bitop3:0xf6
	global_load_lds_dwordx4 v[8:9], off
	v_lshl_add_u64 v[4:5], v[4:5], 0, s[52:53]
	s_mov_b32 m0, s93
	s_add_u32 s4, s12, 0x10080
	global_load_lds_dwordx4 v[4:5], off
	v_lshl_add_u64 v[4:5], v[6:7], 0, s[52:53]
	s_mov_b32 m0, s95
	s_addc_u32 s5, s13, 0
	global_load_lds_dwordx4 v[4:5], off
	s_add_i32 m0, s64, 0x1c000
	v_lshl_add_u64 v[4:5], s[4:5], 0, v[136:137]
	global_load_lds_dwordx4 v[4:5], off
	v_lshl_add_u64 v[4:5], s[4:5], 0, v[140:141]
	s_add_i32 m0, s64, 0x1e000
	s_cmpk_lt_u32 s3, 0x100
	global_load_lds_dwordx4 v[4:5], off
	v_and_b32_e32 v4, 7, v3
	v_subrev_co_u32_e64 v142, s[4:5], 5, v4
	v_lshlrev_b32_e32 v4, 14, v12
	v_and_b32_e32 v4, 0xffff8000, v4
	v_lshl_add_u32 v4, v13, 11, v4
	v_and_b32_e32 v5, 1, v12
	v_lshl_or_b32 v4, v5, 6, v4
	s_cselect_b64 s[36:37], -1, 0
	s_lshl_b32 s3, s38, 8
	v_lshl_add_u32 v144, v14, 1, v4
	v_lshlrev_b32_e32 v4, 14, v15
	s_add_i32 s3, s3, 0
	v_and_b32_e32 v4, 0xffff8000, v4
	s_waitcnt vmcnt(6)
	s_lshl_b32 s27, s55, 3
	s_add_i32 s3, s3, 0x20000
	v_lshl_add_u32 v4, v16, 11, v4
	v_and_b32_e32 v5, 1, v15
	s_cmp_eq_u64 s[16:17], 0
	v_lshl_or_b32 v4, v5, 6, v4
	v_add_u32_e32 v175, s3, v19
	s_cselect_b64 s[38:39], -1, 0
	v_lshl_or_b32 v176, s7, 6, v143
	v_mov_b32_e32 v145, v2
	v_lshl_add_u32 v146, v17, 1, v4
	v_mov_b32_e32 v147, v2
	s_mov_b32 s76, 0
	v_add_u32_e32 v177, 0, v21
	s_barrier
	s_sub_u32 s12, s12, s32
	s_subb_u32 s13, s13, 0
	s_sub_u32 s10, s10, s32
	s_subb_u32 s11, s11, 0
	s_branch .LBB0_613

;     DI bool next(int i, Unit& u) const { const int L = i * 32 + rank; if (L >= ppg * nN) return false; u.pm = ppg * grp + (L % ppg); const int p0 = L / ppg, p1 = p0 + rot; u.pn = rev ? nN - 1 - p0 : (p1 >= nN ? p1 - nN : p1); return true; }
; #define PG8_STAGE(bufoff, gbase, voff) do { _Pragma("unroll") for (int _i = 0; _i < 2; ++_i) \
;         __builtin_amdgcn_global_load_lds((const unsigned*)((const char*)(gbase) + (voff)[_i]), (PG8_LAS unsigned*)(lds + (bufoff) + ldsw + _i * 8192), 16, 0, 0); } while (0)
; #define PG8_LDA(dst, b, h) do { _Pragma("unroll") for (int m = 0; m < 4; ++m) _Pragma("unroll") for (int k = 0; k < 2; ++k) dst[m][k] = *(const PG8_LAS bf16x8*)(lds + PG8_SA(b, h) + aoff + m * 2048 + k * 1024); } while (0)
; #define PG8_LDB(dst, b, h) do { _Pragma("unroll") for (int n = 0; n < 2; ++n) _Pragma("unroll") for (int k = 0; k < 2; ++k) dst[n][k] = *(const PG8_LAS bf16x8*)(lds + PG8_SB(b, h) + boff + n * 2048 + k * 1024); } while (0)
; #define PG8_WAIT_V(n) asm volatile("s_waitcnt vmcnt(" #n ")" ::: "memory")
; #define PG8_WAIT_L(n) asm volatile("s_waitcnt lgkmcnt(" #n ")" ::: "memory")
; template <class Epi, class Sched, bool ALIGN_EPI = false, bool SP2 = false>
; __device__ __forceinline__ void gemm_phase(PG8_LAS unsigned char* lds, const Gemm g, const Sched& S, const Epi& E, const int tid) {
;     ...
;         const bool has_next = S.next(ui + 1, nxt);
;         const char* nA = has_next ? (const char*)g.A + (size_t)nxt.pm * tstep : cA; const char* nB = has_next ? (const char*)g.Bt + (size_t)nxt.pn * tstep : cB;
;         for (int t = 0; t < nt; t += 2) {
;             const bool last = (t == nt - 2);
;             const char* a1 = cA + (size_t)(t + 1) * kstep;
;             const char* a2 = last ? nA : cA + (size_t)(t + 2) * kstep; const char* b2 = last ? nB : cB + (size_t)(t + 2) * kstep;
;             const char* a3 = a2 + kstep; const char* b3 = b2 + kstep;
;             if (last && has_next) S.a_ready(nxt);
;             if constexpr (SP2) {
;             PG8_LDB(B0, 0, 0); PG8_LDB(B1, 0, 1); PG8_SCHED; PG8_LDA(At, 0, 0); PG8_STAGE(PG8_SA(1, 1), a1 + hstep, voffA);
;             PG8_WAIT_V(8); PG8_WAIT_L(0); PG8_BAR; PG8_MMA(0, 0, At, B0); PG8_MMA(0, 1, At, B1); PG8_BAR; PG8_SCHED;
;             PG8_LDA(At, 0, 1); PG8_STAGE(PG8_SB(0, 0), b2, voffB); PG8_STAGE(PG8_SB(0, 1), b2 + hstepB, voffB); PG8_STAGE(PG8_SA(0, 0), a2, voffA);
.LBB0_615:
	s_ashr_i32 s79, s78, 31
	s_lshl_b64 s[40:41], s[78:79], 19
	s_add_u32 s80, s24, s40
	s_addc_u32 s81, s25, s41
	s_and_b64 s[40:41], s[82:83], exec
	s_cselect_b32 s3, s81, s11
	s_cselect_b32 s7, s80, s10
	s_add_u32 s7, s7, s32
	s_addc_u32 s3, s3, 0
	s_ashr_i32 s97, s96, 31
	s_lshl_b64 s[40:41], s[96:97], 19
	s_add_u32 s84, s28, s40
	s_addc_u32 s85, s29, s41
	s_and_b64 s[40:41], s[82:83], exec
	s_cselect_b32 s9, s85, s13
	s_cselect_b32 s42, s84, s12
	s_add_u32 s42, s42, s32
	s_addc_u32 s9, s9, 0
	s_add_u32 s10, s10, 0x40080
	s_addc_u32 s11, s11, 0
	s_mov_b32 s43, s12
	v_mov_b32_e32 v4, 0
	s_mov_b32 s66, s13
	s_mov_b32 s67, -2
	v_mov_b32_e32 v5, v4
	v_mov_b32_e32 v6, v4
	v_mov_b32_e32 v7, v4
	v_mov_b32_e32 v8, v4
	v_mov_b32_e32 v9, v4
	v_mov_b32_e32 v10, v4
	v_mov_b32_e32 v11, v4
	v_mov_b32_e32 v20, v4
	v_mov_b32_e32 v21, v4
	v_mov_b32_e32 v22, v4
	v_mov_b32_e32 v23, v4
	v_mov_b32_e32 v24, v4
	v_mov_b32_e32 v25, v4
	v_mov_b32_e32 v26, v4
	v_mov_b32_e32 v27, v4
	v_mov_b32_e32 v36, v4
	v_mov_b32_e32 v37, v4
	v_mov_b32_e32 v38, v4
	v_mov_b32_e32 v39, v4
	v_mov_b32_e32 v40, v4
	v_mov_b32_e32 v41, v4
	v_mov_b32_e32 v42, v4
	v_mov_b32_e32 v43, v4
	v_mov_b32_e32 v52, v4
	v_mov_b32_e32 v53, v4
	v_mov_b32_e32 v54, v4
	v_mov_b32_e32 v55, v4
	v_mov_b32_e32 v56, v4
	v_mov_b32_e32 v57, v4
	v_mov_b32_e32 v58, v4
	v_mov_b32_e32 v59, v4
	v_mov_b32_e32 v12, v4
	v_mov_b32_e32 v13, v4
	v_mov_b32_e32 v14, v4
	v_mov_b32_e32 v15, v4
	v_mov_b32_e32 v16, v4
	v_mov_b32_e32 v17, v4
	v_mov_b32_e32 v18, v4
	v_mov_b32_e32 v19, v4
	v_mov_b32_e32 v28, v4
	v_mov_b32_e32 v29, v4
	v_mov_b32_e32 v30, v4
	v_mov_b32_e32 v31, v4
	v_mov_b32_e32 v32, v4
	v_mov_b32_e32 v33, v4
	v_mov_b32_e32 v34, v4
	v_mov_b32_e32 v35, v4
	v_mov_b32_e32 v44, v4
	v_mov_b32_e32 v45, v4
	v_mov_b32_e32 v46, v4
	v_mov_b32_e32 v47, v4
	v_mov_b32_e32 v48, v4
	v_mov_b32_e32 v49, v4
	v_mov_b32_e32 v50, v4
	v_mov_b32_e32 v51, v4
	v_mov_b32_e32 v60, v4
	v_mov_b32_e32 v61, v4
	v_mov_b32_e32 v62, v4
	v_mov_b32_e32 v63, v4
	v_mov_b32_e32 v64, v4
	v_mov_b32_e32 v65, v4
	v_mov_b32_e32 v66, v4
	v_mov_b32_e32 v67, v4
	v_mov_b32_e32 v68, v4
	v_mov_b32_e32 v69, v4
	v_mov_b32_e32 v70, v4
	v_mov_b32_e32 v71, v4
	v_mov_b32_e32 v72, v4
	v_mov_b32_e32 v73, v4
	v_mov_b32_e32 v74, v4
	v_mov_b32_e32 v75, v4
	v_mov_b32_e32 v84, v4
	v_mov_b32_e32 v85, v4
	v_mov_b32_e32 v86, v4
	v_mov_b32_e32 v87, v4
	v_mov_b32_e32 v88, v4
	v_mov_b32_e32 v89, v4
	v_mov_b32_e32 v90, v4
	v_mov_b32_e32 v91, v4
	v_mov_b32_e32 v100, v4
	v_mov_b32_e32 v101, v4
	v_mov_b32_e32 v102, v4
	v_mov_b32_e32 v103, v4
	v_mov_b32_e32 v104, v4
	v_mov_b32_e32 v105, v4
	v_mov_b32_e32 v106, v4
	v_mov_b32_e32 v107, v4
	v_mov_b32_e32 v116, v4
	v_mov_b32_e32 v117, v4
	v_mov_b32_e32 v118, v4
	v_mov_b32_e32 v119, v4
	v_mov_b32_e32 v120, v4
	v_mov_b32_e32 v121, v4
	v_mov_b32_e32 v122, v4
	v_mov_b32_e32 v123, v4
	v_mov_b32_e32 v76, v4
	v_mov_b32_e32 v77, v4
	v_mov_b32_e32 v78, v4
	v_mov_b32_e32 v79, v4
	v_mov_b32_e32 v80, v4
	v_mov_b32_e32 v81, v4
	v_mov_b32_e32 v82, v4
	v_mov_b32_e32 v83, v4
	v_mov_b32_e32 v92, v4
	v_mov_b32_e32 v93, v4
	v_mov_b32_e32 v94, v4
	v_mov_b32_e32 v95, v4
	v_mov_b32_e32 v96, v4
	v_mov_b32_e32 v97, v4
	v_mov_b32_e32 v98, v4
	v_mov_b32_e32 v99, v4
	v_mov_b32_e32 v108, v4
	v_mov_b32_e32 v109, v4
	v_mov_b32_e32 v110, v4
	v_mov_b32_e32 v111, v4
	v_mov_b32_e32 v112, v4
	v_mov_b32_e32 v113, v4
	v_mov_b32_e32 v114, v4
	v_mov_b32_e32 v115, v4
	v_mov_b32_e32 v124, v4
	v_mov_b32_e32 v125, v4
	v_mov_b32_e32 v126, v4
	v_mov_b32_e32 v127, v4
	v_mov_b32_e32 v128, v4
	v_mov_b32_e32 v129, v4
	v_mov_b32_e32 v130, v4
	v_mov_b32_e32 v131, v4
.LBB0_616:
	s_lshl_b32 s100, s67, 7
	s_add_i32 s100, s100, s32
	s_add_i32 s100, s100, 0x100
	s_add_i32 s99, s100, 0x100
	s_and_b32 s100, s100, 0x700
	s_and_b32 s99, s99, 0x700
	s_add_u32 s100, s10, s100
	s_addc_u32 s101, s11, 0
	s_add_u32 s12, s10, 0xfffbff80
	s_addc_u32 s13, s11, -1
	s_add_u32 s12, s12, s99
	s_addc_u32 s13, s13, 0
	s_add_i32 s79, 0, 0x10000
	s_cmp_eq_u32 s67, 12
	s_cselect_b32 s41, s3, s13
	s_cselect_b32 s40, s7, s12
	s_add_u32 s12, s43, s99
	s_addc_u32 s13, s66, 0
	s_cmp_eq_u32 s67, 12
	s_cselect_b32 s13, s9, s13
	s_cselect_b32 s12, s42, s12
	s_add_i32 s88, 0, 0x14000
	v_add_u32_e32 v160, s79, v174
	v_add_u32_e32 v186, s88, v174
	ds_read_b128 v[148:151], v160
	ds_read_b128 v[152:155], v160 offset:1024
	ds_read_b128 v[156:159], v160 offset:2048
	ds_read_b128 v[160:163], v160 offset:3072
	ds_read_b128 v[164:167], v186
	ds_read_b128 v[178:181], v186 offset:1024
	ds_read_b128 v[182:185], v186 offset:2048
	ds_read_b128 v[186:189], v186 offset:3072
	v_lshl_add_u64 v[232:233], s[100:101], 0, v[144:145]
	s_add_i32 m0, s64, 0xc000
	ds_read_b128 v[190:193], v177
	ds_read_b128 v[194:197], v177 offset:1024
	ds_read_b128 v[198:201], v177 offset:2048
	ds_read_b128 v[212:215], v177 offset:3072
	ds_read_b128 v[216:219], v177 offset:4096
	ds_read_b128 v[220:223], v177 offset:5120
	ds_read_b128 v[224:227], v177 offset:6144
	ds_read_b128 v[228:231], v177 offset:7168
	global_load_lds_dwordx4 v[232:233], off
	v_lshl_add_u64 v[232:233], s[100:101], 0, v[146:147]
	s_add_i32 m0, s64, 0xe000
	s_nop 0
	global_load_lds_dwordx4 v[232:233], off
	s_waitcnt vmcnt(8)
	s_waitcnt lgkmcnt(0)
	s_barrier
; #define PG8_STAGE(bufoff, gbase, voff) do { _Pragma("unroll") for (int _i = 0; _i < 2; ++_i) \
;         __builtin_amdgcn_global_load_lds((const unsigned*)((const char*)(gbase) + (voff)[_i]), (PG8_LAS unsigned*)(lds + (bufoff) + ldsw + _i * 8192), 16, 0, 0); } while (0)
; #define PG8_LDA(dst, b, h) do { _Pragma("unroll") for (int m = 0; m < 4; ++m) _Pragma("unroll") for (int k = 0; k < 2; ++k) dst[m][k] = *(const PG8_LAS bf16x8*)(lds + PG8_SA(b, h) + aoff + m * 2048 + k * 1024); } while (0)
; #define PG8_LDB(dst, b, h) do { _Pragma("unroll") for (int n = 0; n < 2; ++n) _Pragma("unroll") for (int k = 0; k < 2; ++k) dst[n][k] = *(const PG8_LAS bf16x8*)(lds + PG8_SB(b, h) + boff + n * 2048 + k * 1024); } while (0)
; #define PG8_MMA(ai, bj, At, Bt) do { __builtin_amdgcn_s_setprio(1); _Pragma("unroll") for (int m = 0; m < 4; ++m) _Pragma("unroll") for (int n = 0; n < 2; ++n) _Pragma("unroll") for (int k = 0; k < 2; ++k) \
;         acc[ai][bj][m][n] = __builtin_amdgcn_mfma_f32_16x16x32_bf16(Bt[n][k], At[m][k], acc[ai][bj][m][n], 0, 0, 0); __builtin_amdgcn_s_setprio(0); } while (0)
; #define PG8_WAIT_V(n) asm volatile("s_waitcnt vmcnt(" #n ")" ::: "memory")
; #define PG8_WAIT_L(n) asm volatile("s_waitcnt lgkmcnt(" #n ")" ::: "memory")
; #define PG8_BAR __builtin_amdgcn_s_barrier()
; #define PG8_SCHED __builtin_amdgcn_sched_barrier(0)
; template <class Epi, class Sched, bool ALIGN_EPI = false, bool SP2 = false>
; __device__ __forceinline__ void gemm_phase(PG8_LAS unsigned char* lds, const Gemm g, const Sched& S, const Epi& E, const int tid) {
;     ...
;             PG8_LDB(B0, 0, 0); PG8_LDB(B1, 0, 1); PG8_SCHED; PG8_LDA(At, 0, 0); PG8_STAGE(PG8_SA(1, 1), a1 + hstep, voffA);
;             PG8_WAIT_V(8); PG8_WAIT_L(0); PG8_BAR; PG8_MMA(0, 0, At, B0); PG8_MMA(0, 1, At, B1); PG8_BAR; PG8_SCHED;
;             PG8_LDA(At, 0, 1); PG8_STAGE(PG8_SB(0, 0), b2, voffB); PG8_STAGE(PG8_SB(0, 1), b2 + hstepB, voffB); PG8_STAGE(PG8_SA(0, 0), a2, voffA);
;             PG8_WAIT_V(8); PG8_WAIT_L(0); PG8_BAR; PG8_MMA(1, 0, At, B0); PG8_MMA(1, 1, At, B1); PG8_BAR; PG8_SCHED;
	s_setprio 1
	s_waitcnt lgkmcnt(0)
	v_mfma_f32_16x16x32_bf16 v[128:131], v[148:151], v[190:193], v[128:131]
	v_mfma_f32_16x16x32_bf16 v[124:127], v[156:159], v[190:193], v[124:127]
	v_mfma_f32_16x16x32_bf16 v[112:115], v[148:151], v[198:201], v[112:115]
	v_mfma_f32_16x16x32_bf16 v[108:111], v[156:159], v[198:201], v[108:111]
	v_mfma_f32_16x16x32_bf16 v[96:99], v[148:151], v[216:219], v[96:99]
	v_mfma_f32_16x16x32_bf16 v[92:95], v[156:159], v[216:219], v[92:95]
	v_mfma_f32_16x16x32_bf16 v[80:83], v[148:151], v[224:227], v[80:83]
	v_mfma_f32_16x16x32_bf16 v[76:79], v[156:159], v[224:227], v[76:79]
	v_mfma_f32_16x16x32_bf16 v[128:131], v[152:155], v[194:197], v[128:131]
	v_mfma_f32_16x16x32_bf16 v[124:127], v[160:163], v[194:197], v[124:127]
	v_mfma_f32_16x16x32_bf16 v[112:115], v[152:155], v[212:215], v[112:115]
	v_mfma_f32_16x16x32_bf16 v[108:111], v[160:163], v[212:215], v[108:111]
	v_mfma_f32_16x16x32_bf16 v[96:99], v[152:155], v[220:223], v[96:99]
	v_mfma_f32_16x16x32_bf16 v[92:95], v[160:163], v[220:223], v[92:95]
	v_mfma_f32_16x16x32_bf16 v[80:83], v[152:155], v[228:231], v[80:83]
	v_mfma_f32_16x16x32_bf16 v[76:79], v[160:163], v[228:231], v[76:79]
	s_setprio 0
	s_setprio 1
	v_mfma_f32_16x16x32_bf16 v[120:123], v[164:167], v[190:193], v[120:123]
	v_mfma_f32_16x16x32_bf16 v[116:119], v[182:185], v[190:193], v[116:119]
	v_mfma_f32_16x16x32_bf16 v[104:107], v[164:167], v[198:201], v[104:107]
	v_mfma_f32_16x16x32_bf16 v[100:103], v[182:185], v[198:201], v[100:103]
	v_mfma_f32_16x16x32_bf16 v[88:91], v[164:167], v[216:219], v[88:91]
	v_mfma_f32_16x16x32_bf16 v[84:87], v[182:185], v[216:219], v[84:87]
	v_mfma_f32_16x16x32_bf16 v[72:75], v[164:167], v[224:227], v[72:75]
	v_mfma_f32_16x16x32_bf16 v[68:71], v[182:185], v[224:227], v[68:71]
	v_mfma_f32_16x16x32_bf16 v[120:123], v[178:181], v[194:197], v[120:123]
	v_mfma_f32_16x16x32_bf16 v[116:119], v[186:189], v[194:197], v[116:119]
	v_mfma_f32_16x16x32_bf16 v[104:107], v[178:181], v[212:215], v[104:107]
	v_mfma_f32_16x16x32_bf16 v[100:103], v[186:189], v[212:215], v[100:103]
	v_mfma_f32_16x16x32_bf16 v[88:91], v[178:181], v[220:223], v[88:91]
	v_mfma_f32_16x16x32_bf16 v[84:87], v[186:189], v[220:223], v[84:87]
	v_mfma_f32_16x16x32_bf16 v[72:75], v[178:181], v[228:231], v[72:75]
	v_mfma_f32_16x16x32_bf16 v[68:71], v[186:189], v[228:231], v[68:71]
	s_setprio 0
	s_barrier
	s_add_i32 s79, s79, s63
	v_lshl_add_u64 v[232:233], s[12:13], 0, v[136:137]
	s_mov_b32 m0, s79
	ds_read_b128 v[190:193], v177 offset:16384
	ds_read_b128 v[194:197], v177 offset:17408
	ds_read_b128 v[198:201], v177 offset:18432
	ds_read_b128 v[212:215], v177 offset:19456
	ds_read_b128 v[216:219], v177 offset:20480
	ds_read_b128 v[220:223], v177 offset:21504
	ds_read_b128 v[224:227], v177 offset:22528
	ds_read_b128 v[228:231], v177 offset:23552
	global_load_lds_dwordx4 v[232:233], off
	s_add_i32 m0, s79, 0x2000
	s_add_u32 vcc_lo, s12, 0x10000
	v_lshl_add_u64 v[234:235], s[12:13], 0, v[140:141]
	s_addc_u32 vcc_hi, s13, 0
	s_add_i32 s79, s88, s63
	global_load_lds_dwordx4 v[234:235], off
	v_lshl_add_u64 v[236:237], vcc, 0, v[136:137]
	s_mov_b32 m0, s79
	v_lshl_add_u64 v[238:239], s[40:41], 0, v[138:139]
	global_load_lds_dwordx4 v[236:237], off
	v_lshl_add_u64 v[236:237], vcc, 0, v[140:141]
	s_add_i32 m0, s79, 0x2000
	s_nop 0
	global_load_lds_dwordx4 v[236:237], off
	v_lshl_add_u64 v[236:237], s[40:41], 0, v[134:135]
	s_mov_b32 m0, s64
	s_nop 0
	global_load_lds_dwordx4 v[236:237], off
	s_mov_b32 m0, s65
	s_nop 0
	global_load_lds_dwordx4 v[238:239], off
	s_waitcnt vmcnt(8)
	s_waitcnt lgkmcnt(0)
	s_barrier
	s_setprio 1
	s_waitcnt lgkmcnt(0)
	v_mfma_f32_16x16x32_bf16 v[64:67], v[148:151], v[190:193], v[64:67]
	v_mfma_f32_16x16x32_bf16 v[60:63], v[156:159], v[190:193], v[60:63]
	v_mfma_f32_16x16x32_bf16 v[48:51], v[148:151], v[198:201], v[48:51]
	v_mfma_f32_16x16x32_bf16 v[44:47], v[156:159], v[198:201], v[44:47]
	v_mfma_f32_16x16x32_bf16 v[32:35], v[148:151], v[216:219], v[32:35]
	v_mfma_f32_16x16x32_bf16 v[28:31], v[156:159], v[216:219], v[28:31]
	v_mfma_f32_16x16x32_bf16 v[16:19], v[148:151], v[224:227], v[16:19]
	v_mfma_f32_16x16x32_bf16 v[12:15], v[156:159], v[224:227], v[12:15]
	v_mfma_f32_16x16x32_bf16 v[64:67], v[152:155], v[194:197], v[64:67]
	v_mfma_f32_16x16x32_bf16 v[60:63], v[160:163], v[194:197], v[60:63]
	v_mfma_f32_16x16x32_bf16 v[48:51], v[152:155], v[212:215], v[48:51]
	v_mfma_f32_16x16x32_bf16 v[44:47], v[160:163], v[212:215], v[44:47]
	v_mfma_f32_16x16x32_bf16 v[32:35], v[152:155], v[220:223], v[32:35]
	v_mfma_f32_16x16x32_bf16 v[28:31], v[160:163], v[220:223], v[28:31]
	v_mfma_f32_16x16x32_bf16 v[16:19], v[152:155], v[228:231], v[16:19]
	v_mfma_f32_16x16x32_bf16 v[12:15], v[160:163], v[228:231], v[12:15]
	s_setprio 0
	s_setprio 1
	v_mfma_f32_16x16x32_bf16 v[56:59], v[164:167], v[190:193], v[56:59]
	v_mfma_f32_16x16x32_bf16 v[52:55], v[182:185], v[190:193], v[52:55]
	v_mfma_f32_16x16x32_bf16 v[40:43], v[164:167], v[198:201], v[40:43]
	v_mfma_f32_16x16x32_bf16 v[36:39], v[182:185], v[198:201], v[36:39]
	v_mfma_f32_16x16x32_bf16 v[24:27], v[164:167], v[216:219], v[24:27]
	v_mfma_f32_16x16x32_bf16 v[20:23], v[182:185], v[216:219], v[20:23]
	v_mfma_f32_16x16x32_bf16 v[8:11], v[164:167], v[224:227], v[8:11]
	v_mfma_f32_16x16x32_bf16 v[4:7], v[182:185], v[224:227], v[4:7]
	v_mfma_f32_16x16x32_bf16 v[56:59], v[178:181], v[194:197], v[56:59]
	v_mfma_f32_16x16x32_bf16 v[52:55], v[186:189], v[194:197], v[52:55]
	v_mfma_f32_16x16x32_bf16 v[40:43], v[178:181], v[212:215], v[40:43]
	v_mfma_f32_16x16x32_bf16 v[36:39], v[186:189], v[212:215], v[36:39]
	v_mfma_f32_16x16x32_bf16 v[24:27], v[178:181], v[220:223], v[24:27]
	v_mfma_f32_16x16x32_bf16 v[20:23], v[186:189], v[220:223], v[20:23]
	v_mfma_f32_16x16x32_bf16 v[8:11], v[178:181], v[228:231], v[8:11]
	v_mfma_f32_16x16x32_bf16 v[4:7], v[186:189], v[228:231], v[4:7]
	s_setprio 0
	s_barrier
; #define PG8_STAGE(bufoff, gbase, voff) do { _Pragma("unroll") for (int _i = 0; _i < 2; ++_i) \
;         __builtin_amdgcn_global_load_lds((const unsigned*)((const char*)(gbase) + (voff)[_i]), (PG8_LAS unsigned*)(lds + (bufoff) + ldsw + _i * 8192), 16, 0, 0); } while (0)
; #define PG8_LDA(dst, b, h) do { _Pragma("unroll") for (int m = 0; m < 4; ++m) _Pragma("unroll") for (int k = 0; k < 2; ++k) dst[m][k] = *(const PG8_LAS bf16x8*)(lds + PG8_SA(b, h) + aoff + m * 2048 + k * 1024); } while (0)
; #define PG8_LDB(dst, b, h) do { _Pragma("unroll") for (int n = 0; n < 2; ++n) _Pragma("unroll") for (int k = 0; k < 2; ++k) dst[n][k] = *(const PG8_LAS bf16x8*)(lds + PG8_SB(b, h) + boff + n * 2048 + k * 1024); } while (0)
; #define PG8_MMA(ai, bj, At, Bt) do { __builtin_amdgcn_s_setprio(1); _Pragma("unroll") for (int m = 0; m < 4; ++m) _Pragma("unroll") for (int n = 0; n < 2; ++n) _Pragma("unroll") for (int k = 0; k < 2; ++k) \
;         acc[ai][bj][m][n] = __builtin_amdgcn_mfma_f32_16x16x32_bf16(Bt[n][k], At[m][k], acc[ai][bj][m][n], 0, 0, 0); __builtin_amdgcn_s_setprio(0); } while (0)
; #define PG8_WAIT_V(n) asm volatile("s_waitcnt vmcnt(" #n ")" ::: "memory")
; #define PG8_WAIT_L(n) asm volatile("s_waitcnt lgkmcnt(" #n ")" ::: "memory")
; #define PG8_BAR __builtin_amdgcn_s_barrier()
; #define PG8_SCHED __builtin_amdgcn_sched_barrier(0)
; template <class Epi, class Sched, bool ALIGN_EPI = false, bool SP2 = false>
; __device__ __forceinline__ void gemm_phase(PG8_LAS unsigned char* lds, const Gemm g, const Sched& S, const Epi& E, const int tid) {
;     ...
;             PG8_LDB(B0, 1, 0); PG8_LDB(B1, 1, 1); PG8_SCHED; PG8_LDA(At, 1, 0); PG8_STAGE(PG8_SA(0, 1), a2 + hstep, voffA);
;             PG8_WAIT_V(8); PG8_WAIT_L(0); PG8_BAR; PG8_MMA(0, 0, At, B0); PG8_MMA(0, 1, At, B1); PG8_BAR; PG8_SCHED;
	s_add_i32 s79, 0, 0x18000
	s_add_i32 s88, 0, 0x1c000
	v_add_u32_e32 v160, s79, v174
	v_add_u32_e32 v186, s88, v174
	ds_read_b128 v[148:151], v160
	ds_read_b128 v[152:155], v160 offset:1024
	ds_read_b128 v[156:159], v160 offset:2048
	ds_read_b128 v[160:163], v160 offset:3072
	ds_read_b128 v[164:167], v186
	ds_read_b128 v[178:181], v186 offset:1024
	ds_read_b128 v[182:185], v186 offset:2048
	ds_read_b128 v[186:189], v186 offset:3072
	s_add_u32 s40, s40, 0x40000
	s_addc_u32 s41, s41, 0
	s_mov_b32 m0, s86
	v_lshl_add_u64 v[240:241], s[40:41], 0, v[134:135]
	ds_read_b128 v[190:193], v177 offset:32768
	ds_read_b128 v[194:197], v177 offset:33792
	ds_read_b128 v[198:201], v177 offset:34816
	ds_read_b128 v[212:215], v177 offset:35840
	ds_read_b128 v[216:219], v177 offset:36864
	ds_read_b128 v[220:223], v177 offset:37888
	ds_read_b128 v[224:227], v177 offset:38912
	ds_read_b128 v[228:231], v177 offset:39936
	global_load_lds_dwordx4 v[240:241], off
	v_lshl_add_u64 v[240:241], s[40:41], 0, v[138:139]
	s_mov_b32 m0, s87
	s_nop 0
	global_load_lds_dwordx4 v[240:241], off
	s_waitcnt vmcnt(8)
	s_waitcnt lgkmcnt(0)
	s_barrier
	s_setprio 1
	s_waitcnt lgkmcnt(0)
	v_mfma_f32_16x16x32_bf16 v[128:131], v[148:151], v[190:193], v[128:131]
	v_mfma_f32_16x16x32_bf16 v[124:127], v[156:159], v[190:193], v[124:127]
	v_mfma_f32_16x16x32_bf16 v[112:115], v[148:151], v[198:201], v[112:115]
	v_mfma_f32_16x16x32_bf16 v[108:111], v[156:159], v[198:201], v[108:111]
	v_mfma_f32_16x16x32_bf16 v[96:99], v[148:151], v[216:219], v[96:99]
	v_mfma_f32_16x16x32_bf16 v[92:95], v[156:159], v[216:219], v[92:95]
	v_mfma_f32_16x16x32_bf16 v[80:83], v[148:151], v[224:227], v[80:83]
	v_mfma_f32_16x16x32_bf16 v[76:79], v[156:159], v[224:227], v[76:79]
	v_mfma_f32_16x16x32_bf16 v[128:131], v[152:155], v[194:197], v[128:131]
	v_mfma_f32_16x16x32_bf16 v[124:127], v[160:163], v[194:197], v[124:127]
	v_mfma_f32_16x16x32_bf16 v[112:115], v[152:155], v[212:215], v[112:115]
	v_mfma_f32_16x16x32_bf16 v[108:111], v[160:163], v[212:215], v[108:111]
	v_mfma_f32_16x16x32_bf16 v[96:99], v[152:155], v[220:223], v[96:99]
	v_mfma_f32_16x16x32_bf16 v[92:95], v[160:163], v[220:223], v[92:95]
	v_mfma_f32_16x16x32_bf16 v[80:83], v[152:155], v[228:231], v[80:83]
	v_mfma_f32_16x16x32_bf16 v[76:79], v[160:163], v[228:231], v[76:79]
	s_setprio 0
	s_setprio 1
	v_mfma_f32_16x16x32_bf16 v[120:123], v[164:167], v[190:193], v[120:123]
	v_mfma_f32_16x16x32_bf16 v[116:119], v[182:185], v[190:193], v[116:119]
	v_mfma_f32_16x16x32_bf16 v[104:107], v[164:167], v[198:201], v[104:107]
	v_mfma_f32_16x16x32_bf16 v[100:103], v[182:185], v[198:201], v[100:103]
	v_mfma_f32_16x16x32_bf16 v[88:91], v[164:167], v[216:219], v[88:91]
	v_mfma_f32_16x16x32_bf16 v[84:87], v[182:185], v[216:219], v[84:87]
	v_mfma_f32_16x16x32_bf16 v[72:75], v[164:167], v[224:227], v[72:75]
	v_mfma_f32_16x16x32_bf16 v[68:71], v[182:185], v[224:227], v[68:71]
	v_mfma_f32_16x16x32_bf16 v[120:123], v[178:181], v[194:197], v[120:123]
	v_mfma_f32_16x16x32_bf16 v[116:119], v[186:189], v[194:197], v[116:119]
	v_mfma_f32_16x16x32_bf16 v[104:107], v[178:181], v[212:215], v[104:107]
	v_mfma_f32_16x16x32_bf16 v[100:103], v[186:189], v[212:215], v[100:103]
	v_mfma_f32_16x16x32_bf16 v[88:91], v[178:181], v[220:223], v[88:91]
	v_mfma_f32_16x16x32_bf16 v[84:87], v[186:189], v[220:223], v[84:87]
	v_mfma_f32_16x16x32_bf16 v[72:75], v[178:181], v[228:231], v[72:75]
	v_mfma_f32_16x16x32_bf16 v[68:71], v[186:189], v[228:231], v[68:71]
	s_setprio 0
	s_barrier
; #define PG8_STAGE(bufoff, gbase, voff) do { _Pragma("unroll") for (int _i = 0; _i < 2; ++_i) \
;         __builtin_amdgcn_global_load_lds((const unsigned*)((const char*)(gbase) + (voff)[_i]), (PG8_LAS unsigned*)(lds + (bufoff) + ldsw + _i * 8192), 16, 0, 0); } while (0)
; #define PG8_LDA(dst, b, h) do { _Pragma("unroll") for (int m = 0; m < 4; ++m) _Pragma("unroll") for (int k = 0; k < 2; ++k) dst[m][k] = *(const PG8_LAS bf16x8*)(lds + PG8_SA(b, h) + aoff + m * 2048 + k * 1024); } while (0)
; #define PG8_MMA(ai, bj, At, Bt) do { __builtin_amdgcn_s_setprio(1); _Pragma("unroll") for (int m = 0; m < 4; ++m) _Pragma("unroll") for (int n = 0; n < 2; ++n) _Pragma("unroll") for (int k = 0; k < 2; ++k) \
;         acc[ai][bj][m][n] = __builtin_amdgcn_mfma_f32_16x16x32_bf16(Bt[n][k], At[m][k], acc[ai][bj][m][n], 0, 0, 0); __builtin_amdgcn_s_setprio(0); } while (0)
; #define PG8_WAIT_V(n) asm volatile("s_waitcnt vmcnt(" #n ")" ::: "memory")
; #define PG8_WAIT_L(n) asm volatile("s_waitcnt lgkmcnt(" #n ")" ::: "memory")
; #define PG8_BAR __builtin_amdgcn_s_barrier()
; #define PG8_SCHED __builtin_amdgcn_sched_barrier(0)
; template <class Epi, class Sched, bool ALIGN_EPI = false, bool SP2 = false>
; __device__ __forceinline__ void gemm_phase(PG8_LAS unsigned char* lds, const Gemm g, const Sched& S, const Epi& E, const int tid) {
;     ...
;         for (int t = 0; t < nt; t += 2) {
;     ...
;             PG8_LDA(At, 1, 1); PG8_STAGE(PG8_SB(1, 0), b3, voffB); PG8_STAGE(PG8_SB(1, 1), b3 + hstepB, voffB); PG8_STAGE(PG8_SA(1, 0), a3, voffA);
;             PG8_WAIT_V(8); PG8_WAIT_L(0); PG8_BAR; PG8_MMA(1, 0, At, B0); PG8_MMA(1, 1, At, B1); PG8_BAR; PG8_SCHED;
	s_add_i32 s40, s79, s63
	v_lshl_add_u64 v[232:233], v[232:233], 0, s[52:53]
	s_mov_b32 m0, s40
	ds_read_b128 v[190:193], v177 offset:49152
	ds_read_b128 v[194:197], v177 offset:50176
	ds_read_b128 v[198:201], v177 offset:51200
	ds_read_b128 v[212:215], v177 offset:52224
	ds_read_b128 v[216:219], v177 offset:53248
	ds_read_b128 v[220:223], v177 offset:54272
	ds_read_b128 v[224:227], v177 offset:55296
	ds_read_b128 v[228:231], v177 offset:56320
	global_load_lds_dwordx4 v[232:233], off
	s_add_i32 m0, s40, 0x2000
	s_add_u32 s12, s12, 0x10080
	v_lshl_add_u64 v[232:233], v[234:235], 0, s[52:53]
	s_addc_u32 s13, s13, 0
	s_add_i32 s40, s88, s63
	global_load_lds_dwordx4 v[232:233], off
	v_lshl_add_u64 v[232:233], s[12:13], 0, v[136:137]
	s_mov_b32 m0, s40
	s_nop 0
	global_load_lds_dwordx4 v[232:233], off
	v_lshl_add_u64 v[232:233], s[12:13], 0, v[140:141]
	s_add_i32 m0, s40, 0x2000
	s_nop 0
	global_load_lds_dwordx4 v[232:233], off
	v_lshl_add_u64 v[232:233], v[236:237], 0, s[52:53]
	s_mov_b32 m0, s93
	s_nop 0
	global_load_lds_dwordx4 v[232:233], off
	v_lshl_add_u64 v[232:233], v[238:239], 0, s[52:53]
	s_mov_b32 m0, s95
	s_nop 0
	global_load_lds_dwordx4 v[232:233], off
	s_waitcnt vmcnt(8)
	s_waitcnt lgkmcnt(0)
	s_barrier
	s_setprio 1
	s_waitcnt lgkmcnt(0)
	v_mfma_f32_16x16x32_bf16 v[64:67], v[148:151], v[190:193], v[64:67]
	v_mfma_f32_16x16x32_bf16 v[60:63], v[156:159], v[190:193], v[60:63]
	v_mfma_f32_16x16x32_bf16 v[48:51], v[148:151], v[198:201], v[48:51]
	v_mfma_f32_16x16x32_bf16 v[44:47], v[156:159], v[198:201], v[44:47]
	v_mfma_f32_16x16x32_bf16 v[32:35], v[148:151], v[216:219], v[32:35]
	v_mfma_f32_16x16x32_bf16 v[28:31], v[156:159], v[216:219], v[28:31]
	v_mfma_f32_16x16x32_bf16 v[16:19], v[148:151], v[224:227], v[16:19]
	v_mfma_f32_16x16x32_bf16 v[12:15], v[156:159], v[224:227], v[12:15]
	v_mfma_f32_16x16x32_bf16 v[64:67], v[152:155], v[194:197], v[64:67]
	v_mfma_f32_16x16x32_bf16 v[60:63], v[160:163], v[194:197], v[60:63]
	v_mfma_f32_16x16x32_bf16 v[48:51], v[152:155], v[212:215], v[48:51]
	v_mfma_f32_16x16x32_bf16 v[44:47], v[160:163], v[212:215], v[44:47]
	v_mfma_f32_16x16x32_bf16 v[32:35], v[152:155], v[220:223], v[32:35]
	v_mfma_f32_16x16x32_bf16 v[28:31], v[160:163], v[220:223], v[28:31]
	v_mfma_f32_16x16x32_bf16 v[16:19], v[152:155], v[228:231], v[16:19]
	v_mfma_f32_16x16x32_bf16 v[12:15], v[160:163], v[228:231], v[12:15]
	s_setprio 0
	s_setprio 1
	v_mfma_f32_16x16x32_bf16 v[56:59], v[164:167], v[190:193], v[56:59]
	v_mfma_f32_16x16x32_bf16 v[52:55], v[182:185], v[190:193], v[52:55]
	v_mfma_f32_16x16x32_bf16 v[40:43], v[164:167], v[198:201], v[40:43]
	v_mfma_f32_16x16x32_bf16 v[36:39], v[182:185], v[198:201], v[36:39]
	v_mfma_f32_16x16x32_bf16 v[24:27], v[164:167], v[216:219], v[24:27]
	v_mfma_f32_16x16x32_bf16 v[20:23], v[182:185], v[216:219], v[20:23]
	v_mfma_f32_16x16x32_bf16 v[8:11], v[164:167], v[224:227], v[8:11]
	v_mfma_f32_16x16x32_bf16 v[4:7], v[182:185], v[224:227], v[4:7]
	v_mfma_f32_16x16x32_bf16 v[56:59], v[178:181], v[194:197], v[56:59]
	v_mfma_f32_16x16x32_bf16 v[52:55], v[186:189], v[194:197], v[52:55]
	v_mfma_f32_16x16x32_bf16 v[40:43], v[178:181], v[212:215], v[40:43]
	v_mfma_f32_16x16x32_bf16 v[36:39], v[186:189], v[212:215], v[36:39]
	v_mfma_f32_16x16x32_bf16 v[24:27], v[178:181], v[220:223], v[24:27]
	v_mfma_f32_16x16x32_bf16 v[20:23], v[186:189], v[220:223], v[20:23]
	v_mfma_f32_16x16x32_bf16 v[8:11], v[178:181], v[228:231], v[8:11]
	v_mfma_f32_16x16x32_bf16 v[4:7], v[186:189], v[228:231], v[4:7]
	s_setprio 0
	s_barrier
	s_add_i32 s67, s67, 2
	s_cmp_gt_u32 s67, 13
	s_cbranch_scc0 .LBB0_616
	s_and_b64 vcc, exec, s[36:37]
	s_cbranch_vccz .LBB0_619
	s_barrier

; #define PG8_STAGE(bufoff, gbase, voff) do { _Pragma("unroll") for (int _i = 0; _i < 2; ++_i) \
;         __builtin_amdgcn_global_load_lds((const unsigned*)((const char*)(gbase) + (voff)[_i]), (PG8_LAS unsigned*)(lds + (bufoff) + ldsw + _i * 8192), 16, 0, 0); } while (0)
; #define PG8_WAIT_V(n) asm volatile("s_waitcnt vmcnt(" #n ")" ::: "memory")
; #define PG8_BAR __builtin_amdgcn_s_barrier()
;     DI void init_issue(u32x4 (&w)[R8::HAS_PRE ? 16 : 1], const Unit& u, int wr, int wc, int fr, int fq) const {
;         if constexpr (R8::HAS_PRE) {
;             const int row0 = u.pm * BM + wr * 64 + fr, col0 = u.pn * BM + (PERM ? wc * 64 : wc * 32) + 8 * fq;
; #pragma unroll
;             for (int ai = 0; ai < 2; ++ai)
; #pragma unroll
;                 for (int m = 0; m < 4; ++m)
; #pragma unroll
;                     for (int bj = 0; bj < 2; ++bj) w[(ai * 4 + m) * 2 + bj] = e.pre(row0 + ai * HALF + m * 16, col0 + bj * (PERM ? 32 : HALF));
;         }
; template <class Epi, class Sched, bool ALIGN_EPI = false, bool SP2 = false>
; __device__ __forceinline__ void gemm_phase(PG8_LAS unsigned char* lds, const Gemm g, const Sched& S, const Epi& E, const int tid) {
;     ...
;     if constexpr (Epi::HAS_INIT) E.init_issue(iw_, cur, wr, wc, fr, fq);
;     ...
;     const char* cA = (const char*)g.A + (size_t)cur.pm * tstep; const char* cB = (const char*)g.Bt + (size_t)cur.pn * tstep;
;     S.a_ready(cur);
;     if constexpr (SP2) {
;         PG8_STAGE(PG8_SB(0, 0), cB, voffB); PG8_STAGE(PG8_SB(0, 1), cB + hstepB, voffB); PG8_STAGE(PG8_SA(0, 0), cA, voffA); PG8_STAGE(PG8_SA(0, 1), cA + hstep, voffA);
;         if (wr == 1) PG8_BAR;
;         PG8_WAIT_V(2); PG8_BAR;
;         PG8_STAGE(PG8_SB(1, 0), cB + kstep, voffB); PG8_STAGE(PG8_SA(1, 0), cA + kstep, voffA); PG8_STAGE(PG8_SB(1, 1), cB + hstepB + kstep, voffB);
;         PG8_WAIT_V(6); PG8_BAR;
;     } else {
;         PG8_STAGE(PG8_SB(0, 0), cB, voffB); PG8_STAGE(PG8_SA(0, 0), cA, voffA); PG8_STAGE(PG8_SB(0, 1), cB + hstepB, voffB); PG8_STAGE(PG8_SA(0, 1), cA + hstep, voffA);
;         if (wr == 1) PG8_BAR;
;         PG8_WAIT_V(4); PG8_BAR;
;         PG8_STAGE(PG8_SB(1, 0), cB + kstep, voffB); PG8_STAGE(PG8_SA(1, 0), cA + kstep, voffA); PG8_STAGE(PG8_SB(1, 1), cB + hstepB + kstep, voffB);
;         PG8_WAIT_V(6); PG8_BAR;
.LBB0_970:
	v_ashrrev_i32_e32 v5, 31, v3
	v_lshrrev_b32_e32 v5, 26, v5
	v_add_u32_e32 v5, v3, v5
	s_waitcnt vmcnt(0)
	v_ashrrev_i32_e32 v142, 6, v5
	v_bfe_i32 v5, v3, 27, 1
	v_lshlrev_b32_e32 v4, 4, v3
	v_lshrrev_b32_e32 v5, 22, v5
	v_add_u32_e32 v5, v4, v5
	v_and_b32_e32 v5, 0xfffffc00, v5
	s_ashr_i32 s42, s14, 6
	v_sub_u32_e32 v5, v4, v5
	s_waitcnt lgkmcnt(0)
	s_add_u32 s0, s12, s0
	v_lshrrev_b32_e32 v6, 4, v5
	s_addc_u32 s1, s13, s1
	s_lshl_b32 s6, s94, 21
	v_bitop3_b32 v5, v6, v5, 32 bitop3:0x6c
	s_add_u32 s10, s0, s6
	v_ashrrev_i32_e32 v7, 31, v5
	s_addc_u32 s11, s1, 0
	v_lshrrev_b32_e32 v7, 26, v7
	s_add_u32 s6, s12, 0x14f00000
	v_add_u32_e32 v7, v5, v7
	s_addc_u32 s7, s13, 0
	v_lshlrev_b32_e32 v6, 3, v142
	v_ashrrev_i32_e32 v143, 6, v7
	v_and_b32_e32 v7, 0xc0, v7
	s_add_u32 s8, s12, 0xc300000
	v_and_b32_e32 v6, -16, v6
	v_sub_u32_e32 v5, v5, v7
	s_addc_u32 s9, s13, 0
	v_add_u32_e32 v133, v143, v6
	v_lshlrev_b32_e32 v6, 5, v142
	v_ashrrev_i16_sdwa v5, v205, sext(v5) dst_sel:DWORD dst_unused:UNUSED_PAD src0_sel:DWORD src1_sel:BYTE_0
	s_add_u32 s0, s12, 0x2e200000
	v_and_b32_e32 v6, 32, v6
	v_bfe_i32 v144, v5, 0, 16
	v_lshrrev_b32_e32 v5, 2, v133
	v_readlane_b32 s88, v250, 8
	s_addc_u32 s1, s13, 0
	v_add_u32_e32 v132, v6, v144
	v_lshlrev_b32_e32 v155, 1, v133
	v_and_b32_e32 v153, 4, v5
	v_and_b32_e32 v154, 3, v143
	v_and_b32_e32 v152, 15, v3
	s_andn2_b64 vcc, exec, s[4:5]
	s_lshl_b32 s43, s42, 10
	v_readlane_b32 s89, v250, 9
	s_cbranch_vccnz .LBB0_1018
	v_and_b32_e32 v5, 0x1fffd8, v155
	v_or3_b32 v5, v154, v5, v153
	v_lshlrev_b32_e32 v6, 1, v132
	v_add_u32_e32 v4, 0x2000, v4
	v_lshl_add_u32 v136, v5, 11, v6
	v_ashrrev_i32_e32 v5, 31, v4
	v_lshrrev_b32_e32 v5, 22, v5
	v_add_u32_e32 v5, v4, v5
	v_ashrrev_i32_e32 v145, 10, v5
	v_mul_i32_i24_e32 v5, 0x400, v145
	v_sub_u32_e32 v4, v4, v5
	v_lshrrev_b32_e32 v5, 4, v4
	v_bitop3_b32 v4, v5, v4, 32 bitop3:0x6c
	v_lshl_add_u32 v134, v133, 11, v6
	v_ashrrev_i32_e32 v6, 31, v4
	v_lshrrev_b32_e32 v6, 26, v6
	v_add_u32_e32 v6, v4, v6
	v_lshlrev_b32_e32 v5, 3, v145
	v_ashrrev_i32_e32 v147, 6, v6
	v_and_b32_e32 v6, 0xc0, v6
	v_and_b32_e32 v5, -16, v5
	v_sub_u32_e32 v4, v4, v6
	v_add_u32_e32 v5, v147, v5
	v_ashrrev_i16_sdwa v4, v205, sext(v4) dst_sel:DWORD dst_unused:UNUSED_PAD src0_sel:DWORD src1_sel:BYTE_0
	v_lshlrev_b32_e32 v7, 5, v145
	v_bfe_i32 v148, v4, 0, 16
	v_lshlrev_b32_e32 v4, 1, v5
	v_lshrrev_b32_e32 v6, 2, v5
	s_ashr_i32 s5, s14, 8
	v_and_b32_e32 v7, 32, v7
	v_and_b32_e32 v6, 4, v6
	v_and_b32_e32 v8, 3, v147
	v_and_b32_e32 v4, 0x1fffd8, v4
	s_lshl_b32 s15, s5, 6
	s_lshl_b32 s12, s28, 8
	s_and_b32 s4, s42, 3
	v_or3_b32 v4, v8, v6, v4
	v_add_lshl_u32 v6, v7, v148, 1
	s_add_i32 s12, s12, s15
	v_bfe_u32 v146, v3, 4, 2
	v_lshl_add_u32 v140, v4, 11, v6
	v_or_b32_e32 v4, s12, v152
	s_lshl_b32 s12, s24, 8
	s_lshl_b32 s54, s4, 6
	v_lshlrev_b32_e32 v156, 3, v146
	s_or_b32 s12, s12, s54
	v_or_b32_e32 v10, 16, v4
	v_lshl_add_u32 v138, v5, 11, v6
	v_or_b32_e32 v6, s12, v156
	v_ashrrev_i32_e32 v5, 31, v4
	v_ashrrev_i32_e32 v11, 31, v10
	v_lshlrev_b64 v[8:9], 11, v[4:5]
	v_ashrrev_i32_e32 v7, 31, v6
	v_lshlrev_b64 v[10:11], 11, v[10:11]
	v_lshl_add_u64 v[8:9], s[8:9], 0, v[8:9]
	v_lshlrev_b64 v[6:7], 1, v[6:7]
	v_lshl_add_u64 v[10:11], s[8:9], 0, v[10:11]
	v_lshl_add_u64 v[8:9], v[8:9], 0, v[6:7]
	v_lshl_add_u64 v[10:11], v[10:11], 0, v[6:7]
	global_load_dwordx4 v[64:67], v[8:9], off
	global_load_dwordx4 v[56:59], v[8:9], off offset:64
	global_load_dwordx4 v[60:63], v[10:11], off
	global_load_dwordx4 v[48:51], v[10:11], off offset:64
	v_or_b32_e32 v10, 32, v4
	v_or_b32_e32 v4, 48, v4
	v_ashrrev_i32_e32 v11, 31, v10
	v_ashrrev_i32_e32 v5, 31, v4
	v_lshlrev_b64 v[10:11], 11, v[10:11]
	v_lshlrev_b64 v[4:5], 11, v[4:5]
	v_lshl_add_u64 v[10:11], s[8:9], 0, v[10:11]
	v_lshl_add_u64 v[4:5], s[8:9], 0, v[4:5]
	v_lshl_add_u64 v[10:11], v[10:11], 0, v[6:7]
	v_lshl_add_u64 v[4:5], v[4:5], 0, v[6:7]
	v_add_co_u32_e32 v6, vcc, s57, v8
	global_load_dwordx4 v[52:55], v[10:11], off
	global_load_dwordx4 v[40:43], v[10:11], off offset:64
	v_addc_co_u32_e32 v7, vcc, 0, v9, vcc
	global_load_dwordx4 v[44:47], v[4:5], off
	global_load_dwordx4 v[36:39], v[4:5], off offset:64
	v_lshl_add_u64 v[4:5], v[8:9], 0, s[50:51]
	global_load_dwordx4 v[32:35], v[6:7], off
	global_load_dwordx4 v[28:31], v[4:5], off offset:64
	v_add_co_u32_e32 v6, vcc, s26, v8
	s_mov_b32 s12, 0x50000
	s_nop 0
	v_addc_co_u32_e32 v7, vcc, 0, v9, vcc
	v_lshl_add_u64 v[4:5], v[8:9], 0, s[72:73]
	global_load_dwordx4 v[24:27], v[6:7], off
	global_load_dwordx4 v[20:23], v[4:5], off offset:64
	v_add_co_u32_e32 v6, vcc, s12, v8
	s_mov_b64 s[12:13], 0x58000
	s_nop 0
	v_addc_co_u32_e32 v7, vcc, 0, v9, vcc
	v_lshl_add_u64 v[16:17], v[8:9], 0, s[12:13]
	s_mov_b32 s12, 0x58000
	s_ashr_i32 s29, s28, 31
	s_ashr_i32 s25, s24, 31
	v_lshl_add_u64 v[4:5], v[8:9], 0, s[74:75]
	v_add_co_u32_e32 v8, vcc, s12, v8
	s_lshl_b64 s[12:13], s[28:29], 19
	s_lshl_b64 s[16:17], s[24:25], 19
	s_lshr_b32 s32, s2, 3
	s_lshr_b32 s99, s2, 6
	s_add_i32 s32, s32, s99
	s_and_b32 s32, s32, 3
	s_lshl_b32 s32, s32, 8
	s_add_u32 s36, s10, s16
	s_addc_u32 s37, s11, s17
	s_add_u32 s36, s36, s32
	s_addc_u32 s37, s37, 0
	s_add_i32 s29, s43, 0
	v_addc_co_u32_e32 v9, vcc, 0, v9, vcc
	s_add_i32 m0, s29, 0x10000
	global_load_dwordx4 v[12:15], v[6:7], off
	s_nop 0
	global_load_dwordx4 v[4:7], v[4:5], off offset:64
	s_nop 0
	global_load_dwordx4 v[8:11], v[8:9], off
	s_nop 0
	global_load_dwordx4 v[16:19], v[16:17], off offset:64
	v_mov_b32_e32 v137, v2
	global_load_lds_dwordx4 v136, s[36:37]
	s_add_i32 m0, s29, 0x12000
	s_add_u32 s16, s36, 0x10000
	global_load_lds_dwordx4 v140, s[36:37]
	s_addc_u32 s17, s37, 0
	s_add_i32 m0, s29, 0x14000
	v_mov_b32_e32 v141, v2
	global_load_lds_dwordx4 v136, s[16:17]
	s_add_i32 m0, s29, 0x16000
	s_add_u32 s38, s6, s12
	s_addc_u32 s39, s7, s13
	s_add_u32 s38, s38, s32
	s_addc_u32 s39, s39, 0
	s_add_i32 s55, s29, 0x2000
	global_load_lds_dwordx4 v140, s[16:17]
	s_mov_b32 m0, s29
	s_add_u32 s12, s38, 0x40000
	global_load_lds_dwordx4 v134, s[38:39]
	s_mov_b32 m0, s55
	s_addc_u32 s13, s39, 0
	s_add_i32 s62, s29, 0x4000
	global_load_lds_dwordx4 v138, s[38:39]
	s_mov_b32 m0, s62
	s_add_i32 s63, s29, 0x6000
	global_load_lds_dwordx4 v134, s[12:13]
	s_mov_b32 m0, s63
	v_mov_b32_e32 v135, v2
	global_load_lds_dwordx4 v138, s[12:13]
	v_mov_b32_e32 v139, v2
	s_cmp_eq_u32 s5, 1
	v_lshl_add_u64 v[74:75], s[36:37], 0, v[136:137]
	v_lshl_add_u64 v[72:73], s[36:37], 0, v[140:141]
	v_lshl_add_u64 v[68:69], s[38:39], 0, v[134:135]
	s_cselect_b64 s[12:13], -1, 0
	s_cmp_lg_u32 s5, 1
	v_lshl_add_u64 v[70:71], s[38:39], 0, v[138:139]
	s_cbranch_scc1 .LBB0_973
	s_barrier
; DI float bf_lo(unsigned u) { return __uint_as_float(u << 16); }
; DI float bf_hi(unsigned u) { return __uint_as_float(u & 0xffff0000u); }
; #define PG8_STAGE(bufoff, gbase, voff) do { _Pragma("unroll") for (int _i = 0; _i < 2; ++_i) \
;         __builtin_amdgcn_global_load_lds((const unsigned*)((const char*)(gbase) + (voff)[_i]), (PG8_LAS unsigned*)(lds + (bufoff) + ldsw + _i * 8192), 16, 0, 0); } while (0)
; #define PG8_WAIT_V(n) asm volatile("s_waitcnt vmcnt(" #n ")" ::: "memory")
; #define PG8_BAR __builtin_amdgcn_s_barrier()
;     DI void init_finish(f32x4 (&acc)[2][2][4][2], const u32x4 (&w)[R8::HAS_PRE ? 16 : 1]) const {
;         if constexpr (R8::HAS_PRE) {
; #pragma unroll
;             for (int ai = 0; ai < 2; ++ai)
; #pragma unroll
;                 for (int m = 0; m < 4; ++m)
; #pragma unroll
;                     for (int bj = 0; bj < 2; ++bj) { const u32x4 v = w[(ai * 4 + m) * 2 + bj];
;                         acc[ai][bj][m][0] = (f32x4){bf_lo(v.x), bf_hi(v.x), bf_lo(v.y), bf_hi(v.y)}; acc[ai][bj][m][1] = (f32x4){bf_lo(v.z), bf_hi(v.z), bf_lo(v.w), bf_hi(v.w)}; }
;         }
; template <class Epi, class Sched, bool ALIGN_EPI = false, bool SP2 = false>
; __device__ __forceinline__ void gemm_phase(PG8_LAS unsigned char* lds, const Gemm g, const Sched& S, const Epi& E, const int tid) {
;     ...
;         PG8_STAGE(PG8_SB(1, 0), cB + kstep, voffB); PG8_STAGE(PG8_SA(1, 0), cA + kstep, voffA); PG8_STAGE(PG8_SB(1, 1), cB + hstepB + kstep, voffB);
;         PG8_WAIT_V(6); PG8_BAR;
;     }
;     if constexpr (Epi::HAS_INIT) E.init_finish(acc, iw_);
.LBB0_973:
	v_or_b32_e32 v157, s15, v152
	v_lshlrev_b32_e32 v76, 6, v157
	v_lshlrev_b32_e32 v77, 4, v146
	s_movk_i32 s15, 0x3c0
	v_lshlrev_b32_e32 v78, 2, v157
	v_and_or_b32 v76, v76, s15, v77
	s_lshl_b32 s5, s5, 13
	v_and_b32_e32 v78, 32, v78
	v_bitop3_b32 v149, v76, s5, v78 bitop3:0xde
	v_lshl_or_b32 v76, v152, 6, v77
	v_lshlrev_b32_e32 v77, 2, v152
	s_add_i32 m0, s29, 0x18000
	v_lshl_add_u64 v[74:75], v[74:75], 0, s[52:53]
	s_lshl_b32 s4, s4, 12
	v_and_b32_e32 v77, 32, v77
	s_waitcnt vmcnt(2)
	s_barrier
	global_load_lds_dwordx4 v[74:75], off
	v_lshl_add_u64 v[72:73], v[72:73], 0, s[52:53]
	s_add_i32 m0, s29, 0x1a000
	s_add_i32 s64, s29, 0x8000
	s_add_i32 s65, s29, 0xa000
	v_bitop3_b32 v158, s4, v76, v77 bitop3:0xf6
	global_load_lds_dwordx4 v[72:73], off
	v_lshl_add_u64 v[68:69], v[68:69], 0, s[52:53]
	s_mov_b32 m0, s64
	s_add_u32 s4, s36, 0x10080
	global_load_lds_dwordx4 v[68:69], off
	v_lshl_add_u64 v[68:69], v[70:71], 0, s[52:53]
	s_mov_b32 m0, s65
	s_addc_u32 s5, s37, 0
	global_load_lds_dwordx4 v[68:69], off
	s_add_i32 m0, s29, 0x1c000
	v_lshl_add_u64 v[68:69], s[4:5], 0, v[136:137]
	global_load_lds_dwordx4 v[68:69], off
	v_lshl_add_u64 v[68:69], s[4:5], 0, v[140:141]
	s_add_i32 m0, s29, 0x1e000
	v_cmp_eq_u32_e64 s[4:5], 0, v146
	global_load_lds_dwordx4 v[68:69], off
	v_lshlrev_b32_e32 v146, 14, v142
	v_and_b32_e32 v146, 0xffff8000, v146
	v_lshl_add_u32 v143, v143, 11, v146
	v_and_b32_e32 v142, 1, v142
	v_lshl_or_b32 v142, v142, 6, v143
	v_lshl_add_u32 v142, v144, 1, v142
	v_lshlrev_b32_e32 v144, 14, v145
	v_and_b32_e32 v144, 0xffff8000, v144
	s_waitcnt vmcnt(6)
	v_lshl_add_u32 v144, v147, 11, v144
	v_and_b32_e32 v145, 1, v145
	s_cmpk_lt_u32 s14, 0x100
	v_lshl_or_b32 v144, v145, 6, v144
	s_waitcnt vmcnt(0)
	v_lshlrev_b32_e32 v120, 16, v64
	v_and_b32_e32 v121, 0xffff0000, v64
	v_lshlrev_b32_e32 v122, 16, v65
	v_and_b32_e32 v123, 0xffff0000, v65
	v_lshlrev_b32_e32 v128, 16, v66
	v_and_b32_e32 v129, 0xffff0000, v66
	v_lshlrev_b32_e32 v130, 16, v67
	v_and_b32_e32 v131, 0xffff0000, v67
	v_lshlrev_b32_e32 v116, 16, v56
	v_and_b32_e32 v117, 0xffff0000, v56
	v_lshlrev_b32_e32 v118, 16, v57
	v_and_b32_e32 v119, 0xffff0000, v57
	v_lshlrev_b32_e32 v124, 16, v58
	v_and_b32_e32 v125, 0xffff0000, v58
	v_lshlrev_b32_e32 v126, 16, v59
	v_and_b32_e32 v127, 0xffff0000, v59
	v_lshlrev_b32_e32 v100, 16, v60
	v_and_b32_e32 v101, 0xffff0000, v60
	v_lshlrev_b32_e32 v102, 16, v61
	v_and_b32_e32 v103, 0xffff0000, v61
	v_lshlrev_b32_e32 v108, 16, v62
	v_and_b32_e32 v109, 0xffff0000, v62
	v_lshlrev_b32_e32 v110, 16, v63
	v_and_b32_e32 v111, 0xffff0000, v63
	v_lshlrev_b32_e32 v104, 16, v48
	v_and_b32_e32 v105, 0xffff0000, v48
	v_lshlrev_b32_e32 v106, 16, v49
	v_and_b32_e32 v107, 0xffff0000, v49
	v_lshlrev_b32_e32 v112, 16, v50
	v_and_b32_e32 v113, 0xffff0000, v50
	v_lshlrev_b32_e32 v114, 16, v51
	v_and_b32_e32 v115, 0xffff0000, v51
	v_lshlrev_b32_e32 v84, 16, v52
	v_and_b32_e32 v85, 0xffff0000, v52
	v_lshlrev_b32_e32 v86, 16, v53
	v_and_b32_e32 v87, 0xffff0000, v53
	v_lshlrev_b32_e32 v92, 16, v54
	v_and_b32_e32 v93, 0xffff0000, v54
	v_lshlrev_b32_e32 v94, 16, v55
	v_and_b32_e32 v95, 0xffff0000, v55
	v_lshlrev_b32_e32 v88, 16, v40
	v_and_b32_e32 v89, 0xffff0000, v40
	v_lshlrev_b32_e32 v90, 16, v41
	v_and_b32_e32 v91, 0xffff0000, v41
	v_lshlrev_b32_e32 v96, 16, v42
	v_and_b32_e32 v97, 0xffff0000, v42
	v_lshlrev_b32_e32 v98, 16, v43
	v_and_b32_e32 v99, 0xffff0000, v43
	v_lshlrev_b32_e32 v68, 16, v44
	v_and_b32_e32 v69, 0xffff0000, v44
	v_lshlrev_b32_e32 v70, 16, v45
	v_and_b32_e32 v71, 0xffff0000, v45
	v_lshlrev_b32_e32 v76, 16, v46
	v_and_b32_e32 v77, 0xffff0000, v46
	v_lshlrev_b32_e32 v78, 16, v47
	v_and_b32_e32 v79, 0xffff0000, v47
	v_lshlrev_b32_e32 v72, 16, v36
	v_and_b32_e32 v73, 0xffff0000, v36
	v_lshlrev_b32_e32 v74, 16, v37
	v_and_b32_e32 v75, 0xffff0000, v37
	v_lshlrev_b32_e32 v80, 16, v38
	v_and_b32_e32 v81, 0xffff0000, v38
	v_lshlrev_b32_e32 v82, 16, v39
	v_and_b32_e32 v83, 0xffff0000, v39
	v_lshlrev_b32_e32 v52, 16, v32
	v_and_b32_e32 v53, 0xffff0000, v32
	v_lshlrev_b32_e32 v54, 16, v33
	v_and_b32_e32 v55, 0xffff0000, v33
	v_lshlrev_b32_e32 v60, 16, v34
	v_and_b32_e32 v61, 0xffff0000, v34
	v_lshlrev_b32_e32 v62, 16, v35
	v_and_b32_e32 v63, 0xffff0000, v35
	v_lshlrev_b32_e32 v56, 16, v28
	v_and_b32_e32 v57, 0xffff0000, v28
	v_lshlrev_b32_e32 v58, 16, v29
	v_and_b32_e32 v59, 0xffff0000, v29
	v_lshlrev_b32_e32 v64, 16, v30
	v_and_b32_e32 v65, 0xffff0000, v30
	v_lshlrev_b32_e32 v66, 16, v31
	v_and_b32_e32 v67, 0xffff0000, v31
	v_lshlrev_b32_e32 v36, 16, v24
	v_and_b32_e32 v37, 0xffff0000, v24
	v_lshlrev_b32_e32 v38, 16, v25
	v_and_b32_e32 v39, 0xffff0000, v25
	v_lshlrev_b32_e32 v44, 16, v26
	v_and_b32_e32 v45, 0xffff0000, v26
	v_lshlrev_b32_e32 v46, 16, v27
	v_and_b32_e32 v47, 0xffff0000, v27
	v_lshlrev_b32_e32 v40, 16, v20
	v_and_b32_e32 v41, 0xffff0000, v20
	v_lshlrev_b32_e32 v42, 16, v21
	v_and_b32_e32 v43, 0xffff0000, v21
	v_lshlrev_b32_e32 v48, 16, v22
	v_and_b32_e32 v49, 0xffff0000, v22
	v_lshlrev_b32_e32 v50, 16, v23
	v_and_b32_e32 v51, 0xffff0000, v23
	v_lshlrev_b32_e32 v20, 16, v12
	v_and_b32_e32 v21, 0xffff0000, v12
	v_lshlrev_b32_e32 v22, 16, v13
	v_and_b32_e32 v23, 0xffff0000, v13
	v_lshlrev_b32_e32 v28, 16, v14
	v_and_b32_e32 v29, 0xffff0000, v14
	v_lshlrev_b32_e32 v30, 16, v15
	v_and_b32_e32 v31, 0xffff0000, v15
	v_lshlrev_b32_e32 v24, 16, v4
	v_and_b32_e32 v25, 0xffff0000, v4
	v_lshlrev_b32_e32 v26, 16, v5
	v_and_b32_e32 v27, 0xffff0000, v5
	v_lshlrev_b32_e32 v32, 16, v6
	v_and_b32_e32 v33, 0xffff0000, v6
	v_lshlrev_b32_e32 v34, 16, v7
	v_and_b32_e32 v35, 0xffff0000, v7
	v_lshlrev_b32_e32 v4, 16, v8
	v_and_b32_e32 v5, 0xffff0000, v8
	v_lshlrev_b32_e32 v6, 16, v9
	v_and_b32_e32 v7, 0xffff0000, v9
	v_lshlrev_b32_e32 v12, 16, v10
	v_and_b32_e32 v13, 0xffff0000, v10
	v_lshlrev_b32_e32 v14, 16, v11
	v_and_b32_e32 v15, 0xffff0000, v11
	v_lshlrev_b32_e32 v8, 16, v16
	v_and_b32_e32 v9, 0xffff0000, v16
	v_lshlrev_b32_e32 v10, 16, v17
	v_and_b32_e32 v11, 0xffff0000, v17
	v_lshlrev_b32_e32 v16, 16, v18
	v_and_b32_e32 v17, 0xffff0000, v18
	v_lshlrev_b32_e32 v18, 16, v19
	v_and_b32_e32 v19, 0xffff0000, v19
	s_cselect_b64 s[14:15], -1, 0
	s_mov_b32 s66, 0
	s_lshl_b32 s67, s27, 3
	v_or_b32_e32 v159, s54, v156
	v_mov_b32_e32 v143, v2
	v_lshl_add_u32 v144, v148, 1, v144
	v_mov_b32_e32 v145, v2
	v_add_u32_e32 v160, 0, v149
	s_barrier
	s_sub_u32 s36, s36, s32
	s_subb_u32 s37, s37, 0
	s_sub_u32 s38, s38, s32
	s_subb_u32 s39, s39, 0
	s_branch .LBB0_976

; #define PG8_STAGE(bufoff, gbase, voff) do { _Pragma("unroll") for (int _i = 0; _i < 2; ++_i) \
;         __builtin_amdgcn_global_load_lds((const unsigned*)((const char*)(gbase) + (voff)[_i]), (PG8_LAS unsigned*)(lds + (bufoff) + ldsw + _i * 8192), 16, 0, 0); } while (0)
; #define PG8_LDA(dst, b, h) do { _Pragma("unroll") for (int m = 0; m < 4; ++m) _Pragma("unroll") for (int k = 0; k < 2; ++k) dst[m][k] = *(const PG8_LAS bf16x8*)(lds + PG8_SA(b, h) + aoff + m * 2048 + k * 1024); } while (0)
; #define PG8_BAR __builtin_amdgcn_s_barrier()
; template <class Epi, class Sched, bool ALIGN_EPI = false, bool SP2 = false>
; __device__ __forceinline__ void gemm_phase(PG8_LAS unsigned char* lds, const Gemm g, const Sched& S, const Epi& E, const int tid) {
;     ...
;         const char* nA = has_next ? (const char*)g.A + (size_t)nxt.pm * tstep : cA; const char* nB = has_next ? (const char*)g.Bt + (size_t)nxt.pn * tstep : cB;
;         for (int t = 0; t < nt; t += 2) {
;             const bool last = (t == nt - 2);
;             const char* a1 = cA + (size_t)(t + 1) * kstep;
;             const char* a2 = last ? nA : cA + (size_t)(t + 2) * kstep; const char* b2 = last ? nB : cB + (size_t)(t + 2) * kstep;
;             const char* a3 = a2 + kstep; const char* b3 = b2 + kstep;
;             if (last && has_next) S.a_ready(nxt);
;             if constexpr (SP2) {
;             PG8_LDB(B0, 0, 0); PG8_LDB(B1, 0, 1); PG8_SCHED; PG8_LDA(At, 0, 0); PG8_STAGE(PG8_SA(1, 1), a1 + hstep, voffA);
;             PG8_WAIT_V(8); PG8_WAIT_L(0); PG8_BAR; PG8_MMA(0, 0, At, B0); PG8_MMA(0, 1, At, B1); PG8_BAR; PG8_SCHED;
;             PG8_LDA(At, 0, 1); PG8_STAGE(PG8_SB(0, 0), b2, voffB); PG8_STAGE(PG8_SB(0, 1), b2 + hstepB, voffB); PG8_STAGE(PG8_SA(0, 0), a2, voffA);
;             PG8_WAIT_V(8); PG8_WAIT_L(0); PG8_BAR; PG8_MMA(1, 0, At, B0); PG8_MMA(1, 1, At, B1); PG8_BAR; PG8_SCHED;
;             PG8_LDB(B0, 1, 0); PG8_LDB(B1, 1, 1); PG8_SCHED; PG8_LDA(At, 1, 0); PG8_STAGE(PG8_SA(0, 1), a2 + hstep, voffA);
;             PG8_WAIT_V(8); PG8_WAIT_L(0); PG8_BAR; PG8_MMA(0, 0, At, B0); PG8_MMA(0, 1, At, B1); PG8_BAR; PG8_SCHED;
;             PG8_LDA(At, 1, 1); PG8_STAGE(PG8_SB(1, 0), b3, voffB); PG8_STAGE(PG8_SB(1, 1), b3 + hstepB, voffB); PG8_STAGE(PG8_SA(1, 0), a3, voffA);
;             PG8_WAIT_V(8); PG8_WAIT_L(0); PG8_BAR; PG8_MMA(1, 0, At, B0); PG8_MMA(1, 1, At, B1); PG8_BAR; PG8_SCHED;
.LBB0_978:
	s_ashr_i32 s19, s18, 31
	s_lshl_b64 s[20:21], s[18:19], 19
	s_add_u32 s20, s6, s20
	s_addc_u32 s21, s7, s21
	s_and_b64 s[22:23], s[30:31], exec
	s_cselect_b32 s19, s21, s39
	s_cselect_b32 s25, s20, s38
	s_add_u32 s25, s25, s32
	s_addc_u32 s19, s19, 0
	s_ashr_i32 s17, s16, 31
	s_lshl_b64 s[22:23], s[16:17], 19
	s_add_u32 s22, s10, s22
	s_addc_u32 s23, s11, s23
	s_and_b64 s[40:41], s[30:31], exec
	s_cselect_b32 s17, s23, s37
	s_cselect_b32 s76, s22, s36
	s_add_u32 s76, s76, s32
	s_addc_u32 s17, s17, 0
	s_add_u32 s38, s38, 0x40080
	s_addc_u32 s39, s39, 0
	s_mov_b32 s78, s36
	s_mov_b32 s79, s37
	s_mov_b32 s80, -2
.LBB0_979:
	s_lshl_b32 s100, s80, 7
	s_add_i32 s100, s100, s32
	s_add_i32 s100, s100, 0x100
	s_add_i32 s99, s100, 0x100
	s_and_b32 s100, s100, 0x700
	s_and_b32 s99, s99, 0x700
	s_add_u32 s100, s38, s100
	s_addc_u32 s101, s39, 0
	s_add_u32 s36, s38, 0xfffbff80
	s_addc_u32 s37, s39, -1
	s_add_u32 s36, s36, s99
	s_addc_u32 s37, s37, 0
	s_add_i32 s81, 0, 0x10000
	s_cmp_eq_u32 s80, 12
	s_cselect_b32 s41, s19, s37
	s_cselect_b32 s40, s25, s36
	v_add_u32_e32 v150, s81, v158
	s_add_u32 s36, s78, s99
	s_addc_u32 s37, s79, 0
	s_cmp_eq_u32 s80, 12
	s_cselect_b32 s37, s17, s37
	s_cselect_b32 s36, s76, s36
	s_add_i32 s84, 0, 0x14000
	ds_read_b128 v[146:149], v150
	ds_read_b128 v[162:165], v150 offset:1024
	ds_read_b128 v[170:173], v150 offset:2048
	ds_read_b128 v[174:177], v150 offset:3072
	v_add_u32_e32 v150, s84, v158
	ds_read_b128 v[178:181], v150
	ds_read_b128 v[182:185], v150 offset:1024
	ds_read_b128 v[186:189], v150 offset:2048
	ds_read_b128 v[190:193], v150 offset:3072
	v_lshl_add_u64 v[150:151], s[100:101], 0, v[142:143]
	s_add_i32 m0, s29, 0xc000
	ds_read_b128 v[194:197], v160
	ds_read_b128 v[198:201], v160 offset:1024
	ds_read_b128 v[212:215], v160 offset:2048
	ds_read_b128 v[216:219], v160 offset:3072
	ds_read_b128 v[220:223], v160 offset:4096
	ds_read_b128 v[224:227], v160 offset:5120
	ds_read_b128 v[228:231], v160 offset:6144
	ds_read_b128 v[232:235], v160 offset:7168
	global_load_lds_dwordx4 v[150:151], off
	v_lshl_add_u64 v[150:151], s[100:101], 0, v[144:145]
	s_add_i32 m0, s29, 0xe000
	s_nop 0
	global_load_lds_dwordx4 v[150:151], off
	s_waitcnt vmcnt(8)
	s_waitcnt lgkmcnt(0)
	s_barrier
	s_setprio 1
	s_waitcnt lgkmcnt(0)
	v_mfma_f32_16x16x32_bf16 v[120:123], v[146:149], v[194:197], v[120:123]
	v_mfma_f32_16x16x32_bf16 v[128:131], v[170:173], v[194:197], v[128:131]
	v_mfma_f32_16x16x32_bf16 v[100:103], v[146:149], v[212:215], v[100:103]
	v_mfma_f32_16x16x32_bf16 v[108:111], v[170:173], v[212:215], v[108:111]
	v_mfma_f32_16x16x32_bf16 v[84:87], v[146:149], v[220:223], v[84:87]
	v_mfma_f32_16x16x32_bf16 v[92:95], v[170:173], v[220:223], v[92:95]
	v_mfma_f32_16x16x32_bf16 v[68:71], v[146:149], v[228:231], v[68:71]
	v_mfma_f32_16x16x32_bf16 v[76:79], v[170:173], v[228:231], v[76:79]
	v_mfma_f32_16x16x32_bf16 v[120:123], v[162:165], v[198:201], v[120:123]
	v_mfma_f32_16x16x32_bf16 v[128:131], v[174:177], v[198:201], v[128:131]
	v_mfma_f32_16x16x32_bf16 v[100:103], v[162:165], v[216:219], v[100:103]
	v_mfma_f32_16x16x32_bf16 v[108:111], v[174:177], v[216:219], v[108:111]
	v_mfma_f32_16x16x32_bf16 v[84:87], v[162:165], v[224:227], v[84:87]
	v_mfma_f32_16x16x32_bf16 v[92:95], v[174:177], v[224:227], v[92:95]
	v_mfma_f32_16x16x32_bf16 v[68:71], v[162:165], v[232:235], v[68:71]
	v_mfma_f32_16x16x32_bf16 v[76:79], v[174:177], v[232:235], v[76:79]
	s_setprio 0
	s_setprio 1
	v_mfma_f32_16x16x32_bf16 v[116:119], v[178:181], v[194:197], v[116:119]
	v_mfma_f32_16x16x32_bf16 v[124:127], v[186:189], v[194:197], v[124:127]
	v_mfma_f32_16x16x32_bf16 v[104:107], v[178:181], v[212:215], v[104:107]
	v_mfma_f32_16x16x32_bf16 v[112:115], v[186:189], v[212:215], v[112:115]
	v_mfma_f32_16x16x32_bf16 v[88:91], v[178:181], v[220:223], v[88:91]
	v_mfma_f32_16x16x32_bf16 v[96:99], v[186:189], v[220:223], v[96:99]
	v_mfma_f32_16x16x32_bf16 v[72:75], v[178:181], v[228:231], v[72:75]
	v_mfma_f32_16x16x32_bf16 v[80:83], v[186:189], v[228:231], v[80:83]
	v_mfma_f32_16x16x32_bf16 v[116:119], v[182:185], v[198:201], v[116:119]
	v_mfma_f32_16x16x32_bf16 v[124:127], v[190:193], v[198:201], v[124:127]
	v_mfma_f32_16x16x32_bf16 v[104:107], v[182:185], v[216:219], v[104:107]
	v_mfma_f32_16x16x32_bf16 v[112:115], v[190:193], v[216:219], v[112:115]
	v_mfma_f32_16x16x32_bf16 v[88:91], v[182:185], v[224:227], v[88:91]
	v_mfma_f32_16x16x32_bf16 v[96:99], v[190:193], v[224:227], v[96:99]
	v_mfma_f32_16x16x32_bf16 v[72:75], v[182:185], v[232:235], v[72:75]
	v_mfma_f32_16x16x32_bf16 v[80:83], v[190:193], v[232:235], v[80:83]
	s_setprio 0
	s_barrier
	s_add_i32 s81, s81, s43
	v_lshl_add_u64 v[150:151], s[36:37], 0, v[136:137]
	s_mov_b32 m0, s81
	ds_read_b128 v[194:197], v160 offset:16384
	ds_read_b128 v[198:201], v160 offset:17408
	ds_read_b128 v[212:215], v160 offset:18432
	ds_read_b128 v[216:219], v160 offset:19456
	ds_read_b128 v[220:223], v160 offset:20480
	ds_read_b128 v[224:227], v160 offset:21504
	ds_read_b128 v[228:231], v160 offset:22528
	ds_read_b128 v[232:235], v160 offset:23552
	global_load_lds_dwordx4 v[150:151], off
	s_add_i32 m0, s81, 0x2000
	s_add_u32 s82, s36, 0x10000
	v_lshl_add_u64 v[166:167], s[36:37], 0, v[140:141]
	s_addc_u32 s83, s37, 0
	s_add_i32 s81, s84, s43
	global_load_lds_dwordx4 v[166:167], off
	v_lshl_add_u64 v[236:237], s[82:83], 0, v[136:137]
	s_mov_b32 m0, s81
	v_lshl_add_u64 v[238:239], s[40:41], 0, v[138:139]
	global_load_lds_dwordx4 v[236:237], off
	v_lshl_add_u64 v[236:237], s[82:83], 0, v[140:141]
	s_add_i32 m0, s81, 0x2000
	s_nop 0
	global_load_lds_dwordx4 v[236:237], off
	v_lshl_add_u64 v[236:237], s[40:41], 0, v[134:135]
	s_mov_b32 m0, s29
	s_nop 0
	global_load_lds_dwordx4 v[236:237], off
	s_mov_b32 m0, s55
	s_nop 0
	global_load_lds_dwordx4 v[238:239], off
	s_waitcnt vmcnt(8)
	s_waitcnt lgkmcnt(0)
	s_barrier
; #define PG8_STAGE(bufoff, gbase, voff) do { _Pragma("unroll") for (int _i = 0; _i < 2; ++_i) \
;         __builtin_amdgcn_global_load_lds((const unsigned*)((const char*)(gbase) + (voff)[_i]), (PG8_LAS unsigned*)(lds + (bufoff) + ldsw + _i * 8192), 16, 0, 0); } while (0)
; #define PG8_LDA(dst, b, h) do { _Pragma("unroll") for (int m = 0; m < 4; ++m) _Pragma("unroll") for (int k = 0; k < 2; ++k) dst[m][k] = *(const PG8_LAS bf16x8*)(lds + PG8_SA(b, h) + aoff + m * 2048 + k * 1024); } while (0)
; #define PG8_LDB(dst, b, h) do { _Pragma("unroll") for (int n = 0; n < 2; ++n) _Pragma("unroll") for (int k = 0; k < 2; ++k) dst[n][k] = *(const PG8_LAS bf16x8*)(lds + PG8_SB(b, h) + boff + n * 2048 + k * 1024); } while (0)
; #define PG8_MMA(ai, bj, At, Bt) do { __builtin_amdgcn_s_setprio(1); _Pragma("unroll") for (int m = 0; m < 4; ++m) _Pragma("unroll") for (int n = 0; n < 2; ++n) _Pragma("unroll") for (int k = 0; k < 2; ++k) \
;         acc[ai][bj][m][n] = __builtin_amdgcn_mfma_f32_16x16x32_bf16(Bt[n][k], At[m][k], acc[ai][bj][m][n], 0, 0, 0); __builtin_amdgcn_s_setprio(0); } while (0)
; #define PG8_WAIT_V(n) asm volatile("s_waitcnt vmcnt(" #n ")" ::: "memory")
; #define PG8_WAIT_L(n) asm volatile("s_waitcnt lgkmcnt(" #n ")" ::: "memory")
; #define PG8_BAR __builtin_amdgcn_s_barrier()
; #define PG8_SCHED __builtin_amdgcn_sched_barrier(0)
; template <class Epi, class Sched, bool ALIGN_EPI = false, bool SP2 = false>
; __device__ __forceinline__ void gemm_phase(PG8_LAS unsigned char* lds, const Gemm g, const Sched& S, const Epi& E, const int tid) {
;     ...
;             PG8_WAIT_V(8); PG8_WAIT_L(0); PG8_BAR; PG8_MMA(0, 0, At, B0); PG8_MMA(0, 1, At, B1); PG8_BAR; PG8_SCHED;
;             PG8_LDA(At, 0, 1); PG8_STAGE(PG8_SB(0, 0), b2, voffB); PG8_STAGE(PG8_SB(0, 1), b2 + hstepB, voffB); PG8_STAGE(PG8_SA(0, 0), a2, voffA);
;             PG8_WAIT_V(8); PG8_WAIT_L(0); PG8_BAR; PG8_MMA(1, 0, At, B0); PG8_MMA(1, 1, At, B1); PG8_BAR; PG8_SCHED;
;             PG8_LDB(B0, 1, 0); PG8_LDB(B1, 1, 1); PG8_SCHED; PG8_LDA(At, 1, 0); PG8_STAGE(PG8_SA(0, 1), a2 + hstep, voffA);
;             PG8_WAIT_V(8); PG8_WAIT_L(0); PG8_BAR; PG8_MMA(0, 0, At, B0); PG8_MMA(0, 1, At, B1); PG8_BAR; PG8_SCHED;
	s_setprio 1
	s_waitcnt lgkmcnt(0)
	v_mfma_f32_16x16x32_bf16 v[52:55], v[146:149], v[194:197], v[52:55]
	v_mfma_f32_16x16x32_bf16 v[60:63], v[170:173], v[194:197], v[60:63]
	v_mfma_f32_16x16x32_bf16 v[36:39], v[146:149], v[212:215], v[36:39]
	v_mfma_f32_16x16x32_bf16 v[44:47], v[170:173], v[212:215], v[44:47]
	v_mfma_f32_16x16x32_bf16 v[20:23], v[146:149], v[220:223], v[20:23]
	v_mfma_f32_16x16x32_bf16 v[28:31], v[170:173], v[220:223], v[28:31]
	v_mfma_f32_16x16x32_bf16 v[4:7], v[146:149], v[228:231], v[4:7]
	v_mfma_f32_16x16x32_bf16 v[12:15], v[170:173], v[228:231], v[12:15]
	v_mfma_f32_16x16x32_bf16 v[52:55], v[162:165], v[198:201], v[52:55]
	v_mfma_f32_16x16x32_bf16 v[60:63], v[174:177], v[198:201], v[60:63]
	v_mfma_f32_16x16x32_bf16 v[36:39], v[162:165], v[216:219], v[36:39]
	v_mfma_f32_16x16x32_bf16 v[44:47], v[174:177], v[216:219], v[44:47]
	v_mfma_f32_16x16x32_bf16 v[20:23], v[162:165], v[224:227], v[20:23]
	v_mfma_f32_16x16x32_bf16 v[28:31], v[174:177], v[224:227], v[28:31]
	v_mfma_f32_16x16x32_bf16 v[4:7], v[162:165], v[232:235], v[4:7]
	v_mfma_f32_16x16x32_bf16 v[12:15], v[174:177], v[232:235], v[12:15]
	s_setprio 0
	s_setprio 1
	v_mfma_f32_16x16x32_bf16 v[56:59], v[178:181], v[194:197], v[56:59]
	v_mfma_f32_16x16x32_bf16 v[64:67], v[186:189], v[194:197], v[64:67]
	v_mfma_f32_16x16x32_bf16 v[40:43], v[178:181], v[212:215], v[40:43]
	v_mfma_f32_16x16x32_bf16 v[48:51], v[186:189], v[212:215], v[48:51]
	v_mfma_f32_16x16x32_bf16 v[24:27], v[178:181], v[220:223], v[24:27]
	v_mfma_f32_16x16x32_bf16 v[32:35], v[186:189], v[220:223], v[32:35]
	v_mfma_f32_16x16x32_bf16 v[8:11], v[178:181], v[228:231], v[8:11]
	v_mfma_f32_16x16x32_bf16 v[16:19], v[186:189], v[228:231], v[16:19]
	v_mfma_f32_16x16x32_bf16 v[56:59], v[182:185], v[198:201], v[56:59]
	v_mfma_f32_16x16x32_bf16 v[64:67], v[190:193], v[198:201], v[64:67]
	v_mfma_f32_16x16x32_bf16 v[40:43], v[182:185], v[216:219], v[40:43]
	v_mfma_f32_16x16x32_bf16 v[48:51], v[190:193], v[216:219], v[48:51]
	v_mfma_f32_16x16x32_bf16 v[24:27], v[182:185], v[224:227], v[24:27]
	v_mfma_f32_16x16x32_bf16 v[32:35], v[190:193], v[224:227], v[32:35]
	v_mfma_f32_16x16x32_bf16 v[8:11], v[182:185], v[232:235], v[8:11]
	v_mfma_f32_16x16x32_bf16 v[16:19], v[190:193], v[232:235], v[16:19]
	s_setprio 0
	s_barrier
	s_add_i32 s81, 0, 0x18000
	v_add_u32_e32 v161, s81, v158
	s_add_i32 s82, 0, 0x1c000
	ds_read_b128 v[146:149], v161
	ds_read_b128 v[162:165], v161 offset:1024
	ds_read_b128 v[170:173], v161 offset:2048
	ds_read_b128 v[174:177], v161 offset:3072
	v_add_u32_e32 v161, s82, v158
	ds_read_b128 v[178:181], v161
	ds_read_b128 v[182:185], v161 offset:1024
	ds_read_b128 v[186:189], v161 offset:2048
	ds_read_b128 v[190:193], v161 offset:3072
	s_add_u32 s40, s40, 0x40000
	s_addc_u32 s41, s41, 0
	s_mov_b32 m0, s62
	v_lshl_add_u64 v[240:241], s[40:41], 0, v[134:135]
	ds_read_b128 v[194:197], v160 offset:32768
	ds_read_b128 v[198:201], v160 offset:33792
	ds_read_b128 v[212:215], v160 offset:34816
	ds_read_b128 v[216:219], v160 offset:35840
	ds_read_b128 v[220:223], v160 offset:36864
	ds_read_b128 v[224:227], v160 offset:37888
	ds_read_b128 v[228:231], v160 offset:38912
	ds_read_b128 v[232:235], v160 offset:39936
	global_load_lds_dwordx4 v[240:241], off
	v_lshl_add_u64 v[240:241], s[40:41], 0, v[138:139]
	s_mov_b32 m0, s63
	s_nop 0
	global_load_lds_dwordx4 v[240:241], off
	s_waitcnt vmcnt(8)
	s_waitcnt lgkmcnt(0)
	s_barrier
	s_setprio 1
	s_waitcnt lgkmcnt(0)
	v_mfma_f32_16x16x32_bf16 v[120:123], v[146:149], v[194:197], v[120:123]
	v_mfma_f32_16x16x32_bf16 v[128:131], v[170:173], v[194:197], v[128:131]
	v_mfma_f32_16x16x32_bf16 v[100:103], v[146:149], v[212:215], v[100:103]
	v_mfma_f32_16x16x32_bf16 v[108:111], v[170:173], v[212:215], v[108:111]
	v_mfma_f32_16x16x32_bf16 v[84:87], v[146:149], v[220:223], v[84:87]
	v_mfma_f32_16x16x32_bf16 v[92:95], v[170:173], v[220:223], v[92:95]
	v_mfma_f32_16x16x32_bf16 v[68:71], v[146:149], v[228:231], v[68:71]
	v_mfma_f32_16x16x32_bf16 v[76:79], v[170:173], v[228:231], v[76:79]
	v_mfma_f32_16x16x32_bf16 v[120:123], v[162:165], v[198:201], v[120:123]
	v_mfma_f32_16x16x32_bf16 v[128:131], v[174:177], v[198:201], v[128:131]
	v_mfma_f32_16x16x32_bf16 v[100:103], v[162:165], v[216:219], v[100:103]
	v_mfma_f32_16x16x32_bf16 v[108:111], v[174:177], v[216:219], v[108:111]
	v_mfma_f32_16x16x32_bf16 v[84:87], v[162:165], v[224:227], v[84:87]
	v_mfma_f32_16x16x32_bf16 v[92:95], v[174:177], v[224:227], v[92:95]
	v_mfma_f32_16x16x32_bf16 v[68:71], v[162:165], v[232:235], v[68:71]
	v_mfma_f32_16x16x32_bf16 v[76:79], v[174:177], v[232:235], v[76:79]
	s_setprio 0
	s_setprio 1
	v_mfma_f32_16x16x32_bf16 v[116:119], v[178:181], v[194:197], v[116:119]
	v_mfma_f32_16x16x32_bf16 v[124:127], v[186:189], v[194:197], v[124:127]
	v_mfma_f32_16x16x32_bf16 v[104:107], v[178:181], v[212:215], v[104:107]
	v_mfma_f32_16x16x32_bf16 v[112:115], v[186:189], v[212:215], v[112:115]
	v_mfma_f32_16x16x32_bf16 v[88:91], v[178:181], v[220:223], v[88:91]
	v_mfma_f32_16x16x32_bf16 v[96:99], v[186:189], v[220:223], v[96:99]
	v_mfma_f32_16x16x32_bf16 v[72:75], v[178:181], v[228:231], v[72:75]
	v_mfma_f32_16x16x32_bf16 v[80:83], v[186:189], v[228:231], v[80:83]
	v_mfma_f32_16x16x32_bf16 v[116:119], v[182:185], v[198:201], v[116:119]
	v_mfma_f32_16x16x32_bf16 v[124:127], v[190:193], v[198:201], v[124:127]
	v_mfma_f32_16x16x32_bf16 v[104:107], v[182:185], v[216:219], v[104:107]
	v_mfma_f32_16x16x32_bf16 v[112:115], v[190:193], v[216:219], v[112:115]
	v_mfma_f32_16x16x32_bf16 v[88:91], v[182:185], v[224:227], v[88:91]
	v_mfma_f32_16x16x32_bf16 v[96:99], v[190:193], v[224:227], v[96:99]
	v_mfma_f32_16x16x32_bf16 v[72:75], v[182:185], v[232:235], v[72:75]
	v_mfma_f32_16x16x32_bf16 v[80:83], v[190:193], v[232:235], v[80:83]
	s_setprio 0
	s_barrier
; #define PG8_STAGE(bufoff, gbase, voff) do { _Pragma("unroll") for (int _i = 0; _i < 2; ++_i) \
;         __builtin_amdgcn_global_load_lds((const unsigned*)((const char*)(gbase) + (voff)[_i]), (PG8_LAS unsigned*)(lds + (bufoff) + ldsw + _i * 8192), 16, 0, 0); } while (0)
; #define PG8_LDA(dst, b, h) do { _Pragma("unroll") for (int m = 0; m < 4; ++m) _Pragma("unroll") for (int k = 0; k < 2; ++k) dst[m][k] = *(const PG8_LAS bf16x8*)(lds + PG8_SA(b, h) + aoff + m * 2048 + k * 1024); } while (0)
; #define PG8_LDB(dst, b, h) do { _Pragma("unroll") for (int n = 0; n < 2; ++n) _Pragma("unroll") for (int k = 0; k < 2; ++k) dst[n][k] = *(const PG8_LAS bf16x8*)(lds + PG8_SB(b, h) + boff + n * 2048 + k * 1024); } while (0)
; #define PG8_MMA(ai, bj, At, Bt) do { __builtin_amdgcn_s_setprio(1); _Pragma("unroll") for (int m = 0; m < 4; ++m) _Pragma("unroll") for (int n = 0; n < 2; ++n) _Pragma("unroll") for (int k = 0; k < 2; ++k) \
;         acc[ai][bj][m][n] = __builtin_amdgcn_mfma_f32_16x16x32_bf16(Bt[n][k], At[m][k], acc[ai][bj][m][n], 0, 0, 0); __builtin_amdgcn_s_setprio(0); } while (0)
; #define PG8_WAIT_V(n) asm volatile("s_waitcnt vmcnt(" #n ")" ::: "memory")
; #define PG8_WAIT_L(n) asm volatile("s_waitcnt lgkmcnt(" #n ")" ::: "memory")
; #define PG8_BAR __builtin_amdgcn_s_barrier()
; #define PG8_SCHED __builtin_amdgcn_sched_barrier(0)
; template <class Epi, class Sched, bool ALIGN_EPI = false, bool SP2 = false>
; __device__ __forceinline__ void gemm_phase(PG8_LAS unsigned char* lds, const Gemm g, const Sched& S, const Epi& E, const int tid) {
;     ...
;             PG8_WAIT_V(8); PG8_WAIT_L(0); PG8_BAR; PG8_MMA(1, 0, At, B0); PG8_MMA(1, 1, At, B1); PG8_BAR; PG8_SCHED;
;             PG8_LDB(B0, 1, 0); PG8_LDB(B1, 1, 1); PG8_SCHED; PG8_LDA(At, 1, 0); PG8_STAGE(PG8_SA(0, 1), a2 + hstep, voffA);
;             PG8_WAIT_V(8); PG8_WAIT_L(0); PG8_BAR; PG8_MMA(0, 0, At, B0); PG8_MMA(0, 1, At, B1); PG8_BAR; PG8_SCHED;
;             PG8_LDA(At, 1, 1); PG8_STAGE(PG8_SB(1, 0), b3, voffB); PG8_STAGE(PG8_SB(1, 1), b3 + hstepB, voffB); PG8_STAGE(PG8_SA(1, 0), a3, voffA);
;             PG8_WAIT_V(8); PG8_WAIT_L(0); PG8_BAR; PG8_MMA(1, 0, At, B0); PG8_MMA(1, 1, At, B1); PG8_BAR; PG8_SCHED;
	s_add_i32 s40, s81, s43
	v_lshl_add_u64 v[150:151], v[150:151], 0, s[52:53]
	s_mov_b32 m0, s40
	ds_read_b128 v[194:197], v160 offset:49152
	ds_read_b128 v[198:201], v160 offset:50176
	ds_read_b128 v[212:215], v160 offset:51200
	ds_read_b128 v[216:219], v160 offset:52224
	ds_read_b128 v[220:223], v160 offset:53248
	ds_read_b128 v[224:227], v160 offset:54272
	ds_read_b128 v[228:231], v160 offset:55296
	ds_read_b128 v[232:235], v160 offset:56320
	global_load_lds_dwordx4 v[150:151], off
	s_add_i32 m0, s40, 0x2000
	s_add_u32 s36, s36, 0x10080
	v_lshl_add_u64 v[150:151], v[166:167], 0, s[52:53]
	s_addc_u32 s37, s37, 0
	s_add_i32 s40, s82, s43
	global_load_lds_dwordx4 v[150:151], off
	v_lshl_add_u64 v[150:151], s[36:37], 0, v[136:137]
	s_mov_b32 m0, s40
	s_nop 0
	global_load_lds_dwordx4 v[150:151], off
	v_lshl_add_u64 v[150:151], s[36:37], 0, v[140:141]
	s_add_i32 m0, s40, 0x2000
	s_nop 0
	global_load_lds_dwordx4 v[150:151], off
	v_lshl_add_u64 v[150:151], v[236:237], 0, s[52:53]
	s_mov_b32 m0, s64
	s_nop 0
	global_load_lds_dwordx4 v[150:151], off
	v_lshl_add_u64 v[150:151], v[238:239], 0, s[52:53]
	s_mov_b32 m0, s65
	s_nop 0
	global_load_lds_dwordx4 v[150:151], off
	s_waitcnt vmcnt(8)
	s_waitcnt lgkmcnt(0)
	s_barrier
	s_setprio 1
	s_waitcnt lgkmcnt(0)
	v_mfma_f32_16x16x32_bf16 v[52:55], v[146:149], v[194:197], v[52:55]
	v_mfma_f32_16x16x32_bf16 v[60:63], v[170:173], v[194:197], v[60:63]
	v_mfma_f32_16x16x32_bf16 v[36:39], v[146:149], v[212:215], v[36:39]
	v_mfma_f32_16x16x32_bf16 v[44:47], v[170:173], v[212:215], v[44:47]
	v_mfma_f32_16x16x32_bf16 v[20:23], v[146:149], v[220:223], v[20:23]
	v_mfma_f32_16x16x32_bf16 v[28:31], v[170:173], v[220:223], v[28:31]
	v_mfma_f32_16x16x32_bf16 v[4:7], v[146:149], v[228:231], v[4:7]
	v_mfma_f32_16x16x32_bf16 v[12:15], v[170:173], v[228:231], v[12:15]
	v_mfma_f32_16x16x32_bf16 v[52:55], v[162:165], v[198:201], v[52:55]
	v_mfma_f32_16x16x32_bf16 v[60:63], v[174:177], v[198:201], v[60:63]
	v_mfma_f32_16x16x32_bf16 v[36:39], v[162:165], v[216:219], v[36:39]
	v_mfma_f32_16x16x32_bf16 v[44:47], v[174:177], v[216:219], v[44:47]
	v_mfma_f32_16x16x32_bf16 v[20:23], v[162:165], v[224:227], v[20:23]
	v_mfma_f32_16x16x32_bf16 v[28:31], v[174:177], v[224:227], v[28:31]
	v_mfma_f32_16x16x32_bf16 v[4:7], v[162:165], v[232:235], v[4:7]
	v_mfma_f32_16x16x32_bf16 v[12:15], v[174:177], v[232:235], v[12:15]
	s_setprio 0
	s_setprio 1
	v_mfma_f32_16x16x32_bf16 v[56:59], v[178:181], v[194:197], v[56:59]
	v_mfma_f32_16x16x32_bf16 v[64:67], v[186:189], v[194:197], v[64:67]
	v_mfma_f32_16x16x32_bf16 v[40:43], v[178:181], v[212:215], v[40:43]
	v_mfma_f32_16x16x32_bf16 v[48:51], v[186:189], v[212:215], v[48:51]
	v_mfma_f32_16x16x32_bf16 v[24:27], v[178:181], v[220:223], v[24:27]
	v_mfma_f32_16x16x32_bf16 v[32:35], v[186:189], v[220:223], v[32:35]
	v_mfma_f32_16x16x32_bf16 v[8:11], v[178:181], v[228:231], v[8:11]
	v_mfma_f32_16x16x32_bf16 v[16:19], v[186:189], v[228:231], v[16:19]
	v_mfma_f32_16x16x32_bf16 v[56:59], v[182:185], v[198:201], v[56:59]
	v_mfma_f32_16x16x32_bf16 v[64:67], v[190:193], v[198:201], v[64:67]
	v_mfma_f32_16x16x32_bf16 v[40:43], v[182:185], v[216:219], v[40:43]
	v_mfma_f32_16x16x32_bf16 v[48:51], v[190:193], v[216:219], v[48:51]
	v_mfma_f32_16x16x32_bf16 v[24:27], v[182:185], v[224:227], v[24:27]
	v_mfma_f32_16x16x32_bf16 v[32:35], v[190:193], v[224:227], v[32:35]
	v_mfma_f32_16x16x32_bf16 v[8:11], v[182:185], v[232:235], v[8:11]
	v_mfma_f32_16x16x32_bf16 v[16:19], v[190:193], v[232:235], v[16:19]
	s_setprio 0
	s_barrier
	s_add_i32 s80, s80, 2
	s_cmp_gt_u32 s80, 13
	s_cbranch_scc0 .LBB0_979
	s_and_b64 vcc, exec, s[14:15]
	s_cbranch_vccz .LBB0_982
	s_barrier

;     DI bool next(int i, Unit& u) const { const int L = i * 32 + rank; if (L >= ppg * nN) return false; u.pm = ppg * grp + (L % ppg); const int p0 = L / ppg, p1 = p0 + rot; u.pn = rev ? nN - 1 - p0 : (p1 >= nN ? p1 - nN : p1); return true; }
; #define PG8_WAIT_V(n) asm volatile("s_waitcnt vmcnt(" #n ")" ::: "memory")
; #define PG8_BAR __builtin_amdgcn_s_barrier()
; template <class Epi, class Sched, bool ALIGN_EPI = false, bool SP2 = false>
; __device__ __forceinline__ void gemm_phase(PG8_LAS unsigned char* lds, const Gemm g, const Sched& S, const Epi& E, const int tid) {
;     ...
;     for (int i = 0; i < 2; ++i) { int R, C; stage_rc(tid * 16 + i * 8192, R, C); const int Rb = Epi::PERM ? (2 * (R & ~31) + perm32(R & 31)) : R;
;         voffA[i] = (unsigned)(R * K + C) * 2u; voffB[i] = (unsigned)(Rb * K + C) * 2u; }
;     const size_t kstep = (size_t)(BK * 2);
;     const size_t hstep = (size_t)HALF * K * 2;
;     const size_t tstep = 2 * hstep;
;     const size_t hstepB = Epi::PERM ? (size_t)32 * K * 2 : hstep;
;     const unsigned ldsw = (unsigned)wid * 1024u;
;     const int aoff = lds_byte(wr * 64 + fr, fq * 8), boff = lds_byte(wc * 32 + fr, fq * 8);
;     ...
;     Unit cur, nxt; int ui = 0;
;     if (!S.next(0, cur)) return;
;     f32x4 acc[2][2][4][2];
;     u32x4 iw_[Epi::HAS_INIT ? 16 : 1];
;     if constexpr (Epi::HAS_INIT) E.init_issue(iw_, cur, wr, wc, fr, fq);
;     else {
; #pragma unroll
;     for (int a = 0; a < 2; ++a)
; #pragma unroll
;         for (int b = 0; b < 2; ++b)
; #pragma unroll
;             for (int m = 0; m < 4; ++m)
; #pragma unroll
;                 for (int n = 0; n < 2; ++n) acc[a][b][m][n] = (f32x4){0.f, 0.f, 0.f, 0.f};
;     }
;     bf16x8 At[4][2], B0[2][2], B1[2][2];
;     const char* cA = (const char*)g.A + (size_t)cur.pm * tstep; const char* cB = (const char*)g.Bt + (size_t)cur.pn * tstep;
;     S.a_ready(cur);
;     if constexpr (SP2) {
;         PG8_STAGE(PG8_SB(0, 0), cB, voffB); PG8_STAGE(PG8_SB(0, 1), cB + hstepB, voffB); PG8_STAGE(PG8_SA(0, 0), cA, voffA); PG8_STAGE(PG8_SA(0, 1), cA + hstep, voffA);
;         if (wr == 1) PG8_BAR;
;         PG8_WAIT_V(2); PG8_BAR;
;         PG8_STAGE(PG8_SB(1, 0), cB + kstep, voffB); PG8_STAGE(PG8_SA(1, 0), cA + kstep, voffA); PG8_STAGE(PG8_SB(1, 1), cB + hstepB + kstep, voffB);
;         PG8_WAIT_V(6); PG8_BAR;
.LBB0_1099:
	s_or_b64 exec, exec, s[6:7]
	v_ashrrev_i32_e32 v4, 31, v3
	v_lshrrev_b32_e32 v4, 26, v4
	v_add_u32_e32 v4, v3, v4
	v_ashrrev_i32_e32 v12, 6, v4
	v_bfe_i32 v4, v3, 27, 1
	v_lshlrev_b32_e32 v150, 4, v3
	v_lshrrev_b32_e32 v4, 22, v4
	v_add_u32_e32 v4, v150, v4
	v_and_b32_e32 v4, 0xfffffc00, v4
	v_sub_u32_e32 v4, v150, v4
	s_mov_b32 s6, s46
	s_mov_b32 s7, s35
	v_lshrrev_b32_e32 v5, 4, v4
	s_lshl_b64 s[14:15], s[6:7], 21
	v_bitop3_b32 v4, v5, v4, 32 bitop3:0x6c
	s_add_u32 s8, s0, s14
	v_ashrrev_i32_e32 v6, 31, v4
	s_addc_u32 s9, s1, s15
	v_lshrrev_b32_e32 v6, 26, v6
	s_add_u32 s12, s8, 0x100000
	v_add_u32_e32 v6, v4, v6
	s_addc_u32 s13, s9, 0
	v_lshlrev_b32_e32 v5, 3, v12
	v_ashrrev_i32_e32 v13, 6, v6
	v_and_b32_e32 v6, 0xc0, v6
	s_add_u32 s8, s0, 0xc300000
	v_and_b32_e32 v5, -16, v5
	v_sub_u32_e32 v4, v4, v6
	s_addc_u32 s9, s1, 0
	v_add_u32_e32 v133, v13, v5
	v_ashrrev_i16_sdwa v4, v205, sext(v4) dst_sel:DWORD dst_unused:UNUSED_PAD src0_sel:DWORD src1_sel:BYTE_0
	s_add_u32 s10, s0, 0x10b00000
	v_lshlrev_b32_e32 v5, 5, v12
	v_bfe_i32 v14, v4, 0, 16
	v_lshrrev_b32_e32 v4, 2, v133
	s_addc_u32 s11, s1, 0
	v_and_b32_e32 v5, 32, v5
	v_and_b32_e32 v153, 4, v4
	v_lshrrev_b32_e32 v4, 1, v3
	v_readfirstlane_b32 s18, v3
	v_add_u32_e32 v132, v5, v14
	v_lshlrev_b32_e32 v155, 1, v133
	v_and_b32_e32 v154, 3, v13
	v_and_b32_e32 v152, 15, v3
	s_cmp_gt_i32 s62, 31
	v_and_b32_e32 v151, 24, v4
	s_waitcnt vmcnt(0) lgkmcnt(0)
	s_barrier
	s_cbranch_scc1 .LBB0_1115
	v_add_u32_e32 v4, 0x2000, v150
	v_ashrrev_i32_e32 v5, 31, v4
	v_lshrrev_b32_e32 v5, 22, v5
	v_add_u32_e32 v5, v4, v5
	v_ashrrev_i32_e32 v15, 10, v5
	v_mul_i32_i24_e32 v5, 0x400, v15
	v_sub_u32_e32 v4, v4, v5
	v_lshrrev_b32_e32 v5, 4, v4
	v_bitop3_b32 v4, v5, v4, 32 bitop3:0x6c
	v_ashrrev_i32_e32 v5, 31, v4
	v_lshrrev_b32_e32 v5, 26, v5
	v_add_u32_e32 v5, v4, v5
	v_lshlrev_b32_e32 v6, 3, v15
	s_ashr_i32 s16, s62, 31
	v_ashrrev_i32_e32 v16, 6, v5
	v_and_b32_e32 v6, -16, v6
	s_lshr_b32 s16, s16, 29
	v_add_u32_e32 v6, v16, v6
	s_add_i32 s16, s62, s16
	v_lshrrev_b32_e32 v7, 2, v6
	v_lshlrev_b32_e32 v9, 1, v6
	v_and_b32_e32 v5, 0xc0, v5
	s_ashr_i32 s36, s16, 3
	s_and_b32 s16, s16, -8
	v_and_b32_e32 v7, 4, v7
	v_and_b32_e32 v8, 3, v16
	v_and_b32_e32 v9, 0x1fffd8, v9
	v_sub_u32_e32 v4, v4, v5
	s_lshl_b32 s64, s3, 3
	s_sub_i32 s16, s62, s16
	v_or3_b32 v7, v8, v7, v9
	v_lshlrev_b32_e32 v8, 5, v15
	v_ashrrev_i16_sdwa v4, v205, sext(v4) dst_sel:DWORD dst_unused:UNUSED_PAD src0_sel:DWORD src1_sel:BYTE_0
	s_add_i32 s38, s64, s16
	s_ashr_i32 s19, s18, 6
	v_and_b32_e32 v8, 32, v8
	v_bfe_i32 v17, v4, 0, 16
	s_ashr_i32 s39, s38, 31
	s_ashr_i32 s37, s36, 31
	s_ashr_i32 s20, s18, 8
	s_lshl_b32 s63, s19, 10
	v_add_lshl_u32 v4, v8, v17, 1
	s_lshl_b64 s[16:17], s[38:39], 19
	s_lshl_b64 s[22:23], s[36:37], 19
	v_lshl_add_u32 v134, v7, 11, v4
	v_lshl_add_u32 v136, v6, 11, v4
	v_and_b32_e32 v4, 0x1fffd8, v155
	s_lshr_b32 s32, s2, 3
	s_lshr_b32 s99, s2, 6
	s_add_i32 s32, s32, s99
	s_and_b32 s32, s32, 3
	s_lshl_b32 s32, s32, 8
	s_add_u32 s42, s12, s22
	v_or3_b32 v4, v154, v4, v153
	v_lshlrev_b32_e32 v5, 1, v132
	s_addc_u32 s43, s13, s23
	s_add_u32 s42, s42, s32
	s_addc_u32 s43, s43, 0
	s_add_i32 s37, s63, 0
	v_lshl_add_u32 v138, v4, 11, v5
	s_add_i32 m0, s37, 0x10000
	v_lshl_add_u32 v140, v133, 11, v5
	global_load_lds_dwordx4 v138, s[42:43]
	s_add_i32 m0, s37, 0x12000
	s_add_u32 s22, s42, 0x10000
	global_load_lds_dwordx4 v134, s[42:43]
	s_addc_u32 s23, s43, 0
	s_add_i32 m0, s37, 0x14000
	v_mov_b32_e32 v139, v2
	global_load_lds_dwordx4 v138, s[22:23]
	s_add_i32 m0, s37, 0x16000
	s_add_u32 s40, s8, s16
	s_addc_u32 s41, s9, s17
	s_add_u32 s40, s40, s32
	s_addc_u32 s41, s41, 0
	s_add_i32 s39, s37, 0x2000
	global_load_lds_dwordx4 v134, s[22:23]
	s_mov_b32 m0, s37
	s_add_u32 s16, s40, 0x40000
	global_load_lds_dwordx4 v140, s[40:41]
	s_mov_b32 m0, s39
	s_addc_u32 s17, s41, 0
	s_add_i32 s65, s37, 0x4000
	global_load_lds_dwordx4 v136, s[40:41]
	s_mov_b32 m0, s65
	s_add_i32 s66, s37, 0x6000
	global_load_lds_dwordx4 v140, s[16:17]
	s_mov_b32 m0, s66
	v_mov_b32_e32 v135, v2
	global_load_lds_dwordx4 v136, s[16:17]
	v_mov_b32_e32 v141, v2
	v_mov_b32_e32 v137, v2
	s_cmp_eq_u32 s20, 1
	v_lshl_add_u64 v[10:11], s[42:43], 0, v[138:139]
	v_lshl_add_u64 v[8:9], s[42:43], 0, v[134:135]
	v_lshl_add_u64 v[4:5], s[40:41], 0, v[140:141]
	s_cselect_b64 s[16:17], -1, 0
	s_cmp_lg_u32 s20, 1
	v_lshl_add_u64 v[6:7], s[40:41], 0, v[136:137]
	s_cbranch_scc1 .LBB0_1102
	s_barrier
.LBB0_1102:
	v_lshlrev_b32_e32 v18, 1, v151
	v_lshlrev_b32_e32 v19, 2, v152
	s_and_b32 s21, s19, 3
	v_lshl_or_b32 v18, v152, 6, v18
	s_lshl_b32 s19, s20, 13
	v_and_b32_e32 v20, 32, v19
	s_add_i32 m0, s37, 0x18000
	v_lshl_add_u64 v[10:11], v[10:11], 0, s[52:53]
	v_bitop3_b32 v21, v18, s19, v20 bitop3:0xde
	s_lshl_b32 s19, s21, 12
	s_waitcnt vmcnt(2)
	s_barrier
	global_load_lds_dwordx4 v[10:11], off
	v_lshl_add_u64 v[8:9], v[8:9], 0, s[52:53]
	s_add_i32 m0, s37, 0x1a000
	s_add_i32 s67, s37, 0x8000
	s_add_i32 s76, s37, 0xa000
	global_load_lds_dwordx4 v[8:9], off
	v_lshl_add_u64 v[4:5], v[4:5], 0, s[52:53]
	s_mov_b32 m0, s67
	s_add_u32 s22, s42, 0x10080
	global_load_lds_dwordx4 v[4:5], off
	v_lshl_add_u64 v[4:5], v[6:7], 0, s[52:53]
	s_mov_b32 m0, s76
	s_addc_u32 s23, s43, 0
	global_load_lds_dwordx4 v[4:5], off
	s_add_i32 m0, s37, 0x1c000
	v_lshl_add_u64 v[4:5], s[22:23], 0, v[138:139]
	global_load_lds_dwordx4 v[4:5], off
	v_lshl_add_u64 v[4:5], s[22:23], 0, v[134:135]
	s_add_i32 m0, s37, 0x1e000
	s_cmpk_lt_u32 s18, 0x100
	global_load_lds_dwordx4 v[4:5], off
	v_cmp_lt_u32_e32 vcc, 7, v152
	v_bitop3_b32 v157, s19, v18, v20 bitop3:0xf6
	s_cselect_b64 s[18:19], -1, 0
	s_lshl_b32 s21, s21, 6
	v_cndmask_b32_e64 v4, 0, 32, vcc
	v_or3_b32 v161, s21, v4, v151
	v_lshlrev_b32_e32 v4, 14, v12
	v_and_b32_e32 v4, 0xffff8000, v4
	v_lshl_add_u32 v4, v13, 11, v4
	v_and_b32_e32 v5, 1, v12
	v_lshl_or_b32 v4, v5, 6, v4
	v_lshl_add_u32 v142, v14, 1, v4
	v_lshlrev_b32_e32 v4, 14, v15
	v_lshl_or_b32 v156, s20, 6, v152
	s_lshl_b32 s20, s20, 8
	v_and_b32_e32 v4, 0xffff8000, v4
	s_waitcnt vmcnt(6)
	s_add_i32 s20, s20, 0
	v_lshl_add_u32 v4, v16, 11, v4
	v_and_b32_e32 v5, 1, v15
	s_add_i32 s20, s20, 0x20000
	v_lshl_or_b32 v4, v5, 6, v4
	s_mov_b32 s78, 0
	v_cndmask_b32_e64 v158, 0, -8, vcc
	v_cndmask_b32_e64 v159, 8, 0, vcc
	v_add_u32_e32 v160, s20, v19
	v_mov_b32_e32 v143, v2
	v_lshl_add_u32 v144, v17, 1, v4
	v_mov_b32_e32 v145, v2
	v_add_u32_e32 v162, 0, v21
	s_barrier
	s_sub_u32 s42, s42, s32
	s_subb_u32 s43, s43, 0
	s_sub_u32 s40, s40, s32
	s_subb_u32 s41, s41, 0
	s_branch .LBB0_1105

; #define PG8_STAGE(bufoff, gbase, voff) do { _Pragma("unroll") for (int _i = 0; _i < 2; ++_i) \
;         __builtin_amdgcn_global_load_lds((const unsigned*)((const char*)(gbase) + (voff)[_i]), (PG8_LAS unsigned*)(lds + (bufoff) + ldsw + _i * 8192), 16, 0, 0); } while (0)
; #define PG8_LDA(dst, b, h) do { _Pragma("unroll") for (int m = 0; m < 4; ++m) _Pragma("unroll") for (int k = 0; k < 2; ++k) dst[m][k] = *(const PG8_LAS bf16x8*)(lds + PG8_SA(b, h) + aoff + m * 2048 + k * 1024); } while (0)
; #define PG8_LDB(dst, b, h) do { _Pragma("unroll") for (int n = 0; n < 2; ++n) _Pragma("unroll") for (int k = 0; k < 2; ++k) dst[n][k] = *(const PG8_LAS bf16x8*)(lds + PG8_SB(b, h) + boff + n * 2048 + k * 1024); } while (0)
; #define PG8_SCHED __builtin_amdgcn_sched_barrier(0)
; template <class Epi, class Sched, bool ALIGN_EPI = false, bool SP2 = false>
; __device__ __forceinline__ void gemm_phase(PG8_LAS unsigned char* lds, const Gemm g, const Sched& S, const Epi& E, const int tid) {
;     ...
;         const char* nA = has_next ? (const char*)g.A + (size_t)nxt.pm * tstep : cA; const char* nB = has_next ? (const char*)g.Bt + (size_t)nxt.pn * tstep : cB;
;         for (int t = 0; t < nt; t += 2) {
;             const bool last = (t == nt - 2);
;             const char* a1 = cA + (size_t)(t + 1) * kstep;
;             const char* a2 = last ? nA : cA + (size_t)(t + 2) * kstep; const char* b2 = last ? nB : cB + (size_t)(t + 2) * kstep;
;             const char* a3 = a2 + kstep; const char* b3 = b2 + kstep;
;             if (last && has_next) S.a_ready(nxt);
;             if constexpr (SP2) {
;             PG8_LDB(B0, 0, 0); PG8_LDB(B1, 0, 1); PG8_SCHED; PG8_LDA(At, 0, 0); PG8_STAGE(PG8_SA(1, 1), a1 + hstep, voffA);
;     ...
;         else {
; #pragma unroll
;         for (int a = 0; a < 2; ++a)
; #pragma unroll
;             for (int b = 0; b < 2; ++b)
; #pragma unroll
;                 for (int m = 0; m < 4; ++m)
; #pragma unroll
;                     for (int n = 0; n < 2; ++n) acc[a][b][m][n] = (f32x4){0.f, 0.f, 0.f, 0.f};
;         }
.LBB0_1107:
	s_ashr_i32 s23, s22, 31
	s_lshl_b64 s[24:25], s[22:23], 19
	s_add_u32 s24, s8, s24
	s_addc_u32 s25, s9, s25
	s_and_b64 s[30:31], s[28:29], exec
	s_cselect_b32 s23, s25, s41
	s_cselect_b32 s79, s24, s40
	s_add_u32 s79, s79, s32
	s_addc_u32 s23, s23, 0
	s_ashr_i32 s21, s20, 31
	s_lshl_b64 s[30:31], s[20:21], 19
	s_add_u32 s30, s12, s30
	s_addc_u32 s31, s13, s31
	s_and_b64 s[54:55], s[28:29], exec
	s_cselect_b32 s21, s31, s43
	s_cselect_b32 s80, s30, s42
	s_add_u32 s80, s80, s32
	s_addc_u32 s21, s21, 0
	s_add_u32 s40, s40, 0x40080
	s_addc_u32 s41, s41, 0
	s_mov_b32 s81, s42
	v_mov_b32_e32 v4, 0
	s_mov_b32 s82, s43
	s_mov_b32 s83, -2
	v_mov_b32_e32 v5, v4
	v_mov_b32_e32 v6, v4
	v_mov_b32_e32 v7, v4
	v_mov_b32_e32 v8, v4
	v_mov_b32_e32 v9, v4
	v_mov_b32_e32 v10, v4
	v_mov_b32_e32 v11, v4
	v_mov_b32_e32 v20, v4
	v_mov_b32_e32 v21, v4
	v_mov_b32_e32 v22, v4
	v_mov_b32_e32 v23, v4
	v_mov_b32_e32 v24, v4
	v_mov_b32_e32 v25, v4
	v_mov_b32_e32 v26, v4
	v_mov_b32_e32 v27, v4
	v_mov_b32_e32 v36, v4
	v_mov_b32_e32 v37, v4
	v_mov_b32_e32 v38, v4
	v_mov_b32_e32 v39, v4
	v_mov_b32_e32 v40, v4
	v_mov_b32_e32 v41, v4
	v_mov_b32_e32 v42, v4
	v_mov_b32_e32 v43, v4
	v_mov_b32_e32 v52, v4
	v_mov_b32_e32 v53, v4
	v_mov_b32_e32 v54, v4
	v_mov_b32_e32 v55, v4
	v_mov_b32_e32 v56, v4
	v_mov_b32_e32 v57, v4
	v_mov_b32_e32 v58, v4
	v_mov_b32_e32 v59, v4
	v_mov_b32_e32 v12, v4
	v_mov_b32_e32 v13, v4
	v_mov_b32_e32 v14, v4
	v_mov_b32_e32 v15, v4
	v_mov_b32_e32 v16, v4
	v_mov_b32_e32 v17, v4
	v_mov_b32_e32 v18, v4
	v_mov_b32_e32 v19, v4
	v_mov_b32_e32 v28, v4
	v_mov_b32_e32 v29, v4
	v_mov_b32_e32 v30, v4
	v_mov_b32_e32 v31, v4
	v_mov_b32_e32 v32, v4
	v_mov_b32_e32 v33, v4
	v_mov_b32_e32 v34, v4
	v_mov_b32_e32 v35, v4
	v_mov_b32_e32 v44, v4
	v_mov_b32_e32 v45, v4
	v_mov_b32_e32 v46, v4
	v_mov_b32_e32 v47, v4
	v_mov_b32_e32 v48, v4
	v_mov_b32_e32 v49, v4
	v_mov_b32_e32 v50, v4
	v_mov_b32_e32 v51, v4
	v_mov_b32_e32 v60, v4
	v_mov_b32_e32 v61, v4
	v_mov_b32_e32 v62, v4
	v_mov_b32_e32 v63, v4
	v_mov_b32_e32 v64, v4
	v_mov_b32_e32 v65, v4
	v_mov_b32_e32 v66, v4
	v_mov_b32_e32 v67, v4
	v_mov_b32_e32 v68, v4
	v_mov_b32_e32 v69, v4
	v_mov_b32_e32 v70, v4
	v_mov_b32_e32 v71, v4
	v_mov_b32_e32 v72, v4
	v_mov_b32_e32 v73, v4
	v_mov_b32_e32 v74, v4
	v_mov_b32_e32 v75, v4
	v_mov_b32_e32 v84, v4
	v_mov_b32_e32 v85, v4
	v_mov_b32_e32 v86, v4
	v_mov_b32_e32 v87, v4
	v_mov_b32_e32 v88, v4
	v_mov_b32_e32 v89, v4
	v_mov_b32_e32 v90, v4
	v_mov_b32_e32 v91, v4
	v_mov_b32_e32 v100, v4
	v_mov_b32_e32 v101, v4
	v_mov_b32_e32 v102, v4
	v_mov_b32_e32 v103, v4
	v_mov_b32_e32 v104, v4
	v_mov_b32_e32 v105, v4
	v_mov_b32_e32 v106, v4
	v_mov_b32_e32 v107, v4
	v_mov_b32_e32 v116, v4
	v_mov_b32_e32 v117, v4
	v_mov_b32_e32 v118, v4
	v_mov_b32_e32 v119, v4
	v_mov_b32_e32 v120, v4
	v_mov_b32_e32 v121, v4
	v_mov_b32_e32 v122, v4
	v_mov_b32_e32 v123, v4
	v_mov_b32_e32 v76, v4
	v_mov_b32_e32 v77, v4
	v_mov_b32_e32 v78, v4
	v_mov_b32_e32 v79, v4
	v_mov_b32_e32 v80, v4
	v_mov_b32_e32 v81, v4
	v_mov_b32_e32 v82, v4
	v_mov_b32_e32 v83, v4
	v_mov_b32_e32 v92, v4
	v_mov_b32_e32 v93, v4
	v_mov_b32_e32 v94, v4
	v_mov_b32_e32 v95, v4
	v_mov_b32_e32 v96, v4
	v_mov_b32_e32 v97, v4
	v_mov_b32_e32 v98, v4
	v_mov_b32_e32 v99, v4
	v_mov_b32_e32 v108, v4
	v_mov_b32_e32 v109, v4
	v_mov_b32_e32 v110, v4
	v_mov_b32_e32 v111, v4
	v_mov_b32_e32 v112, v4
	v_mov_b32_e32 v113, v4
	v_mov_b32_e32 v114, v4
	v_mov_b32_e32 v115, v4
	v_mov_b32_e32 v124, v4
	v_mov_b32_e32 v125, v4
	v_mov_b32_e32 v126, v4
	v_mov_b32_e32 v127, v4
	v_mov_b32_e32 v128, v4
	v_mov_b32_e32 v129, v4
	v_mov_b32_e32 v130, v4
	v_mov_b32_e32 v131, v4
.LBB0_1108:
	s_lshl_b32 s100, s83, 7
	s_add_i32 s100, s100, s32
	s_add_i32 s100, s100, 0x100
	s_add_i32 s99, s100, 0x100
	s_and_b32 s100, s100, 0x700
	s_and_b32 s99, s99, 0x700
	s_add_u32 s100, s40, s100
	s_addc_u32 s101, s41, 0
	s_add_u32 s42, s40, 0xfffbff80
	s_addc_u32 s43, s41, -1
	s_add_u32 s42, s42, s99
	s_addc_u32 s43, s43, 0
	s_add_i32 s84, 0, 0x10000
	s_cmp_eq_u32 s83, 12
	s_cselect_b32 s55, s23, s43
	s_cselect_b32 s54, s79, s42
	v_add_u32_e32 v163, s84, v157
	s_add_u32 s42, s81, s99
	s_addc_u32 s43, s82, 0
	s_cmp_eq_u32 s83, 12
	s_cselect_b32 s43, s21, s43
	s_cselect_b32 s42, s80, s42
	s_add_i32 s86, 0, 0x14000
	ds_read_b128 v[146:149], v163
	ds_read_b128 v[164:167], v163 offset:1024
	ds_read_b128 v[170:173], v163 offset:2048
	ds_read_b128 v[174:177], v163 offset:3072
	v_add_u32_e32 v163, s86, v157
	ds_read_b128 v[178:181], v163
	ds_read_b128 v[182:185], v163 offset:1024
	ds_read_b128 v[186:189], v163 offset:2048
	ds_read_b128 v[190:193], v163 offset:3072
	v_lshl_add_u64 v[236:237], s[100:101], 0, v[142:143]
	s_add_i32 m0, s37, 0xc000
	ds_read_b128 v[194:197], v162
	ds_read_b128 v[198:201], v162 offset:1024
	ds_read_b128 v[212:215], v162 offset:2048
	ds_read_b128 v[216:219], v162 offset:3072
	ds_read_b128 v[220:223], v162 offset:4096
	ds_read_b128 v[224:227], v162 offset:5120
	ds_read_b128 v[228:231], v162 offset:6144
	ds_read_b128 v[232:235], v162 offset:7168
	global_load_lds_dwordx4 v[236:237], off
	v_lshl_add_u64 v[236:237], s[100:101], 0, v[144:145]
	s_add_i32 m0, s37, 0xe000
	s_nop 0
	global_load_lds_dwordx4 v[236:237], off
	s_waitcnt vmcnt(8)
	s_waitcnt lgkmcnt(0)
	s_barrier
; #define PG8_STAGE(bufoff, gbase, voff) do { _Pragma("unroll") for (int _i = 0; _i < 2; ++_i) \
;         __builtin_amdgcn_global_load_lds((const unsigned*)((const char*)(gbase) + (voff)[_i]), (PG8_LAS unsigned*)(lds + (bufoff) + ldsw + _i * 8192), 16, 0, 0); } while (0)
; #define PG8_LDA(dst, b, h) do { _Pragma("unroll") for (int m = 0; m < 4; ++m) _Pragma("unroll") for (int k = 0; k < 2; ++k) dst[m][k] = *(const PG8_LAS bf16x8*)(lds + PG8_SA(b, h) + aoff + m * 2048 + k * 1024); } while (0)
; #define PG8_LDB(dst, b, h) do { _Pragma("unroll") for (int n = 0; n < 2; ++n) _Pragma("unroll") for (int k = 0; k < 2; ++k) dst[n][k] = *(const PG8_LAS bf16x8*)(lds + PG8_SB(b, h) + boff + n * 2048 + k * 1024); } while (0)
; #define PG8_MMA(ai, bj, At, Bt) do { __builtin_amdgcn_s_setprio(1); _Pragma("unroll") for (int m = 0; m < 4; ++m) _Pragma("unroll") for (int n = 0; n < 2; ++n) _Pragma("unroll") for (int k = 0; k < 2; ++k) \
;         acc[ai][bj][m][n] = __builtin_amdgcn_mfma_f32_16x16x32_bf16(Bt[n][k], At[m][k], acc[ai][bj][m][n], 0, 0, 0); __builtin_amdgcn_s_setprio(0); } while (0)
; #define PG8_WAIT_V(n) asm volatile("s_waitcnt vmcnt(" #n ")" ::: "memory")
; #define PG8_WAIT_L(n) asm volatile("s_waitcnt lgkmcnt(" #n ")" ::: "memory")
; #define PG8_BAR __builtin_amdgcn_s_barrier()
; #define PG8_SCHED __builtin_amdgcn_sched_barrier(0)
; template <class Epi, class Sched, bool ALIGN_EPI = false, bool SP2 = false>
; __device__ __forceinline__ void gemm_phase(PG8_LAS unsigned char* lds, const Gemm g, const Sched& S, const Epi& E, const int tid) {
;     ...
;             PG8_LDB(B0, 0, 0); PG8_LDB(B1, 0, 1); PG8_SCHED; PG8_LDA(At, 0, 0); PG8_STAGE(PG8_SA(1, 1), a1 + hstep, voffA);
;             PG8_WAIT_V(8); PG8_WAIT_L(0); PG8_BAR; PG8_MMA(0, 0, At, B0); PG8_MMA(0, 1, At, B1); PG8_BAR; PG8_SCHED;
;             PG8_LDA(At, 0, 1); PG8_STAGE(PG8_SB(0, 0), b2, voffB); PG8_STAGE(PG8_SB(0, 1), b2 + hstepB, voffB); PG8_STAGE(PG8_SA(0, 0), a2, voffA);
;             PG8_WAIT_V(8); PG8_WAIT_L(0); PG8_BAR; PG8_MMA(1, 0, At, B0); PG8_MMA(1, 1, At, B1); PG8_BAR; PG8_SCHED;
	s_setprio 1
	s_waitcnt lgkmcnt(0)
	v_mfma_f32_16x16x32_bf16 v[128:131], v[146:149], v[194:197], v[128:131]
	v_mfma_f32_16x16x32_bf16 v[124:127], v[170:173], v[194:197], v[124:127]
	v_mfma_f32_16x16x32_bf16 v[112:115], v[146:149], v[212:215], v[112:115]
	v_mfma_f32_16x16x32_bf16 v[108:111], v[170:173], v[212:215], v[108:111]
	v_mfma_f32_16x16x32_bf16 v[96:99], v[146:149], v[220:223], v[96:99]
	v_mfma_f32_16x16x32_bf16 v[92:95], v[170:173], v[220:223], v[92:95]
	v_mfma_f32_16x16x32_bf16 v[80:83], v[146:149], v[228:231], v[80:83]
	v_mfma_f32_16x16x32_bf16 v[76:79], v[170:173], v[228:231], v[76:79]
	v_mfma_f32_16x16x32_bf16 v[128:131], v[164:167], v[198:201], v[128:131]
	v_mfma_f32_16x16x32_bf16 v[124:127], v[174:177], v[198:201], v[124:127]
	v_mfma_f32_16x16x32_bf16 v[112:115], v[164:167], v[216:219], v[112:115]
	v_mfma_f32_16x16x32_bf16 v[108:111], v[174:177], v[216:219], v[108:111]
	v_mfma_f32_16x16x32_bf16 v[96:99], v[164:167], v[224:227], v[96:99]
	v_mfma_f32_16x16x32_bf16 v[92:95], v[174:177], v[224:227], v[92:95]
	v_mfma_f32_16x16x32_bf16 v[80:83], v[164:167], v[232:235], v[80:83]
	v_mfma_f32_16x16x32_bf16 v[76:79], v[174:177], v[232:235], v[76:79]
	s_setprio 0
	s_setprio 1
	v_mfma_f32_16x16x32_bf16 v[120:123], v[178:181], v[194:197], v[120:123]
	v_mfma_f32_16x16x32_bf16 v[116:119], v[186:189], v[194:197], v[116:119]
	v_mfma_f32_16x16x32_bf16 v[104:107], v[178:181], v[212:215], v[104:107]
	v_mfma_f32_16x16x32_bf16 v[100:103], v[186:189], v[212:215], v[100:103]
	v_mfma_f32_16x16x32_bf16 v[88:91], v[178:181], v[220:223], v[88:91]
	v_mfma_f32_16x16x32_bf16 v[84:87], v[186:189], v[220:223], v[84:87]
	v_mfma_f32_16x16x32_bf16 v[72:75], v[178:181], v[228:231], v[72:75]
	v_mfma_f32_16x16x32_bf16 v[68:71], v[186:189], v[228:231], v[68:71]
	v_mfma_f32_16x16x32_bf16 v[120:123], v[182:185], v[198:201], v[120:123]
	v_mfma_f32_16x16x32_bf16 v[116:119], v[190:193], v[198:201], v[116:119]
	v_mfma_f32_16x16x32_bf16 v[104:107], v[182:185], v[216:219], v[104:107]
	v_mfma_f32_16x16x32_bf16 v[100:103], v[190:193], v[216:219], v[100:103]
	v_mfma_f32_16x16x32_bf16 v[88:91], v[182:185], v[224:227], v[88:91]
	v_mfma_f32_16x16x32_bf16 v[84:87], v[190:193], v[224:227], v[84:87]
	v_mfma_f32_16x16x32_bf16 v[72:75], v[182:185], v[232:235], v[72:75]
	v_mfma_f32_16x16x32_bf16 v[68:71], v[190:193], v[232:235], v[68:71]
	s_setprio 0
	s_barrier
	s_add_i32 s84, s84, s63
	v_lshl_add_u64 v[236:237], s[42:43], 0, v[138:139]
	s_mov_b32 m0, s84
	ds_read_b128 v[194:197], v162 offset:16384
	ds_read_b128 v[198:201], v162 offset:17408
	ds_read_b128 v[212:215], v162 offset:18432
	ds_read_b128 v[216:219], v162 offset:19456
	ds_read_b128 v[220:223], v162 offset:20480
	ds_read_b128 v[224:227], v162 offset:21504
	ds_read_b128 v[228:231], v162 offset:22528
	ds_read_b128 v[232:235], v162 offset:23552
	global_load_lds_dwordx4 v[236:237], off
	s_add_i32 m0, s84, 0x2000
	s_add_u32 s84, s42, 0x10000
	v_lshl_add_u64 v[238:239], s[42:43], 0, v[134:135]
	s_addc_u32 s85, s43, 0
	s_add_i32 s86, s86, s63
	global_load_lds_dwordx4 v[238:239], off
	v_lshl_add_u64 v[240:241], s[84:85], 0, v[138:139]
	s_mov_b32 m0, s86
	v_lshl_add_u64 v[242:243], s[54:55], 0, v[136:137]
	global_load_lds_dwordx4 v[240:241], off
	v_lshl_add_u64 v[240:241], s[84:85], 0, v[134:135]
	s_add_i32 m0, s86, 0x2000
	s_nop 0
	global_load_lds_dwordx4 v[240:241], off
	v_lshl_add_u64 v[240:241], s[54:55], 0, v[140:141]
	s_mov_b32 m0, s37
	s_nop 0
	global_load_lds_dwordx4 v[240:241], off
	s_mov_b32 m0, s39
	s_nop 0
	global_load_lds_dwordx4 v[242:243], off
	s_waitcnt vmcnt(8)
	s_waitcnt lgkmcnt(0)
	s_barrier
	s_setprio 1
	s_waitcnt lgkmcnt(0)
	v_mfma_f32_16x16x32_bf16 v[64:67], v[146:149], v[194:197], v[64:67]
	v_mfma_f32_16x16x32_bf16 v[60:63], v[170:173], v[194:197], v[60:63]
	v_mfma_f32_16x16x32_bf16 v[48:51], v[146:149], v[212:215], v[48:51]
	v_mfma_f32_16x16x32_bf16 v[44:47], v[170:173], v[212:215], v[44:47]
	v_mfma_f32_16x16x32_bf16 v[32:35], v[146:149], v[220:223], v[32:35]
	v_mfma_f32_16x16x32_bf16 v[28:31], v[170:173], v[220:223], v[28:31]
	v_mfma_f32_16x16x32_bf16 v[16:19], v[146:149], v[228:231], v[16:19]
	v_mfma_f32_16x16x32_bf16 v[12:15], v[170:173], v[228:231], v[12:15]
	v_mfma_f32_16x16x32_bf16 v[64:67], v[164:167], v[198:201], v[64:67]
	v_mfma_f32_16x16x32_bf16 v[60:63], v[174:177], v[198:201], v[60:63]
	v_mfma_f32_16x16x32_bf16 v[48:51], v[164:167], v[216:219], v[48:51]
	v_mfma_f32_16x16x32_bf16 v[44:47], v[174:177], v[216:219], v[44:47]
	v_mfma_f32_16x16x32_bf16 v[32:35], v[164:167], v[224:227], v[32:35]
	v_mfma_f32_16x16x32_bf16 v[28:31], v[174:177], v[224:227], v[28:31]
	v_mfma_f32_16x16x32_bf16 v[16:19], v[164:167], v[232:235], v[16:19]
	v_mfma_f32_16x16x32_bf16 v[12:15], v[174:177], v[232:235], v[12:15]
	s_setprio 0
	s_setprio 1
	v_mfma_f32_16x16x32_bf16 v[56:59], v[178:181], v[194:197], v[56:59]
	v_mfma_f32_16x16x32_bf16 v[52:55], v[186:189], v[194:197], v[52:55]
	v_mfma_f32_16x16x32_bf16 v[40:43], v[178:181], v[212:215], v[40:43]
	v_mfma_f32_16x16x32_bf16 v[36:39], v[186:189], v[212:215], v[36:39]
	v_mfma_f32_16x16x32_bf16 v[24:27], v[178:181], v[220:223], v[24:27]
	v_mfma_f32_16x16x32_bf16 v[20:23], v[186:189], v[220:223], v[20:23]
	v_mfma_f32_16x16x32_bf16 v[8:11], v[178:181], v[228:231], v[8:11]
	v_mfma_f32_16x16x32_bf16 v[4:7], v[186:189], v[228:231], v[4:7]
	v_mfma_f32_16x16x32_bf16 v[56:59], v[182:185], v[198:201], v[56:59]
	v_mfma_f32_16x16x32_bf16 v[52:55], v[190:193], v[198:201], v[52:55]
	v_mfma_f32_16x16x32_bf16 v[40:43], v[182:185], v[216:219], v[40:43]
	v_mfma_f32_16x16x32_bf16 v[36:39], v[190:193], v[216:219], v[36:39]
	v_mfma_f32_16x16x32_bf16 v[24:27], v[182:185], v[224:227], v[24:27]
	v_mfma_f32_16x16x32_bf16 v[20:23], v[190:193], v[224:227], v[20:23]
	v_mfma_f32_16x16x32_bf16 v[8:11], v[182:185], v[232:235], v[8:11]
	v_mfma_f32_16x16x32_bf16 v[4:7], v[190:193], v[232:235], v[4:7]
	s_setprio 0
	s_barrier
; #define PG8_STAGE(bufoff, gbase, voff) do { _Pragma("unroll") for (int _i = 0; _i < 2; ++_i) \
;         __builtin_amdgcn_global_load_lds((const unsigned*)((const char*)(gbase) + (voff)[_i]), (PG8_LAS unsigned*)(lds + (bufoff) + ldsw + _i * 8192), 16, 0, 0); } while (0)
; #define PG8_LDA(dst, b, h) do { _Pragma("unroll") for (int m = 0; m < 4; ++m) _Pragma("unroll") for (int k = 0; k < 2; ++k) dst[m][k] = *(const PG8_LAS bf16x8*)(lds + PG8_SA(b, h) + aoff + m * 2048 + k * 1024); } while (0)
; #define PG8_LDB(dst, b, h) do { _Pragma("unroll") for (int n = 0; n < 2; ++n) _Pragma("unroll") for (int k = 0; k < 2; ++k) dst[n][k] = *(const PG8_LAS bf16x8*)(lds + PG8_SB(b, h) + boff + n * 2048 + k * 1024); } while (0)
; #define PG8_MMA(ai, bj, At, Bt) do { __builtin_amdgcn_s_setprio(1); _Pragma("unroll") for (int m = 0; m < 4; ++m) _Pragma("unroll") for (int n = 0; n < 2; ++n) _Pragma("unroll") for (int k = 0; k < 2; ++k) \
;         acc[ai][bj][m][n] = __builtin_amdgcn_mfma_f32_16x16x32_bf16(Bt[n][k], At[m][k], acc[ai][bj][m][n], 0, 0, 0); __builtin_amdgcn_s_setprio(0); } while (0)
; #define PG8_WAIT_V(n) asm volatile("s_waitcnt vmcnt(" #n ")" ::: "memory")
; #define PG8_WAIT_L(n) asm volatile("s_waitcnt lgkmcnt(" #n ")" ::: "memory")
; #define PG8_BAR __builtin_amdgcn_s_barrier()
; #define PG8_SCHED __builtin_amdgcn_sched_barrier(0)
; template <class Epi, class Sched, bool ALIGN_EPI = false, bool SP2 = false>
; __device__ __forceinline__ void gemm_phase(PG8_LAS unsigned char* lds, const Gemm g, const Sched& S, const Epi& E, const int tid) {
;     ...
;             PG8_LDA(At, 0, 1); PG8_STAGE(PG8_SB(0, 0), b2, voffB); PG8_STAGE(PG8_SB(0, 1), b2 + hstepB, voffB); PG8_STAGE(PG8_SA(0, 0), a2, voffA);
;             PG8_WAIT_V(8); PG8_WAIT_L(0); PG8_BAR; PG8_MMA(1, 0, At, B0); PG8_MMA(1, 1, At, B1); PG8_BAR; PG8_SCHED;
;             PG8_LDB(B0, 1, 0); PG8_LDB(B1, 1, 1); PG8_SCHED; PG8_LDA(At, 1, 0); PG8_STAGE(PG8_SA(0, 1), a2 + hstep, voffA);
;             PG8_WAIT_V(8); PG8_WAIT_L(0); PG8_BAR; PG8_MMA(0, 0, At, B0); PG8_MMA(0, 1, At, B1); PG8_BAR; PG8_SCHED;
	s_add_i32 s84, 0, 0x18000
	v_add_u32_e32 v163, s84, v157
	s_add_i32 s85, 0, 0x1c000
	ds_read_b128 v[146:149], v163
	ds_read_b128 v[164:167], v163 offset:1024
	ds_read_b128 v[170:173], v163 offset:2048
	ds_read_b128 v[174:177], v163 offset:3072
	v_add_u32_e32 v163, s85, v157
	ds_read_b128 v[178:181], v163
	ds_read_b128 v[182:185], v163 offset:1024
	ds_read_b128 v[186:189], v163 offset:2048
	ds_read_b128 v[190:193], v163 offset:3072
	s_add_u32 s54, s54, 0x40000
	s_addc_u32 s55, s55, 0
	s_mov_b32 m0, s65
	v_lshl_add_u64 v[244:245], s[54:55], 0, v[140:141]
	ds_read_b128 v[194:197], v162 offset:32768
	ds_read_b128 v[198:201], v162 offset:33792
	ds_read_b128 v[212:215], v162 offset:34816
	ds_read_b128 v[216:219], v162 offset:35840
	ds_read_b128 v[220:223], v162 offset:36864
	ds_read_b128 v[224:227], v162 offset:37888
	ds_read_b128 v[228:231], v162 offset:38912
	ds_read_b128 v[232:235], v162 offset:39936
	global_load_lds_dwordx4 v[244:245], off
	v_lshl_add_u64 v[244:245], s[54:55], 0, v[136:137]
	s_mov_b32 m0, s66
	s_nop 0
	global_load_lds_dwordx4 v[244:245], off
	s_waitcnt vmcnt(8)
	s_waitcnt lgkmcnt(0)
	s_barrier
	s_setprio 1
	s_waitcnt lgkmcnt(0)
	v_mfma_f32_16x16x32_bf16 v[128:131], v[146:149], v[194:197], v[128:131]
	v_mfma_f32_16x16x32_bf16 v[124:127], v[170:173], v[194:197], v[124:127]
	v_mfma_f32_16x16x32_bf16 v[112:115], v[146:149], v[212:215], v[112:115]
	v_mfma_f32_16x16x32_bf16 v[108:111], v[170:173], v[212:215], v[108:111]
	v_mfma_f32_16x16x32_bf16 v[96:99], v[146:149], v[220:223], v[96:99]
	v_mfma_f32_16x16x32_bf16 v[92:95], v[170:173], v[220:223], v[92:95]
	v_mfma_f32_16x16x32_bf16 v[80:83], v[146:149], v[228:231], v[80:83]
	v_mfma_f32_16x16x32_bf16 v[76:79], v[170:173], v[228:231], v[76:79]
	v_mfma_f32_16x16x32_bf16 v[128:131], v[164:167], v[198:201], v[128:131]
	v_mfma_f32_16x16x32_bf16 v[124:127], v[174:177], v[198:201], v[124:127]
	v_mfma_f32_16x16x32_bf16 v[112:115], v[164:167], v[216:219], v[112:115]
	v_mfma_f32_16x16x32_bf16 v[108:111], v[174:177], v[216:219], v[108:111]
	v_mfma_f32_16x16x32_bf16 v[96:99], v[164:167], v[224:227], v[96:99]
	v_mfma_f32_16x16x32_bf16 v[92:95], v[174:177], v[224:227], v[92:95]
	v_mfma_f32_16x16x32_bf16 v[80:83], v[164:167], v[232:235], v[80:83]
	v_mfma_f32_16x16x32_bf16 v[76:79], v[174:177], v[232:235], v[76:79]
	s_setprio 0
	s_setprio 1
	v_mfma_f32_16x16x32_bf16 v[120:123], v[178:181], v[194:197], v[120:123]
	v_mfma_f32_16x16x32_bf16 v[116:119], v[186:189], v[194:197], v[116:119]
	v_mfma_f32_16x16x32_bf16 v[104:107], v[178:181], v[212:215], v[104:107]
	v_mfma_f32_16x16x32_bf16 v[100:103], v[186:189], v[212:215], v[100:103]
	v_mfma_f32_16x16x32_bf16 v[88:91], v[178:181], v[220:223], v[88:91]
	v_mfma_f32_16x16x32_bf16 v[84:87], v[186:189], v[220:223], v[84:87]
	v_mfma_f32_16x16x32_bf16 v[72:75], v[178:181], v[228:231], v[72:75]
	v_mfma_f32_16x16x32_bf16 v[68:71], v[186:189], v[228:231], v[68:71]
	v_mfma_f32_16x16x32_bf16 v[120:123], v[182:185], v[198:201], v[120:123]
	v_mfma_f32_16x16x32_bf16 v[116:119], v[190:193], v[198:201], v[116:119]
	v_mfma_f32_16x16x32_bf16 v[104:107], v[182:185], v[216:219], v[104:107]
	v_mfma_f32_16x16x32_bf16 v[100:103], v[190:193], v[216:219], v[100:103]
	v_mfma_f32_16x16x32_bf16 v[88:91], v[182:185], v[224:227], v[88:91]
	v_mfma_f32_16x16x32_bf16 v[84:87], v[190:193], v[224:227], v[84:87]
	v_mfma_f32_16x16x32_bf16 v[72:75], v[182:185], v[232:235], v[72:75]
	v_mfma_f32_16x16x32_bf16 v[68:71], v[190:193], v[232:235], v[68:71]
	s_setprio 0
	s_barrier
; #define PG8_STAGE(bufoff, gbase, voff) do { _Pragma("unroll") for (int _i = 0; _i < 2; ++_i) \
;         __builtin_amdgcn_global_load_lds((const unsigned*)((const char*)(gbase) + (voff)[_i]), (PG8_LAS unsigned*)(lds + (bufoff) + ldsw + _i * 8192), 16, 0, 0); } while (0)
; #define PG8_LDA(dst, b, h) do { _Pragma("unroll") for (int m = 0; m < 4; ++m) _Pragma("unroll") for (int k = 0; k < 2; ++k) dst[m][k] = *(const PG8_LAS bf16x8*)(lds + PG8_SA(b, h) + aoff + m * 2048 + k * 1024); } while (0)
; #define PG8_LDB(dst, b, h) do { _Pragma("unroll") for (int n = 0; n < 2; ++n) _Pragma("unroll") for (int k = 0; k < 2; ++k) dst[n][k] = *(const PG8_LAS bf16x8*)(lds + PG8_SB(b, h) + boff + n * 2048 + k * 1024); } while (0)
; #define PG8_MMA(ai, bj, At, Bt) do { __builtin_amdgcn_s_setprio(1); _Pragma("unroll") for (int m = 0; m < 4; ++m) _Pragma("unroll") for (int n = 0; n < 2; ++n) _Pragma("unroll") for (int k = 0; k < 2; ++k) \
;         acc[ai][bj][m][n] = __builtin_amdgcn_mfma_f32_16x16x32_bf16(Bt[n][k], At[m][k], acc[ai][bj][m][n], 0, 0, 0); __builtin_amdgcn_s_setprio(0); } while (0)
; #define PG8_WAIT_V(n) asm volatile("s_waitcnt vmcnt(" #n ")" ::: "memory")
; #define PG8_WAIT_L(n) asm volatile("s_waitcnt lgkmcnt(" #n ")" ::: "memory")
; #define PG8_BAR __builtin_amdgcn_s_barrier()
; #define PG8_SCHED __builtin_amdgcn_sched_barrier(0)
; template <class Epi, class Sched, bool ALIGN_EPI = false, bool SP2 = false>
; __device__ __forceinline__ void gemm_phase(PG8_LAS unsigned char* lds, const Gemm g, const Sched& S, const Epi& E, const int tid) {
;     ...
;             PG8_WAIT_V(8); PG8_WAIT_L(0); PG8_BAR; PG8_MMA(1, 0, At, B0); PG8_MMA(1, 1, At, B1); PG8_BAR; PG8_SCHED;
;             PG8_LDB(B0, 1, 0); PG8_LDB(B1, 1, 1); PG8_SCHED; PG8_LDA(At, 1, 0); PG8_STAGE(PG8_SA(0, 1), a2 + hstep, voffA);
;             PG8_WAIT_V(8); PG8_WAIT_L(0); PG8_BAR; PG8_MMA(0, 0, At, B0); PG8_MMA(0, 1, At, B1); PG8_BAR; PG8_SCHED;
;             PG8_LDA(At, 1, 1); PG8_STAGE(PG8_SB(1, 0), b3, voffB); PG8_STAGE(PG8_SB(1, 1), b3 + hstepB, voffB); PG8_STAGE(PG8_SA(1, 0), a3, voffA);
;             PG8_WAIT_V(8); PG8_WAIT_L(0); PG8_BAR; PG8_MMA(1, 0, At, B0); PG8_MMA(1, 1, At, B1); PG8_BAR; PG8_SCHED;
	s_add_i32 s54, s84, s63
	v_lshl_add_u64 v[236:237], v[236:237], 0, s[52:53]
	s_mov_b32 m0, s54
	ds_read_b128 v[194:197], v162 offset:49152
	ds_read_b128 v[198:201], v162 offset:50176
	ds_read_b128 v[212:215], v162 offset:51200
	ds_read_b128 v[216:219], v162 offset:52224
	ds_read_b128 v[220:223], v162 offset:53248
	ds_read_b128 v[224:227], v162 offset:54272
	ds_read_b128 v[228:231], v162 offset:55296
	ds_read_b128 v[232:235], v162 offset:56320
	global_load_lds_dwordx4 v[236:237], off
	s_add_i32 m0, s54, 0x2000
	s_add_u32 s42, s42, 0x10080
	v_lshl_add_u64 v[236:237], v[238:239], 0, s[52:53]
	s_addc_u32 s43, s43, 0
	s_add_i32 s54, s85, s63
	global_load_lds_dwordx4 v[236:237], off
	v_lshl_add_u64 v[236:237], s[42:43], 0, v[138:139]
	s_mov_b32 m0, s54
	s_nop 0
	global_load_lds_dwordx4 v[236:237], off
	v_lshl_add_u64 v[236:237], s[42:43], 0, v[134:135]
	s_add_i32 m0, s54, 0x2000
	s_nop 0
	global_load_lds_dwordx4 v[236:237], off
	v_lshl_add_u64 v[236:237], v[240:241], 0, s[52:53]
	s_mov_b32 m0, s67
	s_nop 0
	global_load_lds_dwordx4 v[236:237], off
	v_lshl_add_u64 v[236:237], v[242:243], 0, s[52:53]
	s_mov_b32 m0, s76
	s_nop 0
	global_load_lds_dwordx4 v[236:237], off
	s_waitcnt vmcnt(8)
	s_waitcnt lgkmcnt(0)
	s_barrier
	s_setprio 1
	s_waitcnt lgkmcnt(0)
	v_mfma_f32_16x16x32_bf16 v[64:67], v[146:149], v[194:197], v[64:67]
	v_mfma_f32_16x16x32_bf16 v[60:63], v[170:173], v[194:197], v[60:63]
	v_mfma_f32_16x16x32_bf16 v[48:51], v[146:149], v[212:215], v[48:51]
	v_mfma_f32_16x16x32_bf16 v[44:47], v[170:173], v[212:215], v[44:47]
	v_mfma_f32_16x16x32_bf16 v[32:35], v[146:149], v[220:223], v[32:35]
	v_mfma_f32_16x16x32_bf16 v[28:31], v[170:173], v[220:223], v[28:31]
	v_mfma_f32_16x16x32_bf16 v[16:19], v[146:149], v[228:231], v[16:19]
	v_mfma_f32_16x16x32_bf16 v[12:15], v[170:173], v[228:231], v[12:15]
	v_mfma_f32_16x16x32_bf16 v[64:67], v[164:167], v[198:201], v[64:67]
	v_mfma_f32_16x16x32_bf16 v[60:63], v[174:177], v[198:201], v[60:63]
	v_mfma_f32_16x16x32_bf16 v[48:51], v[164:167], v[216:219], v[48:51]
	v_mfma_f32_16x16x32_bf16 v[44:47], v[174:177], v[216:219], v[44:47]
	v_mfma_f32_16x16x32_bf16 v[32:35], v[164:167], v[224:227], v[32:35]
	v_mfma_f32_16x16x32_bf16 v[28:31], v[174:177], v[224:227], v[28:31]
	v_mfma_f32_16x16x32_bf16 v[16:19], v[164:167], v[232:235], v[16:19]
	v_mfma_f32_16x16x32_bf16 v[12:15], v[174:177], v[232:235], v[12:15]
	s_setprio 0
	s_setprio 1
	v_mfma_f32_16x16x32_bf16 v[56:59], v[178:181], v[194:197], v[56:59]
	v_mfma_f32_16x16x32_bf16 v[52:55], v[186:189], v[194:197], v[52:55]
	v_mfma_f32_16x16x32_bf16 v[40:43], v[178:181], v[212:215], v[40:43]
	v_mfma_f32_16x16x32_bf16 v[36:39], v[186:189], v[212:215], v[36:39]
	v_mfma_f32_16x16x32_bf16 v[24:27], v[178:181], v[220:223], v[24:27]
	v_mfma_f32_16x16x32_bf16 v[20:23], v[186:189], v[220:223], v[20:23]
	v_mfma_f32_16x16x32_bf16 v[8:11], v[178:181], v[228:231], v[8:11]
	v_mfma_f32_16x16x32_bf16 v[4:7], v[186:189], v[228:231], v[4:7]
	v_mfma_f32_16x16x32_bf16 v[56:59], v[182:185], v[198:201], v[56:59]
	v_mfma_f32_16x16x32_bf16 v[52:55], v[190:193], v[198:201], v[52:55]
	v_mfma_f32_16x16x32_bf16 v[40:43], v[182:185], v[216:219], v[40:43]
	v_mfma_f32_16x16x32_bf16 v[36:39], v[190:193], v[216:219], v[36:39]
	v_mfma_f32_16x16x32_bf16 v[24:27], v[182:185], v[224:227], v[24:27]
	v_mfma_f32_16x16x32_bf16 v[20:23], v[190:193], v[224:227], v[20:23]
	v_mfma_f32_16x16x32_bf16 v[8:11], v[182:185], v[232:235], v[8:11]
	v_mfma_f32_16x16x32_bf16 v[4:7], v[190:193], v[232:235], v[4:7]
	s_setprio 0
	s_barrier
	s_add_i32 s83, s83, 2
	s_cmp_gt_u32 s83, 13
	s_cbranch_scc0 .LBB0_1108
	s_and_b64 vcc, exec, s[18:19]
	s_cbranch_vccz .LBB0_1111
	s_barrier

; #define PG8_BAR __builtin_amdgcn_s_barrier()
;     DI void init_issue(u32x4 (&w)[R8::HAS_PRE ? 16 : 1], const Unit& u, int wr, int wc, int fr, int fq) const {
;         if constexpr (R8::HAS_PRE) {
;             const int row0 = u.pm * BM + wr * 64 + fr, col0 = u.pn * BM + (PERM ? wc * 64 : wc * 32) + 8 * fq;
; #pragma unroll
;             for (int ai = 0; ai < 2; ++ai)
; #pragma unroll
;                 for (int m = 0; m < 4; ++m)
; #pragma unroll
;                     for (int bj = 0; bj < 2; ++bj) w[(ai * 4 + m) * 2 + bj] = e.pre(row0 + ai * HALF + m * 16, col0 + bj * (PERM ? 32 : HALF));
;         }
; template <class Epi, class Sched, bool ALIGN_EPI = false, bool SP2 = false>
; __device__ __forceinline__ void gemm_phase(PG8_LAS unsigned char* lds, const Gemm g, const Sched& S, const Epi& E, const int tid) {
;     ...
;     for (int i = 0; i < 2; ++i) { int R, C; stage_rc(tid * 16 + i * 8192, R, C); const int Rb = Epi::PERM ? (2 * (R & ~31) + perm32(R & 31)) : R;
;         voffA[i] = (unsigned)(R * K + C) * 2u; voffB[i] = (unsigned)(Rb * K + C) * 2u; }
;     const size_t kstep = (size_t)(BK * 2);
;     const size_t hstep = (size_t)HALF * K * 2;
;     const size_t tstep = 2 * hstep;
;     const size_t hstepB = Epi::PERM ? (size_t)32 * K * 2 : hstep;
;     const unsigned ldsw = (unsigned)wid * 1024u;
;     const int aoff = lds_byte(wr * 64 + fr, fq * 8), boff = lds_byte(wc * 32 + fr, fq * 8);
;     ...
;     Unit cur, nxt; int ui = 0;
;     if (!S.next(0, cur)) return;
;     f32x4 acc[2][2][4][2];
;     u32x4 iw_[Epi::HAS_INIT ? 16 : 1];
;     if constexpr (Epi::HAS_INIT) E.init_issue(iw_, cur, wr, wc, fr, fq);
;     else {
; #pragma unroll
;     for (int a = 0; a < 2; ++a)
; #pragma unroll
;         for (int b = 0; b < 2; ++b)
; #pragma unroll
;             for (int m = 0; m < 4; ++m)
; #pragma unroll
;                 for (int n = 0; n < 2; ++n) acc[a][b][m][n] = (f32x4){0.f, 0.f, 0.f, 0.f};
;     }
;     bf16x8 At[4][2], B0[2][2], B1[2][2];
;     const char* cA = (const char*)g.A + (size_t)cur.pm * tstep; const char* cB = (const char*)g.Bt + (size_t)cur.pn * tstep;
;     S.a_ready(cur);
;     if constexpr (SP2) {
;         PG8_STAGE(PG8_SB(0, 0), cB, voffB); PG8_STAGE(PG8_SB(0, 1), cB + hstepB, voffB); PG8_STAGE(PG8_SA(0, 0), cA, voffA); PG8_STAGE(PG8_SA(0, 1), cA + hstep, voffA);
;         if (wr == 1) PG8_BAR;
;         PG8_WAIT_V(2); PG8_BAR;
.LBB0_1257:
	v_ashrrev_i32_e32 v5, 31, v3
	v_lshrrev_b32_e32 v5, 26, v5
	v_add_u32_e32 v5, v3, v5
	v_ashrrev_i32_e32 v142, 6, v5
	v_bfe_i32 v5, v3, 27, 1
	v_lshlrev_b32_e32 v4, 4, v3
	v_lshrrev_b32_e32 v5, 22, v5
	v_add_u32_e32 v5, v4, v5
	v_and_b32_e32 v5, 0xfffffc00, v5
	s_ashr_i32 s54, s16, 6
	s_lshl_b64 s[8:9], s[8:9], 1
	v_sub_u32_e32 v5, v4, v5
	s_waitcnt lgkmcnt(0)
	s_add_u32 s8, s0, s8
	v_lshrrev_b32_e32 v6, 4, v5
	s_addc_u32 s9, s1, s9
	v_bitop3_b32 v5, v6, v5, 32 bitop3:0x6c
	s_add_u32 s12, s8, 0x900000
	v_ashrrev_i32_e32 v7, 31, v5
	s_addc_u32 s13, s9, 0
	v_lshrrev_b32_e32 v7, 26, v7
	s_add_u32 s8, s0, 0x12d00000
	v_add_u32_e32 v7, v5, v7
	s_addc_u32 s9, s1, 0
	v_lshlrev_b32_e32 v6, 3, v142
	v_ashrrev_i32_e32 v143, 6, v7
	v_and_b32_e32 v7, 0xc0, v7
	s_add_u32 s10, s0, 0xc300000
	v_and_b32_e32 v6, -16, v6
	v_sub_u32_e32 v5, v5, v7
	s_addc_u32 s11, s1, 0
	v_add_u32_e32 v133, v143, v6
	v_lshlrev_b32_e32 v6, 5, v142
	v_ashrrev_i16_sdwa v5, v205, sext(v5) dst_sel:DWORD dst_unused:UNUSED_PAD src0_sel:DWORD src1_sel:BYTE_0
	s_add_u32 s0, s0, 0x2e200000
	v_and_b32_e32 v6, 32, v6
	v_bfe_i32 v144, v5, 0, 16
	v_lshrrev_b32_e32 v5, 2, v133
	s_addc_u32 s1, s1, 0
	v_add_u32_e32 v132, v6, v144
	v_lshlrev_b32_e32 v155, 1, v133
	v_and_b32_e32 v153, 4, v5
	v_and_b32_e32 v154, 3, v143
	v_and_b32_e32 v152, 15, v3
	s_andn2_b64 vcc, exec, s[4:5]
	s_lshl_b32 s55, s54, 10
	s_cbranch_vccnz .LBB0_1305
	v_and_b32_e32 v5, 0x1fffd8, v155
	v_or3_b32 v5, v154, v5, v153
	v_lshlrev_b32_e32 v6, 1, v132
	v_add_u32_e32 v4, 0x2000, v4
	v_lshl_add_u32 v136, v5, 11, v6
	v_ashrrev_i32_e32 v5, 31, v4
	v_lshrrev_b32_e32 v5, 22, v5
	v_add_u32_e32 v5, v4, v5
	v_ashrrev_i32_e32 v145, 10, v5
	v_mul_i32_i24_e32 v5, 0x400, v145
	v_sub_u32_e32 v4, v4, v5
	v_lshrrev_b32_e32 v5, 4, v4
	v_bitop3_b32 v4, v5, v4, 32 bitop3:0x6c
	v_lshl_add_u32 v134, v133, 11, v6
	v_ashrrev_i32_e32 v6, 31, v4
	v_lshrrev_b32_e32 v6, 26, v6
	v_add_u32_e32 v6, v4, v6
	v_lshlrev_b32_e32 v5, 3, v145
	v_ashrrev_i32_e32 v147, 6, v6
	v_and_b32_e32 v6, 0xc0, v6
	v_and_b32_e32 v5, -16, v5
	v_sub_u32_e32 v4, v4, v6
	v_add_u32_e32 v5, v147, v5
	v_ashrrev_i16_sdwa v4, v205, sext(v4) dst_sel:DWORD dst_unused:UNUSED_PAD src0_sel:DWORD src1_sel:BYTE_0
	v_lshlrev_b32_e32 v7, 5, v145
	v_bfe_i32 v148, v4, 0, 16
	v_lshlrev_b32_e32 v4, 1, v5
	v_lshrrev_b32_e32 v6, 2, v5
	s_ashr_i32 s5, s16, 8
	v_and_b32_e32 v7, 32, v7
	v_and_b32_e32 v6, 4, v6
	v_and_b32_e32 v8, 3, v147
	v_and_b32_e32 v4, 0x1fffd8, v4
	s_lshl_b32 s17, s5, 6
	s_lshl_b32 s14, s30, 8
	s_and_b32 s4, s54, 3
	v_or3_b32 v4, v8, v6, v4
	v_add_lshl_u32 v6, v7, v148, 1
	s_add_i32 s14, s14, s17
	v_bfe_u32 v146, v3, 4, 2
	v_lshl_add_u32 v140, v4, 11, v6
	v_or_b32_e32 v4, s14, v152
	s_lshl_b32 s14, s28, 8
	s_lshl_b32 s62, s4, 6
	v_lshlrev_b32_e32 v156, 3, v146
	s_or_b32 s14, s14, s62
	v_or_b32_e32 v10, 16, v4
	v_lshl_add_u32 v138, v5, 11, v6
	v_or_b32_e32 v6, s14, v156
	v_ashrrev_i32_e32 v5, 31, v4
	v_ashrrev_i32_e32 v11, 31, v10
	v_lshlrev_b64 v[8:9], 11, v[4:5]
	v_ashrrev_i32_e32 v7, 31, v6
	v_lshlrev_b64 v[10:11], 11, v[10:11]
	v_lshl_add_u64 v[8:9], s[10:11], 0, v[8:9]
	v_lshlrev_b64 v[6:7], 1, v[6:7]
	v_lshl_add_u64 v[10:11], s[10:11], 0, v[10:11]
	v_lshl_add_u64 v[8:9], v[8:9], 0, v[6:7]
	v_lshl_add_u64 v[10:11], v[10:11], 0, v[6:7]
	global_load_dwordx4 v[64:67], v[8:9], off
	global_load_dwordx4 v[56:59], v[8:9], off offset:64
	global_load_dwordx4 v[60:63], v[10:11], off
	global_load_dwordx4 v[48:51], v[10:11], off offset:64
	v_or_b32_e32 v10, 32, v4
	v_or_b32_e32 v4, 48, v4
	v_ashrrev_i32_e32 v11, 31, v10
	v_ashrrev_i32_e32 v5, 31, v4
	v_lshlrev_b64 v[10:11], 11, v[10:11]
	v_lshlrev_b64 v[4:5], 11, v[4:5]
	v_lshl_add_u64 v[10:11], s[10:11], 0, v[10:11]
	v_lshl_add_u64 v[4:5], s[10:11], 0, v[4:5]
	v_lshl_add_u64 v[10:11], v[10:11], 0, v[6:7]
	v_lshl_add_u64 v[4:5], v[4:5], 0, v[6:7]
	v_add_co_u32_e32 v6, vcc, s57, v8
	global_load_dwordx4 v[52:55], v[10:11], off
	global_load_dwordx4 v[40:43], v[10:11], off offset:64
	v_addc_co_u32_e32 v7, vcc, 0, v9, vcc
	global_load_dwordx4 v[44:47], v[4:5], off
	global_load_dwordx4 v[36:39], v[4:5], off offset:64
	v_lshl_add_u64 v[4:5], v[8:9], 0, s[50:51]
	global_load_dwordx4 v[32:35], v[6:7], off
	global_load_dwordx4 v[28:31], v[4:5], off offset:64
	v_add_co_u32_e32 v6, vcc, s26, v8
	s_mov_b32 s14, 0x50000
	s_nop 0
	v_addc_co_u32_e32 v7, vcc, 0, v9, vcc
	v_lshl_add_u64 v[4:5], v[8:9], 0, s[72:73]
	global_load_dwordx4 v[24:27], v[6:7], off
	global_load_dwordx4 v[20:23], v[4:5], off offset:64
	v_add_co_u32_e32 v6, vcc, s14, v8
	s_mov_b64 s[14:15], 0x58000
	s_nop 0
	v_addc_co_u32_e32 v7, vcc, 0, v9, vcc
	v_lshl_add_u64 v[16:17], v[8:9], 0, s[14:15]
	s_mov_b32 s14, 0x58000
	s_ashr_i32 s31, s30, 31
	s_ashr_i32 s29, s28, 31
	v_lshl_add_u64 v[4:5], v[8:9], 0, s[74:75]
	v_add_co_u32_e32 v8, vcc, s14, v8
	s_lshl_b64 s[14:15], s[30:31], 19
	s_lshl_b64 s[18:19], s[28:29], 19
	s_lshr_b32 s32, s2, 3
	s_lshr_b32 s99, s2, 6
	s_add_i32 s32, s32, s99
	s_and_b32 s32, s32, 3
	s_lshl_b32 s32, s32, 8
	s_add_u32 s38, s12, s18
	s_addc_u32 s39, s13, s19
	s_add_u32 s38, s38, s32
	s_addc_u32 s39, s39, 0
	s_add_i32 s31, s55, 0
	v_addc_co_u32_e32 v9, vcc, 0, v9, vcc
	s_add_i32 m0, s31, 0x10000
	global_load_dwordx4 v[12:15], v[6:7], off
	s_nop 0
	global_load_dwordx4 v[4:7], v[4:5], off offset:64
	s_nop 0
	global_load_dwordx4 v[8:11], v[8:9], off
	s_nop 0
	global_load_dwordx4 v[16:19], v[16:17], off offset:64
	v_mov_b32_e32 v137, v2
	global_load_lds_dwordx4 v136, s[38:39]
	s_add_i32 m0, s31, 0x12000
	s_add_u32 s18, s38, 0x10000
	global_load_lds_dwordx4 v140, s[38:39]
	s_addc_u32 s19, s39, 0
	s_add_i32 m0, s31, 0x14000
	v_mov_b32_e32 v141, v2
	global_load_lds_dwordx4 v136, s[18:19]
	s_add_i32 m0, s31, 0x16000
	s_add_u32 s40, s8, s14
	s_addc_u32 s41, s9, s15
	s_add_u32 s40, s40, s32
	s_addc_u32 s41, s41, 0
	s_add_i32 s63, s31, 0x2000
	global_load_lds_dwordx4 v140, s[18:19]
	s_mov_b32 m0, s31
	s_add_u32 s14, s40, 0x40000
	global_load_lds_dwordx4 v134, s[40:41]
	s_mov_b32 m0, s63
	s_addc_u32 s15, s41, 0
	s_add_i32 s64, s31, 0x4000
	global_load_lds_dwordx4 v138, s[40:41]
	s_mov_b32 m0, s64
	s_add_i32 s65, s31, 0x6000
	global_load_lds_dwordx4 v134, s[14:15]
	s_mov_b32 m0, s65
	v_mov_b32_e32 v135, v2
	global_load_lds_dwordx4 v138, s[14:15]
	v_mov_b32_e32 v139, v2
	s_cmp_eq_u32 s5, 1
	v_lshl_add_u64 v[74:75], s[38:39], 0, v[136:137]
	v_lshl_add_u64 v[72:73], s[38:39], 0, v[140:141]
	v_lshl_add_u64 v[68:69], s[40:41], 0, v[134:135]
	s_cselect_b64 s[14:15], -1, 0
	s_cmp_lg_u32 s5, 1
	v_lshl_add_u64 v[70:71], s[40:41], 0, v[138:139]
	s_cbranch_scc1 .LBB0_1260
	s_barrier
; DI float bf_lo(unsigned u) { return __uint_as_float(u << 16); }
; DI float bf_hi(unsigned u) { return __uint_as_float(u & 0xffff0000u); }
; #define PG8_STAGE(bufoff, gbase, voff) do { _Pragma("unroll") for (int _i = 0; _i < 2; ++_i) \
;         __builtin_amdgcn_global_load_lds((const unsigned*)((const char*)(gbase) + (voff)[_i]), (PG8_LAS unsigned*)(lds + (bufoff) + ldsw + _i * 8192), 16, 0, 0); } while (0)
; #define PG8_WAIT_V(n) asm volatile("s_waitcnt vmcnt(" #n ")" ::: "memory")
; #define PG8_BAR __builtin_amdgcn_s_barrier()
;     DI void init_finish(f32x4 (&acc)[2][2][4][2], const u32x4 (&w)[R8::HAS_PRE ? 16 : 1]) const {
;         if constexpr (R8::HAS_PRE) {
; #pragma unroll
;             for (int ai = 0; ai < 2; ++ai)
; #pragma unroll
;                 for (int m = 0; m < 4; ++m)
; #pragma unroll
;                     for (int bj = 0; bj < 2; ++bj) { const u32x4 v = w[(ai * 4 + m) * 2 + bj];
;                         acc[ai][bj][m][0] = (f32x4){bf_lo(v.x), bf_hi(v.x), bf_lo(v.y), bf_hi(v.y)}; acc[ai][bj][m][1] = (f32x4){bf_lo(v.z), bf_hi(v.z), bf_lo(v.w), bf_hi(v.w)}; }
;         }
;     }
; template <class Epi, class Sched, bool ALIGN_EPI = false, bool SP2 = false>
; __device__ __forceinline__ void gemm_phase(PG8_LAS unsigned char* lds, const Gemm g, const Sched& S, const Epi& E, const int tid) {
;     ...
;         if (wr == 1) PG8_BAR;
;         PG8_WAIT_V(2); PG8_BAR;
;         PG8_STAGE(PG8_SB(1, 0), cB + kstep, voffB); PG8_STAGE(PG8_SA(1, 0), cA + kstep, voffA); PG8_STAGE(PG8_SB(1, 1), cB + hstepB + kstep, voffB);
;         PG8_WAIT_V(6); PG8_BAR;
.LBB0_1260:
	v_or_b32_e32 v157, s17, v152
	v_lshlrev_b32_e32 v76, 6, v157
	v_lshlrev_b32_e32 v77, 4, v146
	s_movk_i32 s17, 0x3c0
	v_lshlrev_b32_e32 v78, 2, v157
	v_and_or_b32 v76, v76, s17, v77
	s_lshl_b32 s5, s5, 13
	v_and_b32_e32 v78, 32, v78
	v_bitop3_b32 v149, v76, s5, v78 bitop3:0xde
	v_lshl_or_b32 v76, v152, 6, v77
	v_lshlrev_b32_e32 v77, 2, v152
	s_add_i32 m0, s31, 0x18000
	v_lshl_add_u64 v[74:75], v[74:75], 0, s[52:53]
	s_lshl_b32 s4, s4, 12
	v_and_b32_e32 v77, 32, v77
	s_waitcnt vmcnt(2)
	s_barrier
	global_load_lds_dwordx4 v[74:75], off
	v_lshl_add_u64 v[72:73], v[72:73], 0, s[52:53]
	s_add_i32 m0, s31, 0x1a000
	s_add_i32 s66, s31, 0x8000
	s_add_i32 s67, s31, 0xa000
	v_bitop3_b32 v158, v76, s4, v77 bitop3:0xde
	global_load_lds_dwordx4 v[72:73], off
	v_lshl_add_u64 v[68:69], v[68:69], 0, s[52:53]
	s_mov_b32 m0, s66
	s_add_u32 s4, s38, 0x10080
	global_load_lds_dwordx4 v[68:69], off
	v_lshl_add_u64 v[68:69], v[70:71], 0, s[52:53]
	s_mov_b32 m0, s67
	s_addc_u32 s5, s39, 0
	global_load_lds_dwordx4 v[68:69], off
	s_add_i32 m0, s31, 0x1c000
	v_lshl_add_u64 v[68:69], s[4:5], 0, v[136:137]
	global_load_lds_dwordx4 v[68:69], off
	v_lshl_add_u64 v[68:69], s[4:5], 0, v[140:141]
	s_add_i32 m0, s31, 0x1e000
	v_cmp_eq_u32_e64 s[4:5], 0, v146
	global_load_lds_dwordx4 v[68:69], off
	v_lshlrev_b32_e32 v146, 14, v142
	v_and_b32_e32 v146, 0xffff8000, v146
	v_lshl_add_u32 v143, v143, 11, v146
	v_and_b32_e32 v142, 1, v142
	v_lshl_or_b32 v142, v142, 6, v143
	v_lshl_add_u32 v142, v144, 1, v142
	v_lshlrev_b32_e32 v144, 14, v145
	v_and_b32_e32 v144, 0xffff8000, v144
	s_waitcnt vmcnt(6)
	v_lshl_add_u32 v144, v147, 11, v144
	v_and_b32_e32 v145, 1, v145
	s_cmpk_lt_u32 s16, 0x100
	v_lshl_or_b32 v144, v145, 6, v144
	s_waitcnt vmcnt(0)
	v_lshlrev_b32_e32 v120, 16, v64
	v_and_b32_e32 v121, 0xffff0000, v64
	v_lshlrev_b32_e32 v122, 16, v65
	v_and_b32_e32 v123, 0xffff0000, v65
	v_lshlrev_b32_e32 v128, 16, v66
	v_and_b32_e32 v129, 0xffff0000, v66
	v_lshlrev_b32_e32 v130, 16, v67
	v_and_b32_e32 v131, 0xffff0000, v67
	v_lshlrev_b32_e32 v116, 16, v56
	v_and_b32_e32 v117, 0xffff0000, v56
	v_lshlrev_b32_e32 v118, 16, v57
	v_and_b32_e32 v119, 0xffff0000, v57
	v_lshlrev_b32_e32 v124, 16, v58
	v_and_b32_e32 v125, 0xffff0000, v58
	v_lshlrev_b32_e32 v126, 16, v59
	v_and_b32_e32 v127, 0xffff0000, v59
	v_lshlrev_b32_e32 v100, 16, v60
	v_and_b32_e32 v101, 0xffff0000, v60
	v_lshlrev_b32_e32 v102, 16, v61
	v_and_b32_e32 v103, 0xffff0000, v61
	v_lshlrev_b32_e32 v108, 16, v62
	v_and_b32_e32 v109, 0xffff0000, v62
	v_lshlrev_b32_e32 v110, 16, v63
	v_and_b32_e32 v111, 0xffff0000, v63
	v_lshlrev_b32_e32 v104, 16, v48
	v_and_b32_e32 v105, 0xffff0000, v48
	v_lshlrev_b32_e32 v106, 16, v49
	v_and_b32_e32 v107, 0xffff0000, v49
	v_lshlrev_b32_e32 v112, 16, v50
	v_and_b32_e32 v113, 0xffff0000, v50
	v_lshlrev_b32_e32 v114, 16, v51
	v_and_b32_e32 v115, 0xffff0000, v51
	v_lshlrev_b32_e32 v84, 16, v52
	v_and_b32_e32 v85, 0xffff0000, v52
	v_lshlrev_b32_e32 v86, 16, v53
	v_and_b32_e32 v87, 0xffff0000, v53
	v_lshlrev_b32_e32 v92, 16, v54
	v_and_b32_e32 v93, 0xffff0000, v54
	v_lshlrev_b32_e32 v94, 16, v55
	v_and_b32_e32 v95, 0xffff0000, v55
	v_lshlrev_b32_e32 v88, 16, v40
	v_and_b32_e32 v89, 0xffff0000, v40
	v_lshlrev_b32_e32 v90, 16, v41
	v_and_b32_e32 v91, 0xffff0000, v41
	v_lshlrev_b32_e32 v96, 16, v42
	v_and_b32_e32 v97, 0xffff0000, v42
	v_lshlrev_b32_e32 v98, 16, v43
	v_and_b32_e32 v99, 0xffff0000, v43
	v_lshlrev_b32_e32 v68, 16, v44
	v_and_b32_e32 v69, 0xffff0000, v44
	v_lshlrev_b32_e32 v70, 16, v45
	v_and_b32_e32 v71, 0xffff0000, v45
	v_lshlrev_b32_e32 v76, 16, v46
	v_and_b32_e32 v77, 0xffff0000, v46
	v_lshlrev_b32_e32 v78, 16, v47
	v_and_b32_e32 v79, 0xffff0000, v47
	v_lshlrev_b32_e32 v72, 16, v36
	v_and_b32_e32 v73, 0xffff0000, v36
	v_lshlrev_b32_e32 v74, 16, v37
	v_and_b32_e32 v75, 0xffff0000, v37
	v_lshlrev_b32_e32 v80, 16, v38
	v_and_b32_e32 v81, 0xffff0000, v38
	v_lshlrev_b32_e32 v82, 16, v39
	v_and_b32_e32 v83, 0xffff0000, v39
	v_lshlrev_b32_e32 v52, 16, v32
	v_and_b32_e32 v53, 0xffff0000, v32
	v_lshlrev_b32_e32 v54, 16, v33
	v_and_b32_e32 v55, 0xffff0000, v33
	v_lshlrev_b32_e32 v60, 16, v34
	v_and_b32_e32 v61, 0xffff0000, v34
	v_lshlrev_b32_e32 v62, 16, v35
	v_and_b32_e32 v63, 0xffff0000, v35
	v_lshlrev_b32_e32 v56, 16, v28
	v_and_b32_e32 v57, 0xffff0000, v28
	v_lshlrev_b32_e32 v58, 16, v29
	v_and_b32_e32 v59, 0xffff0000, v29
	v_lshlrev_b32_e32 v64, 16, v30
	v_and_b32_e32 v65, 0xffff0000, v30
	v_lshlrev_b32_e32 v66, 16, v31
	v_and_b32_e32 v67, 0xffff0000, v31
	v_lshlrev_b32_e32 v36, 16, v24
	v_and_b32_e32 v37, 0xffff0000, v24
	v_lshlrev_b32_e32 v38, 16, v25
	v_and_b32_e32 v39, 0xffff0000, v25
	v_lshlrev_b32_e32 v44, 16, v26
	v_and_b32_e32 v45, 0xffff0000, v26
	v_lshlrev_b32_e32 v46, 16, v27
	v_and_b32_e32 v47, 0xffff0000, v27
	v_lshlrev_b32_e32 v40, 16, v20
	v_and_b32_e32 v41, 0xffff0000, v20
	v_lshlrev_b32_e32 v42, 16, v21
	v_and_b32_e32 v43, 0xffff0000, v21
	v_lshlrev_b32_e32 v48, 16, v22
	v_and_b32_e32 v49, 0xffff0000, v22
	v_lshlrev_b32_e32 v50, 16, v23
	v_and_b32_e32 v51, 0xffff0000, v23
	v_lshlrev_b32_e32 v20, 16, v12
	v_and_b32_e32 v21, 0xffff0000, v12
	v_lshlrev_b32_e32 v22, 16, v13
	v_and_b32_e32 v23, 0xffff0000, v13
	v_lshlrev_b32_e32 v28, 16, v14
	v_and_b32_e32 v29, 0xffff0000, v14
	v_lshlrev_b32_e32 v30, 16, v15
	v_and_b32_e32 v31, 0xffff0000, v15
	v_lshlrev_b32_e32 v24, 16, v4
	v_and_b32_e32 v25, 0xffff0000, v4
	v_lshlrev_b32_e32 v26, 16, v5
	v_and_b32_e32 v27, 0xffff0000, v5
	v_lshlrev_b32_e32 v32, 16, v6
	v_and_b32_e32 v33, 0xffff0000, v6
	v_lshlrev_b32_e32 v34, 16, v7
	v_and_b32_e32 v35, 0xffff0000, v7
	v_lshlrev_b32_e32 v4, 16, v8
	v_and_b32_e32 v5, 0xffff0000, v8
	v_lshlrev_b32_e32 v6, 16, v9
	v_and_b32_e32 v7, 0xffff0000, v9
	v_lshlrev_b32_e32 v12, 16, v10
	v_and_b32_e32 v13, 0xffff0000, v10
	v_lshlrev_b32_e32 v14, 16, v11
	v_and_b32_e32 v15, 0xffff0000, v11
	v_lshlrev_b32_e32 v8, 16, v16
	v_and_b32_e32 v9, 0xffff0000, v16
	v_lshlrev_b32_e32 v10, 16, v17
	v_and_b32_e32 v11, 0xffff0000, v17
	v_lshlrev_b32_e32 v16, 16, v18
	v_and_b32_e32 v17, 0xffff0000, v18
	v_lshlrev_b32_e32 v18, 16, v19
	v_and_b32_e32 v19, 0xffff0000, v19
	s_cselect_b64 s[16:17], -1, 0
	s_mov_b32 s76, 0
	s_lshl_b32 s78, s27, 3
	v_or_b32_e32 v159, s62, v156
	v_mov_b32_e32 v143, v2
	v_lshl_add_u32 v144, v148, 1, v144
	v_mov_b32_e32 v145, v2
	v_add_u32_e32 v160, 0, v149
	s_barrier
	s_sub_u32 s38, s38, s32
	s_subb_u32 s39, s39, 0
	s_sub_u32 s40, s40, s32
	s_subb_u32 s41, s41, 0
	s_branch .LBB0_1263

; #define PG8_STAGE(bufoff, gbase, voff) do { _Pragma("unroll") for (int _i = 0; _i < 2; ++_i) \
;         __builtin_amdgcn_global_load_lds((const unsigned*)((const char*)(gbase) + (voff)[_i]), (PG8_LAS unsigned*)(lds + (bufoff) + ldsw + _i * 8192), 16, 0, 0); } while (0)
; #define PG8_LDA(dst, b, h) do { _Pragma("unroll") for (int m = 0; m < 4; ++m) _Pragma("unroll") for (int k = 0; k < 2; ++k) dst[m][k] = *(const PG8_LAS bf16x8*)(lds + PG8_SA(b, h) + aoff + m * 2048 + k * 1024); } while (0)
; #define PG8_LDB(dst, b, h) do { _Pragma("unroll") for (int n = 0; n < 2; ++n) _Pragma("unroll") for (int k = 0; k < 2; ++k) dst[n][k] = *(const PG8_LAS bf16x8*)(lds + PG8_SB(b, h) + boff + n * 2048 + k * 1024); } while (0)
; #define PG8_MMA(ai, bj, At, Bt) do { __builtin_amdgcn_s_setprio(1); _Pragma("unroll") for (int m = 0; m < 4; ++m) _Pragma("unroll") for (int n = 0; n < 2; ++n) _Pragma("unroll") for (int k = 0; k < 2; ++k) \
;         acc[ai][bj][m][n] = __builtin_amdgcn_mfma_f32_16x16x32_bf16(Bt[n][k], At[m][k], acc[ai][bj][m][n], 0, 0, 0); __builtin_amdgcn_s_setprio(0); } while (0)
; #define PG8_WAIT_V(n) asm volatile("s_waitcnt vmcnt(" #n ")" ::: "memory")
; #define PG8_WAIT_L(n) asm volatile("s_waitcnt lgkmcnt(" #n ")" ::: "memory")
; #define PG8_BAR __builtin_amdgcn_s_barrier()
; template <class Epi, class Sched, bool ALIGN_EPI = false, bool SP2 = false>
; __device__ __forceinline__ void gemm_phase(PG8_LAS unsigned char* lds, const Gemm g, const Sched& S, const Epi& E, const int tid) {
;     ...
;         const char* nA = has_next ? (const char*)g.A + (size_t)nxt.pm * tstep : cA; const char* nB = has_next ? (const char*)g.Bt + (size_t)nxt.pn * tstep : cB;
;         for (int t = 0; t < nt; t += 2) {
;             const bool last = (t == nt - 2);
;             const char* a1 = cA + (size_t)(t + 1) * kstep;
;             const char* a2 = last ? nA : cA + (size_t)(t + 2) * kstep; const char* b2 = last ? nB : cB + (size_t)(t + 2) * kstep;
;             const char* a3 = a2 + kstep; const char* b3 = b2 + kstep;
;             if (last && has_next) S.a_ready(nxt);
;             if constexpr (SP2) {
;             PG8_LDB(B0, 0, 0); PG8_LDB(B1, 0, 1); PG8_SCHED; PG8_LDA(At, 0, 0); PG8_STAGE(PG8_SA(1, 1), a1 + hstep, voffA);
;             PG8_WAIT_V(8); PG8_WAIT_L(0); PG8_BAR; PG8_MMA(0, 0, At, B0); PG8_MMA(0, 1, At, B1); PG8_BAR; PG8_SCHED;
.LBB0_1265:
	s_ashr_i32 s21, s20, 31
	s_lshl_b64 s[22:23], s[20:21], 19
	s_add_u32 s22, s8, s22
	s_addc_u32 s23, s9, s23
	s_and_b64 s[24:25], s[36:37], exec
	s_cselect_b32 s21, s23, s41
	s_cselect_b32 s29, s22, s40
	s_add_u32 s29, s29, s32
	s_addc_u32 s21, s21, 0
	s_ashr_i32 s19, s18, 31
	s_lshl_b64 s[24:25], s[18:19], 19
	s_add_u32 s24, s12, s24
	s_addc_u32 s25, s13, s25
	s_and_b64 s[42:43], s[36:37], exec
	s_cselect_b32 s19, s25, s39
	s_cselect_b32 s79, s24, s38
	s_add_u32 s79, s79, s32
	s_addc_u32 s19, s19, 0
	s_add_u32 s40, s40, 0x40080
	s_addc_u32 s41, s41, 0
	s_mov_b32 s80, s38
	s_mov_b32 s81, s39
	s_mov_b32 s82, -2
.LBB0_1266:
	s_lshl_b32 s100, s82, 7
	s_add_i32 s100, s100, s32
	s_add_i32 s100, s100, 0x100
	s_add_i32 s99, s100, 0x100
	s_and_b32 s100, s100, 0x700
	s_and_b32 s99, s99, 0x700
	s_add_u32 s100, s40, s100
	s_addc_u32 s101, s41, 0
	s_add_u32 s38, s40, 0xfffbff80
	s_addc_u32 s39, s41, -1
	s_add_u32 s38, s38, s99
	s_addc_u32 s39, s39, 0
	s_add_i32 s83, 0, 0x10000
	s_cmp_eq_u32 s82, 12
	s_cselect_b32 s43, s21, s39
	s_cselect_b32 s42, s29, s38
	v_add_u32_e32 v150, s83, v158
	s_add_u32 s38, s80, s99
	s_addc_u32 s39, s81, 0
	s_cmp_eq_u32 s82, 12
	s_cselect_b32 s39, s19, s39
	s_cselect_b32 s38, s79, s38
	s_add_i32 s86, 0, 0x14000
	ds_read_b128 v[146:149], v150
	ds_read_b128 v[162:165], v150 offset:1024
	ds_read_b128 v[170:173], v150 offset:2048
	ds_read_b128 v[174:177], v150 offset:3072
	v_add_u32_e32 v150, s86, v158
	ds_read_b128 v[178:181], v150
	ds_read_b128 v[182:185], v150 offset:1024
	ds_read_b128 v[186:189], v150 offset:2048
	ds_read_b128 v[190:193], v150 offset:3072
	v_lshl_add_u64 v[150:151], s[100:101], 0, v[142:143]
	s_add_i32 m0, s31, 0xc000
	ds_read_b128 v[194:197], v160
	ds_read_b128 v[198:201], v160 offset:1024
	ds_read_b128 v[212:215], v160 offset:2048
	ds_read_b128 v[216:219], v160 offset:3072
	ds_read_b128 v[220:223], v160 offset:4096
	ds_read_b128 v[224:227], v160 offset:5120
	ds_read_b128 v[228:231], v160 offset:6144
	ds_read_b128 v[232:235], v160 offset:7168
	global_load_lds_dwordx4 v[150:151], off
	v_lshl_add_u64 v[150:151], s[100:101], 0, v[144:145]
	s_add_i32 m0, s31, 0xe000
	s_nop 0
	global_load_lds_dwordx4 v[150:151], off
	s_waitcnt vmcnt(8)
	s_waitcnt lgkmcnt(0)
	s_barrier
	s_setprio 1
	s_waitcnt lgkmcnt(0)
	v_mfma_f32_16x16x32_bf16 v[120:123], v[146:149], v[194:197], v[120:123]
	v_mfma_f32_16x16x32_bf16 v[128:131], v[170:173], v[194:197], v[128:131]
	v_mfma_f32_16x16x32_bf16 v[100:103], v[146:149], v[212:215], v[100:103]
	v_mfma_f32_16x16x32_bf16 v[108:111], v[170:173], v[212:215], v[108:111]
	v_mfma_f32_16x16x32_bf16 v[84:87], v[146:149], v[220:223], v[84:87]
	v_mfma_f32_16x16x32_bf16 v[92:95], v[170:173], v[220:223], v[92:95]
	v_mfma_f32_16x16x32_bf16 v[68:71], v[146:149], v[228:231], v[68:71]
	v_mfma_f32_16x16x32_bf16 v[76:79], v[170:173], v[228:231], v[76:79]
	v_mfma_f32_16x16x32_bf16 v[120:123], v[162:165], v[198:201], v[120:123]
	v_mfma_f32_16x16x32_bf16 v[128:131], v[174:177], v[198:201], v[128:131]
	v_mfma_f32_16x16x32_bf16 v[100:103], v[162:165], v[216:219], v[100:103]
	v_mfma_f32_16x16x32_bf16 v[108:111], v[174:177], v[216:219], v[108:111]
	v_mfma_f32_16x16x32_bf16 v[84:87], v[162:165], v[224:227], v[84:87]
	v_mfma_f32_16x16x32_bf16 v[92:95], v[174:177], v[224:227], v[92:95]
	v_mfma_f32_16x16x32_bf16 v[68:71], v[162:165], v[232:235], v[68:71]
	v_mfma_f32_16x16x32_bf16 v[76:79], v[174:177], v[232:235], v[76:79]
	s_setprio 0
	s_setprio 1
	v_mfma_f32_16x16x32_bf16 v[116:119], v[178:181], v[194:197], v[116:119]
	v_mfma_f32_16x16x32_bf16 v[124:127], v[186:189], v[194:197], v[124:127]
	v_mfma_f32_16x16x32_bf16 v[104:107], v[178:181], v[212:215], v[104:107]
	v_mfma_f32_16x16x32_bf16 v[112:115], v[186:189], v[212:215], v[112:115]
	v_mfma_f32_16x16x32_bf16 v[88:91], v[178:181], v[220:223], v[88:91]
	v_mfma_f32_16x16x32_bf16 v[96:99], v[186:189], v[220:223], v[96:99]
	v_mfma_f32_16x16x32_bf16 v[72:75], v[178:181], v[228:231], v[72:75]
	v_mfma_f32_16x16x32_bf16 v[80:83], v[186:189], v[228:231], v[80:83]
	v_mfma_f32_16x16x32_bf16 v[116:119], v[182:185], v[198:201], v[116:119]
	v_mfma_f32_16x16x32_bf16 v[124:127], v[190:193], v[198:201], v[124:127]
	v_mfma_f32_16x16x32_bf16 v[104:107], v[182:185], v[216:219], v[104:107]
	v_mfma_f32_16x16x32_bf16 v[112:115], v[190:193], v[216:219], v[112:115]
	v_mfma_f32_16x16x32_bf16 v[88:91], v[182:185], v[224:227], v[88:91]
	v_mfma_f32_16x16x32_bf16 v[96:99], v[190:193], v[224:227], v[96:99]
	v_mfma_f32_16x16x32_bf16 v[72:75], v[182:185], v[232:235], v[72:75]
	v_mfma_f32_16x16x32_bf16 v[80:83], v[190:193], v[232:235], v[80:83]
	s_setprio 0
	s_barrier
	s_add_i32 s83, s83, s55
	v_lshl_add_u64 v[150:151], s[38:39], 0, v[136:137]
	s_mov_b32 m0, s83
	ds_read_b128 v[194:197], v160 offset:16384
	ds_read_b128 v[198:201], v160 offset:17408
	ds_read_b128 v[212:215], v160 offset:18432
	ds_read_b128 v[216:219], v160 offset:19456
	ds_read_b128 v[220:223], v160 offset:20480
	ds_read_b128 v[224:227], v160 offset:21504
	ds_read_b128 v[228:231], v160 offset:22528
	ds_read_b128 v[232:235], v160 offset:23552
	global_load_lds_dwordx4 v[150:151], off
	s_add_i32 m0, s83, 0x2000
	s_add_u32 s84, s38, 0x10000
	v_lshl_add_u64 v[166:167], s[38:39], 0, v[140:141]
	s_addc_u32 s85, s39, 0
	s_add_i32 s83, s86, s55
	global_load_lds_dwordx4 v[166:167], off
	v_lshl_add_u64 v[236:237], s[84:85], 0, v[136:137]
	s_mov_b32 m0, s83
	v_lshl_add_u64 v[238:239], s[42:43], 0, v[138:139]
	global_load_lds_dwordx4 v[236:237], off
	v_lshl_add_u64 v[236:237], s[84:85], 0, v[140:141]
	s_add_i32 m0, s83, 0x2000
	s_nop 0
	global_load_lds_dwordx4 v[236:237], off
	v_lshl_add_u64 v[236:237], s[42:43], 0, v[134:135]
	s_mov_b32 m0, s31
	s_nop 0
	global_load_lds_dwordx4 v[236:237], off
	s_mov_b32 m0, s63
	s_nop 0
	global_load_lds_dwordx4 v[238:239], off
	s_waitcnt vmcnt(8)
	s_waitcnt lgkmcnt(0)
	s_barrier
; #define PG8_STAGE(bufoff, gbase, voff) do { _Pragma("unroll") for (int _i = 0; _i < 2; ++_i) \
;         __builtin_amdgcn_global_load_lds((const unsigned*)((const char*)(gbase) + (voff)[_i]), (PG8_LAS unsigned*)(lds + (bufoff) + ldsw + _i * 8192), 16, 0, 0); } while (0)
; #define PG8_LDA(dst, b, h) do { _Pragma("unroll") for (int m = 0; m < 4; ++m) _Pragma("unroll") for (int k = 0; k < 2; ++k) dst[m][k] = *(const PG8_LAS bf16x8*)(lds + PG8_SA(b, h) + aoff + m * 2048 + k * 1024); } while (0)
; #define PG8_LDB(dst, b, h) do { _Pragma("unroll") for (int n = 0; n < 2; ++n) _Pragma("unroll") for (int k = 0; k < 2; ++k) dst[n][k] = *(const PG8_LAS bf16x8*)(lds + PG8_SB(b, h) + boff + n * 2048 + k * 1024); } while (0)
; #define PG8_MMA(ai, bj, At, Bt) do { __builtin_amdgcn_s_setprio(1); _Pragma("unroll") for (int m = 0; m < 4; ++m) _Pragma("unroll") for (int n = 0; n < 2; ++n) _Pragma("unroll") for (int k = 0; k < 2; ++k) \
;         acc[ai][bj][m][n] = __builtin_amdgcn_mfma_f32_16x16x32_bf16(Bt[n][k], At[m][k], acc[ai][bj][m][n], 0, 0, 0); __builtin_amdgcn_s_setprio(0); } while (0)
; #define PG8_WAIT_V(n) asm volatile("s_waitcnt vmcnt(" #n ")" ::: "memory")
; #define PG8_WAIT_L(n) asm volatile("s_waitcnt lgkmcnt(" #n ")" ::: "memory")
; #define PG8_BAR __builtin_amdgcn_s_barrier()
; #define PG8_SCHED __builtin_amdgcn_sched_barrier(0)
; template <class Epi, class Sched, bool ALIGN_EPI = false, bool SP2 = false>
; __device__ __forceinline__ void gemm_phase(PG8_LAS unsigned char* lds, const Gemm g, const Sched& S, const Epi& E, const int tid) {
;     ...
;             PG8_WAIT_V(8); PG8_WAIT_L(0); PG8_BAR; PG8_MMA(0, 0, At, B0); PG8_MMA(0, 1, At, B1); PG8_BAR; PG8_SCHED;
;             PG8_LDA(At, 0, 1); PG8_STAGE(PG8_SB(0, 0), b2, voffB); PG8_STAGE(PG8_SB(0, 1), b2 + hstepB, voffB); PG8_STAGE(PG8_SA(0, 0), a2, voffA);
;             PG8_WAIT_V(8); PG8_WAIT_L(0); PG8_BAR; PG8_MMA(1, 0, At, B0); PG8_MMA(1, 1, At, B1); PG8_BAR; PG8_SCHED;
;             PG8_LDB(B0, 1, 0); PG8_LDB(B1, 1, 1); PG8_SCHED; PG8_LDA(At, 1, 0); PG8_STAGE(PG8_SA(0, 1), a2 + hstep, voffA);
;             PG8_WAIT_V(8); PG8_WAIT_L(0); PG8_BAR; PG8_MMA(0, 0, At, B0); PG8_MMA(0, 1, At, B1); PG8_BAR; PG8_SCHED;
	s_setprio 1
	s_waitcnt lgkmcnt(0)
	v_mfma_f32_16x16x32_bf16 v[52:55], v[146:149], v[194:197], v[52:55]
	v_mfma_f32_16x16x32_bf16 v[60:63], v[170:173], v[194:197], v[60:63]
	v_mfma_f32_16x16x32_bf16 v[36:39], v[146:149], v[212:215], v[36:39]
	v_mfma_f32_16x16x32_bf16 v[44:47], v[170:173], v[212:215], v[44:47]
	v_mfma_f32_16x16x32_bf16 v[20:23], v[146:149], v[220:223], v[20:23]
	v_mfma_f32_16x16x32_bf16 v[28:31], v[170:173], v[220:223], v[28:31]
	v_mfma_f32_16x16x32_bf16 v[4:7], v[146:149], v[228:231], v[4:7]
	v_mfma_f32_16x16x32_bf16 v[12:15], v[170:173], v[228:231], v[12:15]
	v_mfma_f32_16x16x32_bf16 v[52:55], v[162:165], v[198:201], v[52:55]
	v_mfma_f32_16x16x32_bf16 v[60:63], v[174:177], v[198:201], v[60:63]
	v_mfma_f32_16x16x32_bf16 v[36:39], v[162:165], v[216:219], v[36:39]
	v_mfma_f32_16x16x32_bf16 v[44:47], v[174:177], v[216:219], v[44:47]
	v_mfma_f32_16x16x32_bf16 v[20:23], v[162:165], v[224:227], v[20:23]
	v_mfma_f32_16x16x32_bf16 v[28:31], v[174:177], v[224:227], v[28:31]
	v_mfma_f32_16x16x32_bf16 v[4:7], v[162:165], v[232:235], v[4:7]
	v_mfma_f32_16x16x32_bf16 v[12:15], v[174:177], v[232:235], v[12:15]
	s_setprio 0
	s_setprio 1
	v_mfma_f32_16x16x32_bf16 v[56:59], v[178:181], v[194:197], v[56:59]
	v_mfma_f32_16x16x32_bf16 v[64:67], v[186:189], v[194:197], v[64:67]
	v_mfma_f32_16x16x32_bf16 v[40:43], v[178:181], v[212:215], v[40:43]
	v_mfma_f32_16x16x32_bf16 v[48:51], v[186:189], v[212:215], v[48:51]
	v_mfma_f32_16x16x32_bf16 v[24:27], v[178:181], v[220:223], v[24:27]
	v_mfma_f32_16x16x32_bf16 v[32:35], v[186:189], v[220:223], v[32:35]
	v_mfma_f32_16x16x32_bf16 v[8:11], v[178:181], v[228:231], v[8:11]
	v_mfma_f32_16x16x32_bf16 v[16:19], v[186:189], v[228:231], v[16:19]
	v_mfma_f32_16x16x32_bf16 v[56:59], v[182:185], v[198:201], v[56:59]
	v_mfma_f32_16x16x32_bf16 v[64:67], v[190:193], v[198:201], v[64:67]
	v_mfma_f32_16x16x32_bf16 v[40:43], v[182:185], v[216:219], v[40:43]
	v_mfma_f32_16x16x32_bf16 v[48:51], v[190:193], v[216:219], v[48:51]
	v_mfma_f32_16x16x32_bf16 v[24:27], v[182:185], v[224:227], v[24:27]
	v_mfma_f32_16x16x32_bf16 v[32:35], v[190:193], v[224:227], v[32:35]
	v_mfma_f32_16x16x32_bf16 v[8:11], v[182:185], v[232:235], v[8:11]
	v_mfma_f32_16x16x32_bf16 v[16:19], v[190:193], v[232:235], v[16:19]
	s_setprio 0
	s_barrier
	s_add_i32 s83, 0, 0x18000
	v_add_u32_e32 v161, s83, v158
	s_add_i32 s84, 0, 0x1c000
	ds_read_b128 v[146:149], v161
	ds_read_b128 v[162:165], v161 offset:1024
	ds_read_b128 v[170:173], v161 offset:2048
	ds_read_b128 v[174:177], v161 offset:3072
	v_add_u32_e32 v161, s84, v158
	ds_read_b128 v[178:181], v161
	ds_read_b128 v[182:185], v161 offset:1024
	ds_read_b128 v[186:189], v161 offset:2048
	ds_read_b128 v[190:193], v161 offset:3072
	s_add_u32 s42, s42, 0x40000
	s_addc_u32 s43, s43, 0
	s_mov_b32 m0, s64
	v_lshl_add_u64 v[240:241], s[42:43], 0, v[134:135]
	ds_read_b128 v[194:197], v160 offset:32768
	ds_read_b128 v[198:201], v160 offset:33792
	ds_read_b128 v[212:215], v160 offset:34816
	ds_read_b128 v[216:219], v160 offset:35840
	ds_read_b128 v[220:223], v160 offset:36864
	ds_read_b128 v[224:227], v160 offset:37888
	ds_read_b128 v[228:231], v160 offset:38912
	ds_read_b128 v[232:235], v160 offset:39936
	global_load_lds_dwordx4 v[240:241], off
	v_lshl_add_u64 v[240:241], s[42:43], 0, v[138:139]
	s_mov_b32 m0, s65
	s_nop 0
	global_load_lds_dwordx4 v[240:241], off
	s_waitcnt vmcnt(8)
	s_waitcnt lgkmcnt(0)
	s_barrier
	s_setprio 1
	s_waitcnt lgkmcnt(0)
	v_mfma_f32_16x16x32_bf16 v[120:123], v[146:149], v[194:197], v[120:123]
	v_mfma_f32_16x16x32_bf16 v[128:131], v[170:173], v[194:197], v[128:131]
	v_mfma_f32_16x16x32_bf16 v[100:103], v[146:149], v[212:215], v[100:103]
	v_mfma_f32_16x16x32_bf16 v[108:111], v[170:173], v[212:215], v[108:111]
	v_mfma_f32_16x16x32_bf16 v[84:87], v[146:149], v[220:223], v[84:87]
	v_mfma_f32_16x16x32_bf16 v[92:95], v[170:173], v[220:223], v[92:95]
	v_mfma_f32_16x16x32_bf16 v[68:71], v[146:149], v[228:231], v[68:71]
	v_mfma_f32_16x16x32_bf16 v[76:79], v[170:173], v[228:231], v[76:79]
	v_mfma_f32_16x16x32_bf16 v[120:123], v[162:165], v[198:201], v[120:123]
	v_mfma_f32_16x16x32_bf16 v[128:131], v[174:177], v[198:201], v[128:131]
	v_mfma_f32_16x16x32_bf16 v[100:103], v[162:165], v[216:219], v[100:103]
	v_mfma_f32_16x16x32_bf16 v[108:111], v[174:177], v[216:219], v[108:111]
	v_mfma_f32_16x16x32_bf16 v[84:87], v[162:165], v[224:227], v[84:87]
	v_mfma_f32_16x16x32_bf16 v[92:95], v[174:177], v[224:227], v[92:95]
	v_mfma_f32_16x16x32_bf16 v[68:71], v[162:165], v[232:235], v[68:71]
	v_mfma_f32_16x16x32_bf16 v[76:79], v[174:177], v[232:235], v[76:79]
	s_setprio 0
	s_setprio 1
	v_mfma_f32_16x16x32_bf16 v[116:119], v[178:181], v[194:197], v[116:119]
	v_mfma_f32_16x16x32_bf16 v[124:127], v[186:189], v[194:197], v[124:127]
	v_mfma_f32_16x16x32_bf16 v[104:107], v[178:181], v[212:215], v[104:107]
	v_mfma_f32_16x16x32_bf16 v[112:115], v[186:189], v[212:215], v[112:115]
	v_mfma_f32_16x16x32_bf16 v[88:91], v[178:181], v[220:223], v[88:91]
	v_mfma_f32_16x16x32_bf16 v[96:99], v[186:189], v[220:223], v[96:99]
	v_mfma_f32_16x16x32_bf16 v[72:75], v[178:181], v[228:231], v[72:75]
	v_mfma_f32_16x16x32_bf16 v[80:83], v[186:189], v[228:231], v[80:83]
	v_mfma_f32_16x16x32_bf16 v[116:119], v[182:185], v[198:201], v[116:119]
	v_mfma_f32_16x16x32_bf16 v[124:127], v[190:193], v[198:201], v[124:127]
	v_mfma_f32_16x16x32_bf16 v[104:107], v[182:185], v[216:219], v[104:107]
	v_mfma_f32_16x16x32_bf16 v[112:115], v[190:193], v[216:219], v[112:115]
	v_mfma_f32_16x16x32_bf16 v[88:91], v[182:185], v[224:227], v[88:91]
	v_mfma_f32_16x16x32_bf16 v[96:99], v[190:193], v[224:227], v[96:99]
	v_mfma_f32_16x16x32_bf16 v[72:75], v[182:185], v[232:235], v[72:75]
	v_mfma_f32_16x16x32_bf16 v[80:83], v[190:193], v[232:235], v[80:83]
	s_setprio 0
	s_barrier
; #define PG8_STAGE(bufoff, gbase, voff) do { _Pragma("unroll") for (int _i = 0; _i < 2; ++_i) \
;         __builtin_amdgcn_global_load_lds((const unsigned*)((const char*)(gbase) + (voff)[_i]), (PG8_LAS unsigned*)(lds + (bufoff) + ldsw + _i * 8192), 16, 0, 0); } while (0)
; #define PG8_LDA(dst, b, h) do { _Pragma("unroll") for (int m = 0; m < 4; ++m) _Pragma("unroll") for (int k = 0; k < 2; ++k) dst[m][k] = *(const PG8_LAS bf16x8*)(lds + PG8_SA(b, h) + aoff + m * 2048 + k * 1024); } while (0)
; #define PG8_LDB(dst, b, h) do { _Pragma("unroll") for (int n = 0; n < 2; ++n) _Pragma("unroll") for (int k = 0; k < 2; ++k) dst[n][k] = *(const PG8_LAS bf16x8*)(lds + PG8_SB(b, h) + boff + n * 2048 + k * 1024); } while (0)
; #define PG8_MMA(ai, bj, At, Bt) do { __builtin_amdgcn_s_setprio(1); _Pragma("unroll") for (int m = 0; m < 4; ++m) _Pragma("unroll") for (int n = 0; n < 2; ++n) _Pragma("unroll") for (int k = 0; k < 2; ++k) \
;         acc[ai][bj][m][n] = __builtin_amdgcn_mfma_f32_16x16x32_bf16(Bt[n][k], At[m][k], acc[ai][bj][m][n], 0, 0, 0); __builtin_amdgcn_s_setprio(0); } while (0)
; #define PG8_WAIT_V(n) asm volatile("s_waitcnt vmcnt(" #n ")" ::: "memory")
; #define PG8_WAIT_L(n) asm volatile("s_waitcnt lgkmcnt(" #n ")" ::: "memory")
; #define PG8_BAR __builtin_amdgcn_s_barrier()
; #define PG8_SCHED __builtin_amdgcn_sched_barrier(0)
; template <class Epi, class Sched, bool ALIGN_EPI = false, bool SP2 = false>
; __device__ __forceinline__ void gemm_phase(PG8_LAS unsigned char* lds, const Gemm g, const Sched& S, const Epi& E, const int tid) {
;     ...
;             PG8_WAIT_V(8); PG8_WAIT_L(0); PG8_BAR; PG8_MMA(1, 0, At, B0); PG8_MMA(1, 1, At, B1); PG8_BAR; PG8_SCHED;
;             PG8_LDB(B0, 1, 0); PG8_LDB(B1, 1, 1); PG8_SCHED; PG8_LDA(At, 1, 0); PG8_STAGE(PG8_SA(0, 1), a2 + hstep, voffA);
;             PG8_WAIT_V(8); PG8_WAIT_L(0); PG8_BAR; PG8_MMA(0, 0, At, B0); PG8_MMA(0, 1, At, B1); PG8_BAR; PG8_SCHED;
;             PG8_LDA(At, 1, 1); PG8_STAGE(PG8_SB(1, 0), b3, voffB); PG8_STAGE(PG8_SB(1, 1), b3 + hstepB, voffB); PG8_STAGE(PG8_SA(1, 0), a3, voffA);
;             PG8_WAIT_V(8); PG8_WAIT_L(0); PG8_BAR; PG8_MMA(1, 0, At, B0); PG8_MMA(1, 1, At, B1); PG8_BAR; PG8_SCHED;
	s_add_i32 s42, s83, s55
	v_lshl_add_u64 v[150:151], v[150:151], 0, s[52:53]
	s_mov_b32 m0, s42
	ds_read_b128 v[194:197], v160 offset:49152
	ds_read_b128 v[198:201], v160 offset:50176
	ds_read_b128 v[212:215], v160 offset:51200
	ds_read_b128 v[216:219], v160 offset:52224
	ds_read_b128 v[220:223], v160 offset:53248
	ds_read_b128 v[224:227], v160 offset:54272
	ds_read_b128 v[228:231], v160 offset:55296
	ds_read_b128 v[232:235], v160 offset:56320
	global_load_lds_dwordx4 v[150:151], off
	s_add_i32 m0, s42, 0x2000
	s_add_u32 s38, s38, 0x10080
	v_lshl_add_u64 v[150:151], v[166:167], 0, s[52:53]
	s_addc_u32 s39, s39, 0
	s_add_i32 s42, s84, s55
	global_load_lds_dwordx4 v[150:151], off
	v_lshl_add_u64 v[150:151], s[38:39], 0, v[136:137]
	s_mov_b32 m0, s42
	s_nop 0
	global_load_lds_dwordx4 v[150:151], off
	v_lshl_add_u64 v[150:151], s[38:39], 0, v[140:141]
	s_add_i32 m0, s42, 0x2000
	s_nop 0
	global_load_lds_dwordx4 v[150:151], off
	v_lshl_add_u64 v[150:151], v[236:237], 0, s[52:53]
	s_mov_b32 m0, s66
	s_nop 0
	global_load_lds_dwordx4 v[150:151], off
	v_lshl_add_u64 v[150:151], v[238:239], 0, s[52:53]
	s_mov_b32 m0, s67
	s_nop 0
	global_load_lds_dwordx4 v[150:151], off
	s_waitcnt vmcnt(8)
	s_waitcnt lgkmcnt(0)
	s_barrier
	s_setprio 1
	s_waitcnt lgkmcnt(0)
	v_mfma_f32_16x16x32_bf16 v[52:55], v[146:149], v[194:197], v[52:55]
	v_mfma_f32_16x16x32_bf16 v[60:63], v[170:173], v[194:197], v[60:63]
	v_mfma_f32_16x16x32_bf16 v[36:39], v[146:149], v[212:215], v[36:39]
	v_mfma_f32_16x16x32_bf16 v[44:47], v[170:173], v[212:215], v[44:47]
	v_mfma_f32_16x16x32_bf16 v[20:23], v[146:149], v[220:223], v[20:23]
	v_mfma_f32_16x16x32_bf16 v[28:31], v[170:173], v[220:223], v[28:31]
	v_mfma_f32_16x16x32_bf16 v[4:7], v[146:149], v[228:231], v[4:7]
	v_mfma_f32_16x16x32_bf16 v[12:15], v[170:173], v[228:231], v[12:15]
	v_mfma_f32_16x16x32_bf16 v[52:55], v[162:165], v[198:201], v[52:55]
	v_mfma_f32_16x16x32_bf16 v[60:63], v[174:177], v[198:201], v[60:63]
	v_mfma_f32_16x16x32_bf16 v[36:39], v[162:165], v[216:219], v[36:39]
	v_mfma_f32_16x16x32_bf16 v[44:47], v[174:177], v[216:219], v[44:47]
	v_mfma_f32_16x16x32_bf16 v[20:23], v[162:165], v[224:227], v[20:23]
	v_mfma_f32_16x16x32_bf16 v[28:31], v[174:177], v[224:227], v[28:31]
	v_mfma_f32_16x16x32_bf16 v[4:7], v[162:165], v[232:235], v[4:7]
	v_mfma_f32_16x16x32_bf16 v[12:15], v[174:177], v[232:235], v[12:15]
	s_setprio 0
	s_setprio 1
	v_mfma_f32_16x16x32_bf16 v[56:59], v[178:181], v[194:197], v[56:59]
	v_mfma_f32_16x16x32_bf16 v[64:67], v[186:189], v[194:197], v[64:67]
	v_mfma_f32_16x16x32_bf16 v[40:43], v[178:181], v[212:215], v[40:43]
	v_mfma_f32_16x16x32_bf16 v[48:51], v[186:189], v[212:215], v[48:51]
	v_mfma_f32_16x16x32_bf16 v[24:27], v[178:181], v[220:223], v[24:27]
	v_mfma_f32_16x16x32_bf16 v[32:35], v[186:189], v[220:223], v[32:35]
	v_mfma_f32_16x16x32_bf16 v[8:11], v[178:181], v[228:231], v[8:11]
	v_mfma_f32_16x16x32_bf16 v[16:19], v[186:189], v[228:231], v[16:19]
	v_mfma_f32_16x16x32_bf16 v[56:59], v[182:185], v[198:201], v[56:59]
	v_mfma_f32_16x16x32_bf16 v[64:67], v[190:193], v[198:201], v[64:67]
	v_mfma_f32_16x16x32_bf16 v[40:43], v[182:185], v[216:219], v[40:43]
	v_mfma_f32_16x16x32_bf16 v[48:51], v[190:193], v[216:219], v[48:51]
	v_mfma_f32_16x16x32_bf16 v[24:27], v[182:185], v[224:227], v[24:27]
	v_mfma_f32_16x16x32_bf16 v[32:35], v[190:193], v[224:227], v[32:35]
	v_mfma_f32_16x16x32_bf16 v[8:11], v[182:185], v[232:235], v[8:11]
	v_mfma_f32_16x16x32_bf16 v[16:19], v[190:193], v[232:235], v[16:19]
	s_setprio 0
	s_barrier
	s_add_i32 s82, s82, 2
	s_cmp_gt_u32 s82, 13
	s_cbranch_scc0 .LBB0_1266
	s_and_b64 vcc, exec, s[16:17]
	s_cbranch_vccz .LBB0_1269
	s_barrier

;     DI bool next(int i, Unit& u) const { const int L = i * 32 + rank; if (L >= ppg * nN) return false; u.pm = ppg * grp + (L % ppg); const int p0 = L / ppg, p1 = p0 + rot; u.pn = rev ? nN - 1 - p0 : (p1 >= nN ? p1 - nN : p1); return true; }
; #define PG8_WAIT_V(n) asm volatile("s_waitcnt vmcnt(" #n ")" ::: "memory")
; #define PG8_BAR __builtin_amdgcn_s_barrier()
; template <class Epi, class Sched, bool ALIGN_EPI = false, bool SP2 = false>
; __device__ __forceinline__ void gemm_phase(PG8_LAS unsigned char* lds, const Gemm g, const Sched& S, const Epi& E, const int tid) {
;     ...
;     for (int i = 0; i < 2; ++i) { int R, C; stage_rc(tid * 16 + i * 8192, R, C); const int Rb = Epi::PERM ? (2 * (R & ~31) + perm32(R & 31)) : R;
;         voffA[i] = (unsigned)(R * K + C) * 2u; voffB[i] = (unsigned)(Rb * K + C) * 2u; }
;     const size_t kstep = (size_t)(BK * 2);
;     const size_t hstep = (size_t)HALF * K * 2;
;     const size_t tstep = 2 * hstep;
;     const size_t hstepB = Epi::PERM ? (size_t)32 * K * 2 : hstep;
;     const unsigned ldsw = (unsigned)wid * 1024u;
;     const int aoff = lds_byte(wr * 64 + fr, fq * 8), boff = lds_byte(wc * 32 + fr, fq * 8);
;     ...
;     Unit cur, nxt; int ui = 0;
;     if (!S.next(0, cur)) return;
;     f32x4 acc[2][2][4][2];
;     u32x4 iw_[Epi::HAS_INIT ? 16 : 1];
;     if constexpr (Epi::HAS_INIT) E.init_issue(iw_, cur, wr, wc, fr, fq);
;     else {
; #pragma unroll
;     for (int a = 0; a < 2; ++a)
; #pragma unroll
;         for (int b = 0; b < 2; ++b)
; #pragma unroll
;             for (int m = 0; m < 4; ++m)
; #pragma unroll
;                 for (int n = 0; n < 2; ++n) acc[a][b][m][n] = (f32x4){0.f, 0.f, 0.f, 0.f};
;     }
;     bf16x8 At[4][2], B0[2][2], B1[2][2];
;     const char* cA = (const char*)g.A + (size_t)cur.pm * tstep; const char* cB = (const char*)g.Bt + (size_t)cur.pn * tstep;
;     S.a_ready(cur);
;     if constexpr (SP2) {
;         PG8_STAGE(PG8_SB(0, 0), cB, voffB); PG8_STAGE(PG8_SB(0, 1), cB + hstepB, voffB); PG8_STAGE(PG8_SA(0, 0), cA, voffA); PG8_STAGE(PG8_SA(0, 1), cA + hstep, voffA);
;         if (wr == 1) PG8_BAR;
;         PG8_WAIT_V(2); PG8_BAR;
;         PG8_STAGE(PG8_SB(1, 0), cB + kstep, voffB); PG8_STAGE(PG8_SA(1, 0), cA + kstep, voffA); PG8_STAGE(PG8_SB(1, 1), cB + hstepB + kstep, voffB);
;         PG8_WAIT_V(6); PG8_BAR;
.LBB0_1371:
	s_or_b64 exec, exec, s[0:1]
	v_ashrrev_i32_e32 v3, 31, v152
	v_lshrrev_b32_e32 v3, 26, v3
	v_add_u32_e32 v3, v152, v3
	v_ashrrev_i32_e32 v12, 6, v3
	v_bfe_i32 v3, v152, 27, 1
	v_lshlrev_b32_e32 v4, 4, v152
	v_lshrrev_b32_e32 v3, 22, v3
	v_add_u32_e32 v3, v4, v3
	v_and_b32_e32 v3, 0xfffffc00, v3
	v_sub_u32_e32 v3, v4, v3
	v_lshrrev_b32_e32 v5, 4, v3
	s_lshl_b64 s[0:1], s[6:7], 23
	v_bitop3_b32 v3, v5, v3, 32 bitop3:0x6c
	s_add_u32 s6, s4, s0
	v_ashrrev_i32_e32 v6, 31, v3
	s_addc_u32 s7, s5, s1
	v_lshrrev_b32_e32 v6, 26, v6
	s_add_u32 s10, s6, 0x2100000
	v_add_u32_e32 v6, v3, v6
	s_addc_u32 s11, s7, 0
	v_lshlrev_b32_e32 v5, 3, v12
	v_ashrrev_i32_e32 v13, 6, v6
	v_and_b32_e32 v6, 0xc0, v6
	s_add_u32 s6, s4, 0xc300000
	v_and_b32_e32 v5, -16, v5
	v_sub_u32_e32 v3, v3, v6
	s_addc_u32 s7, s5, 0
	v_add_u32_e32 v133, v13, v5
	v_ashrrev_i16_sdwa v3, v205, sext(v3) dst_sel:DWORD dst_unused:UNUSED_PAD src0_sel:DWORD src1_sel:BYTE_0
	s_add_u32 s4, s4, 0x17100000
	v_lshlrev_b32_e32 v5, 5, v12
	v_bfe_i32 v14, v3, 0, 16
	v_lshrrev_b32_e32 v3, 2, v133
	s_addc_u32 s5, s5, 0
	v_and_b32_e32 v5, 32, v5
	v_and_b32_e32 v154, 4, v3
	v_lshrrev_b32_e32 v3, 1, v152
	v_readfirstlane_b32 s14, v152
	v_add_u32_e32 v132, v5, v14
	v_lshlrev_b32_e32 v156, 1, v133
	v_and_b32_e32 v155, 3, v13
	v_and_b32_e32 v153, 15, v152
	s_cmpk_gt_i32 s40, 0x7f
	v_and_b32_e32 v3, 24, v3
	s_waitcnt lgkmcnt(0)
	s_barrier
	s_cbranch_scc1 .LBB0_1387
	v_add_u32_e32 v4, 0x2000, v4
	v_ashrrev_i32_e32 v5, 31, v4
	v_lshrrev_b32_e32 v5, 22, v5
	v_add_u32_e32 v5, v4, v5
	v_ashrrev_i32_e32 v15, 10, v5
	v_mul_i32_i24_e32 v5, 0x400, v15
	v_sub_u32_e32 v4, v4, v5
	v_lshrrev_b32_e32 v5, 4, v4
	v_bitop3_b32 v4, v5, v4, 32 bitop3:0x6c
	v_ashrrev_i32_e32 v5, 31, v4
	v_lshrrev_b32_e32 v5, 26, v5
	v_add_u32_e32 v5, v4, v5
	v_lshlrev_b32_e32 v6, 3, v15
	v_ashrrev_i32_e32 v16, 6, v5
	v_and_b32_e32 v6, -16, v6
	s_lshr_b32 s12, s40, 29
	v_add_u32_e32 v6, v16, v6
	s_add_i32 s12, s40, s12
	v_lshrrev_b32_e32 v7, 2, v6
	v_lshlrev_b32_e32 v9, 1, v6
	v_and_b32_e32 v5, 0xc0, v5
	s_and_b32 s13, s12, -8
	v_and_b32_e32 v7, 4, v7
	v_and_b32_e32 v8, 3, v16
	v_and_b32_e32 v9, 0x1fffd8, v9
	v_sub_u32_e32 v4, v4, v5
	s_lshl_b32 s43, s27, 3
	s_sub_i32 s13, s40, s13
	v_or3_b32 v7, v8, v7, v9
	v_lshlrev_b32_e32 v8, 5, v15
	v_ashrrev_i16_sdwa v4, v205, sext(v4) dst_sel:DWORD dst_unused:UNUSED_PAD src0_sel:DWORD src1_sel:BYTE_0
	s_add_i32 s28, s43, s13
	s_ashr_i32 s12, s12, 3
	s_ashr_i32 s15, s14, 6
	v_and_b32_e32 v8, 32, v8
	v_bfe_i32 v17, v4, 0, 16
	s_sub_i32 s34, 15, s12
	s_ashr_i32 s29, s28, 31
	s_ashr_i32 s16, s14, 8
	s_lshl_b32 s42, s15, 10
	v_add_lshl_u32 v4, v8, v17, 1
	s_lshl_b64 s[12:13], s[28:29], 19
	s_lshl_b64 s[18:19], s[34:35], 19
	v_lshl_add_u32 v134, v7, 11, v4
	v_lshl_add_u32 v136, v6, 11, v4
	v_and_b32_e32 v4, 0x1fffd8, v156
	s_lshr_b32 s32, s2, 3
	s_lshr_b32 s99, s2, 6
	s_add_i32 s32, s32, s99
	s_and_b32 s32, s32, 3
	s_lshl_b32 s32, s32, 8
	s_add_u32 s36, s10, s18
	v_or3_b32 v4, v155, v4, v154
	v_lshlrev_b32_e32 v5, 1, v132
	s_addc_u32 s37, s11, s19
	s_add_u32 s36, s36, s32
	s_addc_u32 s37, s37, 0
	s_add_i32 s29, s42, 0
	v_lshl_add_u32 v138, v4, 11, v5
	s_add_i32 m0, s29, 0x10000
	v_lshl_add_u32 v140, v133, 11, v5
	global_load_lds_dwordx4 v138, s[36:37]
	s_add_i32 m0, s29, 0x12000
	s_add_u32 s18, s36, 0x10000
	global_load_lds_dwordx4 v134, s[36:37]
	s_addc_u32 s19, s37, 0
	s_add_i32 m0, s29, 0x14000
	v_mov_b32_e32 v139, v2
	global_load_lds_dwordx4 v138, s[18:19]
	s_add_i32 m0, s29, 0x16000
	s_add_u32 s30, s6, s12
	s_addc_u32 s31, s7, s13
	s_add_u32 s30, s30, s32
	s_addc_u32 s31, s31, 0
	s_add_i32 s54, s29, 0x2000
	global_load_lds_dwordx4 v134, s[18:19]
	s_mov_b32 m0, s29
	s_add_u32 s12, s30, 0x40000
	global_load_lds_dwordx4 v140, s[30:31]
	s_mov_b32 m0, s54
	s_addc_u32 s13, s31, 0
	s_add_i32 s55, s29, 0x4000
	global_load_lds_dwordx4 v136, s[30:31]
	s_mov_b32 m0, s55
	s_add_i32 s62, s29, 0x6000
	global_load_lds_dwordx4 v140, s[12:13]
	s_mov_b32 m0, s62
	v_mov_b32_e32 v135, v2
	global_load_lds_dwordx4 v136, s[12:13]
	v_mov_b32_e32 v141, v2
	v_mov_b32_e32 v137, v2
	s_cmp_eq_u32 s16, 1
	v_lshl_add_u64 v[10:11], s[36:37], 0, v[138:139]
	v_lshl_add_u64 v[8:9], s[36:37], 0, v[134:135]
	v_lshl_add_u64 v[4:5], s[30:31], 0, v[140:141]
	s_cselect_b64 s[12:13], -1, 0
	s_cmp_lg_u32 s16, 1
	v_lshl_add_u64 v[6:7], s[30:31], 0, v[136:137]
	s_cbranch_scc1 .LBB0_1374
	s_barrier
.LBB0_1374:
	v_lshlrev_b32_e32 v18, 1, v3
	v_lshlrev_b32_e32 v19, 2, v153
	s_and_b32 s17, s15, 3
	v_lshl_or_b32 v18, v153, 6, v18
	s_lshl_b32 s15, s16, 13
	v_and_b32_e32 v20, 32, v19
	s_add_i32 m0, s29, 0x18000
	v_lshl_add_u64 v[10:11], v[10:11], 0, s[52:53]
	v_bitop3_b32 v21, v18, s15, v20 bitop3:0xde
	s_lshl_b32 s15, s17, 12
	s_waitcnt vmcnt(2)
	s_barrier
	global_load_lds_dwordx4 v[10:11], off
	v_lshl_add_u64 v[8:9], v[8:9], 0, s[52:53]
	s_add_i32 m0, s29, 0x1a000
	s_add_i32 s63, s29, 0x8000
	s_add_i32 s64, s29, 0xa000
	global_load_lds_dwordx4 v[8:9], off
	v_lshl_add_u64 v[4:5], v[4:5], 0, s[52:53]
	s_mov_b32 m0, s63
	s_add_u32 s18, s36, 0x10080
	global_load_lds_dwordx4 v[4:5], off
	v_lshl_add_u64 v[4:5], v[6:7], 0, s[52:53]
	s_mov_b32 m0, s64
	s_addc_u32 s19, s37, 0
	global_load_lds_dwordx4 v[4:5], off
	s_add_i32 m0, s29, 0x1c000
	v_lshl_add_u64 v[4:5], s[18:19], 0, v[138:139]
	global_load_lds_dwordx4 v[4:5], off
	v_lshl_add_u64 v[4:5], s[18:19], 0, v[134:135]
	s_add_i32 m0, s29, 0x1e000
	s_cmpk_lt_u32 s14, 0x100
	global_load_lds_dwordx4 v[4:5], off
	v_cmp_lt_u32_e32 vcc, 7, v153
	v_bitop3_b32 v158, s15, v18, v20 bitop3:0xf6
	s_cselect_b64 s[14:15], -1, 0
	s_lshl_b32 s17, s17, 6
	v_cndmask_b32_e64 v4, 0, 32, vcc
	v_or3_b32 v162, s17, v4, v3
	v_lshlrev_b32_e32 v4, 14, v12
	v_and_b32_e32 v4, 0xffff8000, v4
	v_lshl_add_u32 v4, v13, 11, v4
	v_and_b32_e32 v5, 1, v12
	v_lshl_or_b32 v4, v5, 6, v4
	v_lshl_add_u32 v142, v14, 1, v4
	v_lshlrev_b32_e32 v4, 14, v15
	v_lshl_or_b32 v157, s16, 6, v153
	s_lshl_b32 s16, s16, 8
	v_and_b32_e32 v4, 0xffff8000, v4
	s_waitcnt vmcnt(6)
	s_add_i32 s16, s16, 0
	v_lshl_add_u32 v4, v16, 11, v4
	v_and_b32_e32 v5, 1, v15
	s_add_i32 s16, s16, 0x20000
	v_lshl_or_b32 v4, v5, 6, v4
	s_mov_b32 s65, 0
	v_cndmask_b32_e64 v159, 0, -8, vcc
	v_cndmask_b32_e64 v160, 8, 0, vcc
	v_add_u32_e32 v161, s16, v19
	v_mov_b32_e32 v143, v2
	v_lshl_add_u32 v144, v17, 1, v4
	v_mov_b32_e32 v145, v2
	v_add_u32_e32 v163, 0, v21
	s_barrier
	s_sub_u32 s36, s36, s32
	s_subb_u32 s37, s37, 0
	s_sub_u32 s30, s30, s32
	s_subb_u32 s31, s31, 0
	s_branch .LBB0_1377

; #define PG8_STAGE(bufoff, gbase, voff) do { _Pragma("unroll") for (int _i = 0; _i < 2; ++_i) \
;         __builtin_amdgcn_global_load_lds((const unsigned*)((const char*)(gbase) + (voff)[_i]), (PG8_LAS unsigned*)(lds + (bufoff) + ldsw + _i * 8192), 16, 0, 0); } while (0)
; #define PG8_LDA(dst, b, h) do { _Pragma("unroll") for (int m = 0; m < 4; ++m) _Pragma("unroll") for (int k = 0; k < 2; ++k) dst[m][k] = *(const PG8_LAS bf16x8*)(lds + PG8_SA(b, h) + aoff + m * 2048 + k * 1024); } while (0)
; #define PG8_LDB(dst, b, h) do { _Pragma("unroll") for (int n = 0; n < 2; ++n) _Pragma("unroll") for (int k = 0; k < 2; ++k) dst[n][k] = *(const PG8_LAS bf16x8*)(lds + PG8_SB(b, h) + boff + n * 2048 + k * 1024); } while (0)
; #define PG8_WAIT_V(n) asm volatile("s_waitcnt vmcnt(" #n ")" ::: "memory")
; #define PG8_WAIT_L(n) asm volatile("s_waitcnt lgkmcnt(" #n ")" ::: "memory")
; #define PG8_BAR __builtin_amdgcn_s_barrier()
; #define PG8_SCHED __builtin_amdgcn_sched_barrier(0)
; template <class Epi, class Sched, bool ALIGN_EPI = false, bool SP2 = false>
; __device__ __forceinline__ void gemm_phase(PG8_LAS unsigned char* lds, const Gemm g, const Sched& S, const Epi& E, const int tid) {
;     ...
;         const char* nA = has_next ? (const char*)g.A + (size_t)nxt.pm * tstep : cA; const char* nB = has_next ? (const char*)g.Bt + (size_t)nxt.pn * tstep : cB;
;         for (int t = 0; t < nt; t += 2) {
;             const bool last = (t == nt - 2);
;             const char* a1 = cA + (size_t)(t + 1) * kstep;
;             const char* a2 = last ? nA : cA + (size_t)(t + 2) * kstep; const char* b2 = last ? nB : cB + (size_t)(t + 2) * kstep;
;             const char* a3 = a2 + kstep; const char* b3 = b2 + kstep;
;             if (last && has_next) S.a_ready(nxt);
;             if constexpr (SP2) {
;             PG8_LDB(B0, 0, 0); PG8_LDB(B1, 0, 1); PG8_SCHED; PG8_LDA(At, 0, 0); PG8_STAGE(PG8_SA(1, 1), a1 + hstep, voffA);
;             PG8_WAIT_V(8); PG8_WAIT_L(0); PG8_BAR; PG8_MMA(0, 0, At, B0); PG8_MMA(0, 1, At, B1); PG8_BAR; PG8_SCHED;
;     ...
;         else {
; #pragma unroll
;         for (int a = 0; a < 2; ++a)
; #pragma unroll
;             for (int b = 0; b < 2; ++b)
; #pragma unroll
;                 for (int m = 0; m < 4; ++m)
; #pragma unroll
;                     for (int n = 0; n < 2; ++n) acc[a][b][m][n] = (f32x4){0.f, 0.f, 0.f, 0.f};
;         }
.LBB0_1379:
	s_ashr_i32 s17, s16, 31
	s_lshl_b64 s[20:21], s[16:17], 19
	s_add_u32 s20, s6, s20
	s_addc_u32 s21, s7, s21
	s_and_b64 s[24:25], s[22:23], exec
	s_cselect_b32 s17, s21, s31
	s_cselect_b32 s66, s20, s30
	s_add_u32 s66, s66, s32
	s_addc_u32 s17, s17, 0
	s_ashr_i32 s19, s18, 31
	s_lshl_b64 s[24:25], s[18:19], 19
	s_add_u32 s24, s10, s24
	s_addc_u32 s25, s11, s25
	s_and_b64 s[38:39], s[22:23], exec
	s_cselect_b32 s19, s25, s37
	s_cselect_b32 s67, s24, s36
	s_add_u32 s67, s67, s32
	s_addc_u32 s19, s19, 0
	s_add_u32 s30, s30, 0x40080
	s_addc_u32 s31, s31, 0
	s_mov_b32 s76, s36
	v_mov_b32_e32 v4, 0
	s_mov_b32 s78, s37
	s_mov_b32 s79, -2
	v_mov_b32_e32 v5, v4
	v_mov_b32_e32 v6, v4
	v_mov_b32_e32 v7, v4
	v_mov_b32_e32 v8, v4
	v_mov_b32_e32 v9, v4
	v_mov_b32_e32 v10, v4
	v_mov_b32_e32 v11, v4
	v_mov_b32_e32 v20, v4
	v_mov_b32_e32 v21, v4
	v_mov_b32_e32 v22, v4
	v_mov_b32_e32 v23, v4
	v_mov_b32_e32 v24, v4
	v_mov_b32_e32 v25, v4
	v_mov_b32_e32 v26, v4
	v_mov_b32_e32 v27, v4
	v_mov_b32_e32 v36, v4
	v_mov_b32_e32 v37, v4
	v_mov_b32_e32 v38, v4
	v_mov_b32_e32 v39, v4
	v_mov_b32_e32 v40, v4
	v_mov_b32_e32 v41, v4
	v_mov_b32_e32 v42, v4
	v_mov_b32_e32 v43, v4
	v_mov_b32_e32 v52, v4
	v_mov_b32_e32 v53, v4
	v_mov_b32_e32 v54, v4
	v_mov_b32_e32 v55, v4
	v_mov_b32_e32 v56, v4
	v_mov_b32_e32 v57, v4
	v_mov_b32_e32 v58, v4
	v_mov_b32_e32 v59, v4
	v_mov_b32_e32 v12, v4
	v_mov_b32_e32 v13, v4
	v_mov_b32_e32 v14, v4
	v_mov_b32_e32 v15, v4
	v_mov_b32_e32 v16, v4
	v_mov_b32_e32 v17, v4
	v_mov_b32_e32 v18, v4
	v_mov_b32_e32 v19, v4
	v_mov_b32_e32 v28, v4
	v_mov_b32_e32 v29, v4
	v_mov_b32_e32 v30, v4
	v_mov_b32_e32 v31, v4
	v_mov_b32_e32 v32, v4
	v_mov_b32_e32 v33, v4
	v_mov_b32_e32 v34, v4
	v_mov_b32_e32 v35, v4
	v_mov_b32_e32 v44, v4
	v_mov_b32_e32 v45, v4
	v_mov_b32_e32 v46, v4
	v_mov_b32_e32 v47, v4
	v_mov_b32_e32 v48, v4
	v_mov_b32_e32 v49, v4
	v_mov_b32_e32 v50, v4
	v_mov_b32_e32 v51, v4
	v_mov_b32_e32 v60, v4
	v_mov_b32_e32 v61, v4
	v_mov_b32_e32 v62, v4
	v_mov_b32_e32 v63, v4
	v_mov_b32_e32 v64, v4
	v_mov_b32_e32 v65, v4
	v_mov_b32_e32 v66, v4
	v_mov_b32_e32 v67, v4
	v_mov_b32_e32 v68, v4
	v_mov_b32_e32 v69, v4
	v_mov_b32_e32 v70, v4
	v_mov_b32_e32 v71, v4
	v_mov_b32_e32 v72, v4
	v_mov_b32_e32 v73, v4
	v_mov_b32_e32 v74, v4
	v_mov_b32_e32 v75, v4
	v_mov_b32_e32 v84, v4
	v_mov_b32_e32 v85, v4
	v_mov_b32_e32 v86, v4
	v_mov_b32_e32 v87, v4
	v_mov_b32_e32 v88, v4
	v_mov_b32_e32 v89, v4
	v_mov_b32_e32 v90, v4
	v_mov_b32_e32 v91, v4
	v_mov_b32_e32 v100, v4
	v_mov_b32_e32 v101, v4
	v_mov_b32_e32 v102, v4
	v_mov_b32_e32 v103, v4
	v_mov_b32_e32 v104, v4
	v_mov_b32_e32 v105, v4
	v_mov_b32_e32 v106, v4
	v_mov_b32_e32 v107, v4
	v_mov_b32_e32 v116, v4
	v_mov_b32_e32 v117, v4
	v_mov_b32_e32 v118, v4
	v_mov_b32_e32 v119, v4
	v_mov_b32_e32 v120, v4
	v_mov_b32_e32 v121, v4
	v_mov_b32_e32 v122, v4
	v_mov_b32_e32 v123, v4
	v_mov_b32_e32 v76, v4
	v_mov_b32_e32 v77, v4
	v_mov_b32_e32 v78, v4
	v_mov_b32_e32 v79, v4
	v_mov_b32_e32 v80, v4
	v_mov_b32_e32 v81, v4
	v_mov_b32_e32 v82, v4
	v_mov_b32_e32 v83, v4
	v_mov_b32_e32 v92, v4
	v_mov_b32_e32 v93, v4
	v_mov_b32_e32 v94, v4
	v_mov_b32_e32 v95, v4
	v_mov_b32_e32 v96, v4
	v_mov_b32_e32 v97, v4
	v_mov_b32_e32 v98, v4
	v_mov_b32_e32 v99, v4
	v_mov_b32_e32 v108, v4
	v_mov_b32_e32 v109, v4
	v_mov_b32_e32 v110, v4
	v_mov_b32_e32 v111, v4
	v_mov_b32_e32 v112, v4
	v_mov_b32_e32 v113, v4
	v_mov_b32_e32 v114, v4
	v_mov_b32_e32 v115, v4
	v_mov_b32_e32 v124, v4
	v_mov_b32_e32 v125, v4
	v_mov_b32_e32 v126, v4
	v_mov_b32_e32 v127, v4
	v_mov_b32_e32 v128, v4
	v_mov_b32_e32 v129, v4
	v_mov_b32_e32 v130, v4
	v_mov_b32_e32 v131, v4
.LBB0_1380:
	s_lshl_b32 s100, s79, 7
	s_add_i32 s100, s100, s32
	s_add_i32 s100, s100, 0x100
	s_add_i32 s99, s100, 0x100
	s_and_b32 s100, s100, 0x700
	s_and_b32 s99, s99, 0x700
	s_add_u32 s100, s30, s100
	s_addc_u32 s101, s31, 0
	s_add_u32 s36, s30, 0xfffbff80
	s_addc_u32 s37, s31, -1
	s_add_u32 s36, s36, s99
	s_addc_u32 s37, s37, 0
	s_add_i32 s80, 0, 0x10000
	s_cmp_eq_u32 s79, 12
	s_cselect_b32 s39, s17, s37
	s_cselect_b32 s38, s66, s36
	v_add_u32_e32 v150, s80, v158
	s_add_u32 s36, s76, s99
	s_addc_u32 s37, s78, 0
	s_cmp_eq_u32 s79, 12
	s_cselect_b32 s37, s19, s37
	s_cselect_b32 s36, s67, s36
	s_add_i32 s82, 0, 0x14000
	ds_read_b128 v[146:149], v150
	ds_read_b128 v[164:167], v150 offset:1024
	ds_read_b128 v[170:173], v150 offset:2048
	ds_read_b128 v[174:177], v150 offset:3072
	v_add_u32_e32 v150, s82, v158
	ds_read_b128 v[178:181], v150
	ds_read_b128 v[182:185], v150 offset:1024
	ds_read_b128 v[186:189], v150 offset:2048
	ds_read_b128 v[190:193], v150 offset:3072
	v_lshl_add_u64 v[150:151], s[100:101], 0, v[142:143]
	s_add_i32 m0, s29, 0xc000
	ds_read_b128 v[194:197], v163
	ds_read_b128 v[198:201], v163 offset:1024
	ds_read_b128 v[212:215], v163 offset:2048
	ds_read_b128 v[216:219], v163 offset:3072
	ds_read_b128 v[220:223], v163 offset:4096
	ds_read_b128 v[224:227], v163 offset:5120
	ds_read_b128 v[228:231], v163 offset:6144
	ds_read_b128 v[232:235], v163 offset:7168
	global_load_lds_dwordx4 v[150:151], off
	v_lshl_add_u64 v[150:151], s[100:101], 0, v[144:145]
	s_add_i32 m0, s29, 0xe000
	s_nop 0
	global_load_lds_dwordx4 v[150:151], off
	s_waitcnt vmcnt(8)
	s_waitcnt lgkmcnt(0)
	s_barrier
; #define PG8_STAGE(bufoff, gbase, voff) do { _Pragma("unroll") for (int _i = 0; _i < 2; ++_i) \
;         __builtin_amdgcn_global_load_lds((const unsigned*)((const char*)(gbase) + (voff)[_i]), (PG8_LAS unsigned*)(lds + (bufoff) + ldsw + _i * 8192), 16, 0, 0); } while (0)
; #define PG8_LDA(dst, b, h) do { _Pragma("unroll") for (int m = 0; m < 4; ++m) _Pragma("unroll") for (int k = 0; k < 2; ++k) dst[m][k] = *(const PG8_LAS bf16x8*)(lds + PG8_SA(b, h) + aoff + m * 2048 + k * 1024); } while (0)
; #define PG8_LDB(dst, b, h) do { _Pragma("unroll") for (int n = 0; n < 2; ++n) _Pragma("unroll") for (int k = 0; k < 2; ++k) dst[n][k] = *(const PG8_LAS bf16x8*)(lds + PG8_SB(b, h) + boff + n * 2048 + k * 1024); } while (0)
; #define PG8_MMA(ai, bj, At, Bt) do { __builtin_amdgcn_s_setprio(1); _Pragma("unroll") for (int m = 0; m < 4; ++m) _Pragma("unroll") for (int n = 0; n < 2; ++n) _Pragma("unroll") for (int k = 0; k < 2; ++k) \
;         acc[ai][bj][m][n] = __builtin_amdgcn_mfma_f32_16x16x32_bf16(Bt[n][k], At[m][k], acc[ai][bj][m][n], 0, 0, 0); __builtin_amdgcn_s_setprio(0); } while (0)
; #define PG8_WAIT_V(n) asm volatile("s_waitcnt vmcnt(" #n ")" ::: "memory")
; #define PG8_WAIT_L(n) asm volatile("s_waitcnt lgkmcnt(" #n ")" ::: "memory")
; #define PG8_BAR __builtin_amdgcn_s_barrier()
; #define PG8_SCHED __builtin_amdgcn_sched_barrier(0)
; template <class Epi, class Sched, bool ALIGN_EPI = false, bool SP2 = false>
; __device__ __forceinline__ void gemm_phase(PG8_LAS unsigned char* lds, const Gemm g, const Sched& S, const Epi& E, const int tid) {
;     ...
;             PG8_LDB(B0, 0, 0); PG8_LDB(B1, 0, 1); PG8_SCHED; PG8_LDA(At, 0, 0); PG8_STAGE(PG8_SA(1, 1), a1 + hstep, voffA);
;             PG8_WAIT_V(8); PG8_WAIT_L(0); PG8_BAR; PG8_MMA(0, 0, At, B0); PG8_MMA(0, 1, At, B1); PG8_BAR; PG8_SCHED;
;             PG8_LDA(At, 0, 1); PG8_STAGE(PG8_SB(0, 0), b2, voffB); PG8_STAGE(PG8_SB(0, 1), b2 + hstepB, voffB); PG8_STAGE(PG8_SA(0, 0), a2, voffA);
;             PG8_WAIT_V(8); PG8_WAIT_L(0); PG8_BAR; PG8_MMA(1, 0, At, B0); PG8_MMA(1, 1, At, B1); PG8_BAR; PG8_SCHED;
	s_setprio 1
	s_waitcnt lgkmcnt(0)
	v_mfma_f32_16x16x32_bf16 v[128:131], v[146:149], v[194:197], v[128:131]
	v_mfma_f32_16x16x32_bf16 v[124:127], v[170:173], v[194:197], v[124:127]
	v_mfma_f32_16x16x32_bf16 v[112:115], v[146:149], v[212:215], v[112:115]
	v_mfma_f32_16x16x32_bf16 v[108:111], v[170:173], v[212:215], v[108:111]
	v_mfma_f32_16x16x32_bf16 v[96:99], v[146:149], v[220:223], v[96:99]
	v_mfma_f32_16x16x32_bf16 v[92:95], v[170:173], v[220:223], v[92:95]
	v_mfma_f32_16x16x32_bf16 v[80:83], v[146:149], v[228:231], v[80:83]
	v_mfma_f32_16x16x32_bf16 v[76:79], v[170:173], v[228:231], v[76:79]
	v_mfma_f32_16x16x32_bf16 v[128:131], v[164:167], v[198:201], v[128:131]
	v_mfma_f32_16x16x32_bf16 v[124:127], v[174:177], v[198:201], v[124:127]
	v_mfma_f32_16x16x32_bf16 v[112:115], v[164:167], v[216:219], v[112:115]
	v_mfma_f32_16x16x32_bf16 v[108:111], v[174:177], v[216:219], v[108:111]
	v_mfma_f32_16x16x32_bf16 v[96:99], v[164:167], v[224:227], v[96:99]
	v_mfma_f32_16x16x32_bf16 v[92:95], v[174:177], v[224:227], v[92:95]
	v_mfma_f32_16x16x32_bf16 v[80:83], v[164:167], v[232:235], v[80:83]
	v_mfma_f32_16x16x32_bf16 v[76:79], v[174:177], v[232:235], v[76:79]
	s_setprio 0
	s_setprio 1
	v_mfma_f32_16x16x32_bf16 v[120:123], v[178:181], v[194:197], v[120:123]
	v_mfma_f32_16x16x32_bf16 v[116:119], v[186:189], v[194:197], v[116:119]
	v_mfma_f32_16x16x32_bf16 v[104:107], v[178:181], v[212:215], v[104:107]
	v_mfma_f32_16x16x32_bf16 v[100:103], v[186:189], v[212:215], v[100:103]
	v_mfma_f32_16x16x32_bf16 v[88:91], v[178:181], v[220:223], v[88:91]
	v_mfma_f32_16x16x32_bf16 v[84:87], v[186:189], v[220:223], v[84:87]
	v_mfma_f32_16x16x32_bf16 v[72:75], v[178:181], v[228:231], v[72:75]
	v_mfma_f32_16x16x32_bf16 v[68:71], v[186:189], v[228:231], v[68:71]
	v_mfma_f32_16x16x32_bf16 v[120:123], v[182:185], v[198:201], v[120:123]
	v_mfma_f32_16x16x32_bf16 v[116:119], v[190:193], v[198:201], v[116:119]
	v_mfma_f32_16x16x32_bf16 v[104:107], v[182:185], v[216:219], v[104:107]
	v_mfma_f32_16x16x32_bf16 v[100:103], v[190:193], v[216:219], v[100:103]
	v_mfma_f32_16x16x32_bf16 v[88:91], v[182:185], v[224:227], v[88:91]
	v_mfma_f32_16x16x32_bf16 v[84:87], v[190:193], v[224:227], v[84:87]
	v_mfma_f32_16x16x32_bf16 v[72:75], v[182:185], v[232:235], v[72:75]
	v_mfma_f32_16x16x32_bf16 v[68:71], v[190:193], v[232:235], v[68:71]
	s_setprio 0
	s_barrier
	s_add_i32 s80, s80, s42
	v_lshl_add_u64 v[150:151], s[36:37], 0, v[138:139]
	s_mov_b32 m0, s80
	ds_read_b128 v[194:197], v163 offset:16384
	ds_read_b128 v[198:201], v163 offset:17408
	ds_read_b128 v[212:215], v163 offset:18432
	ds_read_b128 v[216:219], v163 offset:19456
	ds_read_b128 v[220:223], v163 offset:20480
	ds_read_b128 v[224:227], v163 offset:21504
	ds_read_b128 v[228:231], v163 offset:22528
	ds_read_b128 v[232:235], v163 offset:23552
	global_load_lds_dwordx4 v[150:151], off
	s_add_i32 m0, s80, 0x2000
	s_add_u32 s80, s36, 0x10000
	v_lshl_add_u64 v[236:237], s[36:37], 0, v[134:135]
	s_addc_u32 s81, s37, 0
	s_add_i32 s82, s82, s42
	global_load_lds_dwordx4 v[236:237], off
	v_lshl_add_u64 v[238:239], s[80:81], 0, v[138:139]
	s_mov_b32 m0, s82
	v_lshl_add_u64 v[240:241], s[38:39], 0, v[136:137]
	global_load_lds_dwordx4 v[238:239], off
	v_lshl_add_u64 v[238:239], s[80:81], 0, v[134:135]
	s_add_i32 m0, s82, 0x2000
	s_nop 0
	global_load_lds_dwordx4 v[238:239], off
	v_lshl_add_u64 v[238:239], s[38:39], 0, v[140:141]
	s_mov_b32 m0, s29
	s_nop 0
	global_load_lds_dwordx4 v[238:239], off
	s_mov_b32 m0, s54
	s_nop 0
	global_load_lds_dwordx4 v[240:241], off
	s_waitcnt vmcnt(8)
	s_waitcnt lgkmcnt(0)
	s_barrier
	s_setprio 1
	s_waitcnt lgkmcnt(0)
	v_mfma_f32_16x16x32_bf16 v[64:67], v[146:149], v[194:197], v[64:67]
	v_mfma_f32_16x16x32_bf16 v[60:63], v[170:173], v[194:197], v[60:63]
	v_mfma_f32_16x16x32_bf16 v[48:51], v[146:149], v[212:215], v[48:51]
	v_mfma_f32_16x16x32_bf16 v[44:47], v[170:173], v[212:215], v[44:47]
	v_mfma_f32_16x16x32_bf16 v[32:35], v[146:149], v[220:223], v[32:35]
	v_mfma_f32_16x16x32_bf16 v[28:31], v[170:173], v[220:223], v[28:31]
	v_mfma_f32_16x16x32_bf16 v[16:19], v[146:149], v[228:231], v[16:19]
	v_mfma_f32_16x16x32_bf16 v[12:15], v[170:173], v[228:231], v[12:15]
	v_mfma_f32_16x16x32_bf16 v[64:67], v[164:167], v[198:201], v[64:67]
	v_mfma_f32_16x16x32_bf16 v[60:63], v[174:177], v[198:201], v[60:63]
	v_mfma_f32_16x16x32_bf16 v[48:51], v[164:167], v[216:219], v[48:51]
	v_mfma_f32_16x16x32_bf16 v[44:47], v[174:177], v[216:219], v[44:47]
	v_mfma_f32_16x16x32_bf16 v[32:35], v[164:167], v[224:227], v[32:35]
	v_mfma_f32_16x16x32_bf16 v[28:31], v[174:177], v[224:227], v[28:31]
	v_mfma_f32_16x16x32_bf16 v[16:19], v[164:167], v[232:235], v[16:19]
	v_mfma_f32_16x16x32_bf16 v[12:15], v[174:177], v[232:235], v[12:15]
	s_setprio 0
	s_setprio 1
	v_mfma_f32_16x16x32_bf16 v[56:59], v[178:181], v[194:197], v[56:59]
	v_mfma_f32_16x16x32_bf16 v[52:55], v[186:189], v[194:197], v[52:55]
	v_mfma_f32_16x16x32_bf16 v[40:43], v[178:181], v[212:215], v[40:43]
	v_mfma_f32_16x16x32_bf16 v[36:39], v[186:189], v[212:215], v[36:39]
	v_mfma_f32_16x16x32_bf16 v[24:27], v[178:181], v[220:223], v[24:27]
	v_mfma_f32_16x16x32_bf16 v[20:23], v[186:189], v[220:223], v[20:23]
	v_mfma_f32_16x16x32_bf16 v[8:11], v[178:181], v[228:231], v[8:11]
	v_mfma_f32_16x16x32_bf16 v[4:7], v[186:189], v[228:231], v[4:7]
	v_mfma_f32_16x16x32_bf16 v[56:59], v[182:185], v[198:201], v[56:59]
	v_mfma_f32_16x16x32_bf16 v[52:55], v[190:193], v[198:201], v[52:55]
	v_mfma_f32_16x16x32_bf16 v[40:43], v[182:185], v[216:219], v[40:43]
	v_mfma_f32_16x16x32_bf16 v[36:39], v[190:193], v[216:219], v[36:39]
	v_mfma_f32_16x16x32_bf16 v[24:27], v[182:185], v[224:227], v[24:27]
	v_mfma_f32_16x16x32_bf16 v[20:23], v[190:193], v[224:227], v[20:23]
	v_mfma_f32_16x16x32_bf16 v[8:11], v[182:185], v[232:235], v[8:11]
	v_mfma_f32_16x16x32_bf16 v[4:7], v[190:193], v[232:235], v[4:7]
	s_setprio 0
	s_barrier
; #define PG8_STAGE(bufoff, gbase, voff) do { _Pragma("unroll") for (int _i = 0; _i < 2; ++_i) \
;         __builtin_amdgcn_global_load_lds((const unsigned*)((const char*)(gbase) + (voff)[_i]), (PG8_LAS unsigned*)(lds + (bufoff) + ldsw + _i * 8192), 16, 0, 0); } while (0)
; #define PG8_LDA(dst, b, h) do { _Pragma("unroll") for (int m = 0; m < 4; ++m) _Pragma("unroll") for (int k = 0; k < 2; ++k) dst[m][k] = *(const PG8_LAS bf16x8*)(lds + PG8_SA(b, h) + aoff + m * 2048 + k * 1024); } while (0)
; #define PG8_LDB(dst, b, h) do { _Pragma("unroll") for (int n = 0; n < 2; ++n) _Pragma("unroll") for (int k = 0; k < 2; ++k) dst[n][k] = *(const PG8_LAS bf16x8*)(lds + PG8_SB(b, h) + boff + n * 2048 + k * 1024); } while (0)
; #define PG8_MMA(ai, bj, At, Bt) do { __builtin_amdgcn_s_setprio(1); _Pragma("unroll") for (int m = 0; m < 4; ++m) _Pragma("unroll") for (int n = 0; n < 2; ++n) _Pragma("unroll") for (int k = 0; k < 2; ++k) \
;         acc[ai][bj][m][n] = __builtin_amdgcn_mfma_f32_16x16x32_bf16(Bt[n][k], At[m][k], acc[ai][bj][m][n], 0, 0, 0); __builtin_amdgcn_s_setprio(0); } while (0)
; #define PG8_WAIT_V(n) asm volatile("s_waitcnt vmcnt(" #n ")" ::: "memory")
; #define PG8_WAIT_L(n) asm volatile("s_waitcnt lgkmcnt(" #n ")" ::: "memory")
; #define PG8_BAR __builtin_amdgcn_s_barrier()
; #define PG8_SCHED __builtin_amdgcn_sched_barrier(0)
; template <class Epi, class Sched, bool ALIGN_EPI = false, bool SP2 = false>
; __device__ __forceinline__ void gemm_phase(PG8_LAS unsigned char* lds, const Gemm g, const Sched& S, const Epi& E, const int tid) {
;     ...
;             PG8_LDA(At, 0, 1); PG8_STAGE(PG8_SB(0, 0), b2, voffB); PG8_STAGE(PG8_SB(0, 1), b2 + hstepB, voffB); PG8_STAGE(PG8_SA(0, 0), a2, voffA);
;             PG8_WAIT_V(8); PG8_WAIT_L(0); PG8_BAR; PG8_MMA(1, 0, At, B0); PG8_MMA(1, 1, At, B1); PG8_BAR; PG8_SCHED;
;             PG8_LDB(B0, 1, 0); PG8_LDB(B1, 1, 1); PG8_SCHED; PG8_LDA(At, 1, 0); PG8_STAGE(PG8_SA(0, 1), a2 + hstep, voffA);
;             PG8_WAIT_V(8); PG8_WAIT_L(0); PG8_BAR; PG8_MMA(0, 0, At, B0); PG8_MMA(0, 1, At, B1); PG8_BAR; PG8_SCHED;
	s_add_i32 s80, 0, 0x18000
	s_add_i32 s81, 0, 0x1c000
	v_add_u32_e32 v174, s80, v158
	v_add_u32_e32 v190, s81, v158
	ds_read_b128 v[146:149], v174
	ds_read_b128 v[164:167], v174 offset:1024
	ds_read_b128 v[170:173], v174 offset:2048
	ds_read_b128 v[174:177], v174 offset:3072
	ds_read_b128 v[178:181], v190
	ds_read_b128 v[182:185], v190 offset:1024
	ds_read_b128 v[186:189], v190 offset:2048
	ds_read_b128 v[190:193], v190 offset:3072
	s_add_u32 s38, s38, 0x40000
	s_addc_u32 s39, s39, 0
	s_mov_b32 m0, s55
	v_lshl_add_u64 v[242:243], s[38:39], 0, v[140:141]
	ds_read_b128 v[194:197], v163 offset:32768
	ds_read_b128 v[198:201], v163 offset:33792
	ds_read_b128 v[212:215], v163 offset:34816
	ds_read_b128 v[216:219], v163 offset:35840
	ds_read_b128 v[220:223], v163 offset:36864
	ds_read_b128 v[224:227], v163 offset:37888
	ds_read_b128 v[228:231], v163 offset:38912
	ds_read_b128 v[232:235], v163 offset:39936
	global_load_lds_dwordx4 v[242:243], off
	v_lshl_add_u64 v[242:243], s[38:39], 0, v[136:137]
	s_mov_b32 m0, s62
	s_nop 0
	global_load_lds_dwordx4 v[242:243], off
	s_waitcnt vmcnt(8)
	s_waitcnt lgkmcnt(0)
	s_barrier
	s_setprio 1
	s_waitcnt lgkmcnt(0)
	v_mfma_f32_16x16x32_bf16 v[128:131], v[146:149], v[194:197], v[128:131]
	v_mfma_f32_16x16x32_bf16 v[124:127], v[170:173], v[194:197], v[124:127]
	v_mfma_f32_16x16x32_bf16 v[112:115], v[146:149], v[212:215], v[112:115]
	v_mfma_f32_16x16x32_bf16 v[108:111], v[170:173], v[212:215], v[108:111]
	v_mfma_f32_16x16x32_bf16 v[96:99], v[146:149], v[220:223], v[96:99]
	v_mfma_f32_16x16x32_bf16 v[92:95], v[170:173], v[220:223], v[92:95]
	v_mfma_f32_16x16x32_bf16 v[80:83], v[146:149], v[228:231], v[80:83]
	v_mfma_f32_16x16x32_bf16 v[76:79], v[170:173], v[228:231], v[76:79]
	v_mfma_f32_16x16x32_bf16 v[128:131], v[164:167], v[198:201], v[128:131]
	v_mfma_f32_16x16x32_bf16 v[124:127], v[174:177], v[198:201], v[124:127]
	v_mfma_f32_16x16x32_bf16 v[112:115], v[164:167], v[216:219], v[112:115]
	v_mfma_f32_16x16x32_bf16 v[108:111], v[174:177], v[216:219], v[108:111]
	v_mfma_f32_16x16x32_bf16 v[96:99], v[164:167], v[224:227], v[96:99]
	v_mfma_f32_16x16x32_bf16 v[92:95], v[174:177], v[224:227], v[92:95]
	v_mfma_f32_16x16x32_bf16 v[80:83], v[164:167], v[232:235], v[80:83]
	v_mfma_f32_16x16x32_bf16 v[76:79], v[174:177], v[232:235], v[76:79]
	s_setprio 0
	s_setprio 1
	v_mfma_f32_16x16x32_bf16 v[120:123], v[178:181], v[194:197], v[120:123]
	v_mfma_f32_16x16x32_bf16 v[116:119], v[186:189], v[194:197], v[116:119]
	v_mfma_f32_16x16x32_bf16 v[104:107], v[178:181], v[212:215], v[104:107]
	v_mfma_f32_16x16x32_bf16 v[100:103], v[186:189], v[212:215], v[100:103]
	v_mfma_f32_16x16x32_bf16 v[88:91], v[178:181], v[220:223], v[88:91]
	v_mfma_f32_16x16x32_bf16 v[84:87], v[186:189], v[220:223], v[84:87]
	v_mfma_f32_16x16x32_bf16 v[72:75], v[178:181], v[228:231], v[72:75]
	v_mfma_f32_16x16x32_bf16 v[68:71], v[186:189], v[228:231], v[68:71]
	v_mfma_f32_16x16x32_bf16 v[120:123], v[182:185], v[198:201], v[120:123]
	v_mfma_f32_16x16x32_bf16 v[116:119], v[190:193], v[198:201], v[116:119]
	v_mfma_f32_16x16x32_bf16 v[104:107], v[182:185], v[216:219], v[104:107]
	v_mfma_f32_16x16x32_bf16 v[100:103], v[190:193], v[216:219], v[100:103]
	v_mfma_f32_16x16x32_bf16 v[88:91], v[182:185], v[224:227], v[88:91]
	v_mfma_f32_16x16x32_bf16 v[84:87], v[190:193], v[224:227], v[84:87]
	v_mfma_f32_16x16x32_bf16 v[72:75], v[182:185], v[232:235], v[72:75]
	v_mfma_f32_16x16x32_bf16 v[68:71], v[190:193], v[232:235], v[68:71]
	s_setprio 0
	s_barrier
; #define PG8_STAGE(bufoff, gbase, voff) do { _Pragma("unroll") for (int _i = 0; _i < 2; ++_i) \
;         __builtin_amdgcn_global_load_lds((const unsigned*)((const char*)(gbase) + (voff)[_i]), (PG8_LAS unsigned*)(lds + (bufoff) + ldsw + _i * 8192), 16, 0, 0); } while (0)
; #define PG8_LDA(dst, b, h) do { _Pragma("unroll") for (int m = 0; m < 4; ++m) _Pragma("unroll") for (int k = 0; k < 2; ++k) dst[m][k] = *(const PG8_LAS bf16x8*)(lds + PG8_SA(b, h) + aoff + m * 2048 + k * 1024); } while (0)
; #define PG8_LDB(dst, b, h) do { _Pragma("unroll") for (int n = 0; n < 2; ++n) _Pragma("unroll") for (int k = 0; k < 2; ++k) dst[n][k] = *(const PG8_LAS bf16x8*)(lds + PG8_SB(b, h) + boff + n * 2048 + k * 1024); } while (0)
; #define PG8_MMA(ai, bj, At, Bt) do { __builtin_amdgcn_s_setprio(1); _Pragma("unroll") for (int m = 0; m < 4; ++m) _Pragma("unroll") for (int n = 0; n < 2; ++n) _Pragma("unroll") for (int k = 0; k < 2; ++k) \
;         acc[ai][bj][m][n] = __builtin_amdgcn_mfma_f32_16x16x32_bf16(Bt[n][k], At[m][k], acc[ai][bj][m][n], 0, 0, 0); __builtin_amdgcn_s_setprio(0); } while (0)
; #define PG8_WAIT_V(n) asm volatile("s_waitcnt vmcnt(" #n ")" ::: "memory")
; #define PG8_WAIT_L(n) asm volatile("s_waitcnt lgkmcnt(" #n ")" ::: "memory")
; #define PG8_BAR __builtin_amdgcn_s_barrier()
; #define PG8_SCHED __builtin_amdgcn_sched_barrier(0)
; template <class Epi, class Sched, bool ALIGN_EPI = false, bool SP2 = false>
; __device__ __forceinline__ void gemm_phase(PG8_LAS unsigned char* lds, const Gemm g, const Sched& S, const Epi& E, const int tid) {
;     ...
;             PG8_WAIT_V(8); PG8_WAIT_L(0); PG8_BAR; PG8_MMA(1, 0, At, B0); PG8_MMA(1, 1, At, B1); PG8_BAR; PG8_SCHED;
;             PG8_LDB(B0, 1, 0); PG8_LDB(B1, 1, 1); PG8_SCHED; PG8_LDA(At, 1, 0); PG8_STAGE(PG8_SA(0, 1), a2 + hstep, voffA);
;             PG8_WAIT_V(8); PG8_WAIT_L(0); PG8_BAR; PG8_MMA(0, 0, At, B0); PG8_MMA(0, 1, At, B1); PG8_BAR; PG8_SCHED;
;             PG8_LDA(At, 1, 1); PG8_STAGE(PG8_SB(1, 0), b3, voffB); PG8_STAGE(PG8_SB(1, 1), b3 + hstepB, voffB); PG8_STAGE(PG8_SA(1, 0), a3, voffA);
;             PG8_WAIT_V(8); PG8_WAIT_L(0); PG8_BAR; PG8_MMA(1, 0, At, B0); PG8_MMA(1, 1, At, B1); PG8_BAR; PG8_SCHED;
	s_add_i32 s38, s80, s42
	v_lshl_add_u64 v[150:151], v[150:151], 0, s[52:53]
	s_mov_b32 m0, s38
	ds_read_b128 v[194:197], v163 offset:49152
	ds_read_b128 v[198:201], v163 offset:50176
	ds_read_b128 v[212:215], v163 offset:51200
	ds_read_b128 v[216:219], v163 offset:52224
	ds_read_b128 v[220:223], v163 offset:53248
	ds_read_b128 v[224:227], v163 offset:54272
	ds_read_b128 v[228:231], v163 offset:55296
	ds_read_b128 v[232:235], v163 offset:56320
	global_load_lds_dwordx4 v[150:151], off
	s_add_i32 m0, s38, 0x2000
	s_add_u32 s36, s36, 0x10080
	v_lshl_add_u64 v[150:151], v[236:237], 0, s[52:53]
	s_addc_u32 s37, s37, 0
	s_add_i32 s38, s81, s42
	global_load_lds_dwordx4 v[150:151], off
	v_lshl_add_u64 v[150:151], s[36:37], 0, v[138:139]
	s_mov_b32 m0, s38
	s_nop 0
	global_load_lds_dwordx4 v[150:151], off
	v_lshl_add_u64 v[150:151], s[36:37], 0, v[134:135]
	s_add_i32 m0, s38, 0x2000
	s_nop 0
	global_load_lds_dwordx4 v[150:151], off
	v_lshl_add_u64 v[150:151], v[238:239], 0, s[52:53]
	s_mov_b32 m0, s63
	s_nop 0
	global_load_lds_dwordx4 v[150:151], off
	v_lshl_add_u64 v[150:151], v[240:241], 0, s[52:53]
	s_mov_b32 m0, s64
	s_nop 0
	global_load_lds_dwordx4 v[150:151], off
	s_waitcnt vmcnt(8)
	s_waitcnt lgkmcnt(0)
	s_barrier
	s_setprio 1
	s_waitcnt lgkmcnt(0)
	v_mfma_f32_16x16x32_bf16 v[64:67], v[146:149], v[194:197], v[64:67]
	v_mfma_f32_16x16x32_bf16 v[60:63], v[170:173], v[194:197], v[60:63]
	v_mfma_f32_16x16x32_bf16 v[48:51], v[146:149], v[212:215], v[48:51]
	v_mfma_f32_16x16x32_bf16 v[44:47], v[170:173], v[212:215], v[44:47]
	v_mfma_f32_16x16x32_bf16 v[32:35], v[146:149], v[220:223], v[32:35]
	v_mfma_f32_16x16x32_bf16 v[28:31], v[170:173], v[220:223], v[28:31]
	v_mfma_f32_16x16x32_bf16 v[16:19], v[146:149], v[228:231], v[16:19]
	v_mfma_f32_16x16x32_bf16 v[12:15], v[170:173], v[228:231], v[12:15]
	v_mfma_f32_16x16x32_bf16 v[64:67], v[164:167], v[198:201], v[64:67]
	v_mfma_f32_16x16x32_bf16 v[60:63], v[174:177], v[198:201], v[60:63]
	v_mfma_f32_16x16x32_bf16 v[48:51], v[164:167], v[216:219], v[48:51]
	v_mfma_f32_16x16x32_bf16 v[44:47], v[174:177], v[216:219], v[44:47]
	v_mfma_f32_16x16x32_bf16 v[32:35], v[164:167], v[224:227], v[32:35]
	v_mfma_f32_16x16x32_bf16 v[28:31], v[174:177], v[224:227], v[28:31]
	v_mfma_f32_16x16x32_bf16 v[16:19], v[164:167], v[232:235], v[16:19]
	v_mfma_f32_16x16x32_bf16 v[12:15], v[174:177], v[232:235], v[12:15]
	s_setprio 0
	s_setprio 1
	v_mfma_f32_16x16x32_bf16 v[56:59], v[178:181], v[194:197], v[56:59]
	v_mfma_f32_16x16x32_bf16 v[52:55], v[186:189], v[194:197], v[52:55]
	v_mfma_f32_16x16x32_bf16 v[40:43], v[178:181], v[212:215], v[40:43]
	v_mfma_f32_16x16x32_bf16 v[36:39], v[186:189], v[212:215], v[36:39]
	v_mfma_f32_16x16x32_bf16 v[24:27], v[178:181], v[220:223], v[24:27]
	v_mfma_f32_16x16x32_bf16 v[20:23], v[186:189], v[220:223], v[20:23]
	v_mfma_f32_16x16x32_bf16 v[8:11], v[178:181], v[228:231], v[8:11]
	v_mfma_f32_16x16x32_bf16 v[4:7], v[186:189], v[228:231], v[4:7]
	v_mfma_f32_16x16x32_bf16 v[56:59], v[182:185], v[198:201], v[56:59]
	v_mfma_f32_16x16x32_bf16 v[52:55], v[190:193], v[198:201], v[52:55]
	v_mfma_f32_16x16x32_bf16 v[40:43], v[182:185], v[216:219], v[40:43]
	v_mfma_f32_16x16x32_bf16 v[36:39], v[190:193], v[216:219], v[36:39]
	v_mfma_f32_16x16x32_bf16 v[24:27], v[182:185], v[224:227], v[24:27]
	v_mfma_f32_16x16x32_bf16 v[20:23], v[190:193], v[224:227], v[20:23]
	v_mfma_f32_16x16x32_bf16 v[8:11], v[182:185], v[232:235], v[8:11]
	v_mfma_f32_16x16x32_bf16 v[4:7], v[190:193], v[232:235], v[4:7]
	s_setprio 0
	s_barrier
	s_add_i32 s79, s79, 2
	s_cmp_gt_u32 s79, 13
	s_cbranch_scc0 .LBB0_1380
	s_and_b64 vcc, exec, s[14:15]
	s_cbranch_vccz .LBB0_1383
	s_barrier
